# K-loops: M0 writes placed before the adjacent DMA address add so the s_nop wait states disappear (89 sites); on top of peeled version
# speedup vs baseline: 1.0127x; 1.0033x over previous
;     DI bool next(int i, Unit& u) const { const long L = (long)i * G + c; if (L >= T.nwg) return false; T.map((int)L, u.pm, u.pn); u.seg = 0; return true; }
;     DI bool next(int i, Unit& u) const { const int ti = i / 3; const long L = (long)ti * G + c; if (L >= T.nwg) return false; T.map((int)L, u.pm, u.pn); u.seg = i - 3 * ti; return true; }
;     DI const char* aptr(const Unit& u) const { return A + (size_t)u.pm * ta + (size_t)kofs(u.seg) * 2; }
;     DI const char* bptr(const Unit& u) const { return B + (size_t)u.pn * tb + (size_t)kofs(u.seg) * 2; }
; #define PG8_STAGE(bufoff, gbase, voff) do { _Pragma("unroll") for (int _i = 0; _i < 2; ++_i) \
;         __builtin_amdgcn_global_load_lds((const unsigned*)((const char*)(gbase) + (voff)[_i]), (LAS unsigned*)(lds + (bufoff) + ldsw + _i * 8192), 16, 0, 0); } while (0)
; #define PG8_LDA(dst, b, h) do { _Pragma("unroll") for (int m = 0; m < 4; ++m) _Pragma("unroll") for (int k = 0; k < 2; ++k) dst[m][k] = *(const LAS bf16x8*)(lds + PG8_SA(b, h) + aoff + m * 2048 + k * 1024); } while (0)
; #define PG8_WAIT_V(n) asm volatile("s_waitcnt vmcnt(" #n ")" ::: "memory")
; #define PG8_WAIT_L(n) asm volatile("s_waitcnt lgkmcnt(" #n ")" ::: "memory")
; template <class Epi, class Sched>
; DI void gemm_phase(LAS unsigned char* lds, const int wv, const int lda, const int ldb, const Sched& S, const Epi& E) {
;     ...
;         const bool has_next = S.next(ui + 1, nxt);
;         const char* nA = has_next ? S.aptr(nxt) : cA; const char* nB = has_next ? S.bptr(nxt) : cB;
;         for (int t = 0; t < nt; t += 2) {
;             const bool last = (t == nt - 2);
;             const char* a1 = cA + (size_t)(t + 1) * kstep;
;             const char* a2 = last ? nA : cA + (size_t)(t + 2) * kstep; const char* b2 = last ? nB : cB + (size_t)(t + 2) * kstep;
;             const char* a3 = a2 + kstep; const char* b3 = b2 + kstep;
;             PG8_LDB(B0, 0, 0); PG8_LDB(B1, 0, 1); PG8_SCHED; PG8_LDA(At, 0, 0); PG8_STAGE(PG8_SA(1, 1), a1 + hstepA, voffA);
;             PG8_WAIT_V(8); PG8_WAIT_L(0); PG8_BAR; PG8_MMA(0, 0, At, B0); PG8_MMA(0, 1, At, B1); PG8_BAR; PG8_SCHED;
;             PG8_LDA(At, 0, 1); PG8_STAGE(PG8_SB(0, 0), b2, voffB); PG8_STAGE(PG8_SB(0, 1), b2 + hstepB, voffB); PG8_STAGE(PG8_SA(0, 0), a2, voffA);
;             PG8_WAIT_V(8); PG8_WAIT_L(0); PG8_BAR; PG8_MMA(1, 0, At, B0); PG8_MMA(1, 1, At, B1); PG8_BAR; PG8_SCHED;
.LBB0_377:
	s_ashr_i32 s23, s22, 31
	s_lshl_b64 s[0:1], s[22:23], 20
	s_add_u32 s24, s8, s0
	s_addc_u32 s25, s9, s1
	s_and_b64 s[0:1], s[40:41], exec
	s_cselect_b32 s0, s25, s35
	s_cselect_b32 s1, s24, s34
	s_ashr_i32 s19, s18, 31
	s_lshl_b64 s[16:17], s[18:19], 20
	s_add_u32 s26, s45, s16
	s_addc_u32 s27, s46, s17
	s_and_b64 s[16:17], s[40:41], exec
	s_cselect_b32 s5, s27, s37
	s_cselect_b32 s16, s26, s36
	s_add_u32 s34, s34, 0x80080
	s_addc_u32 s35, s35, 0
	s_add_u32 s17, s36, 0x100
	s_addc_u32 s19, s37, 0
	s_mov_b32 s23, -2
	s_waitcnt vmcnt(0)
	s_add_u32 s33, s34, 0xfff80080
	s_addc_u32 s36, s35, -1
	s_add_i32 s61, 0, 0x10000
	s_cmp_eq_u32 s23, 28
	s_cselect_b32 s39, s0, s36
	s_cselect_b32 s38, s1, s33
	s_cselect_b32 s37, s5, s19
	s_cselect_b32 s36, s16, s17
	s_add_i32 s33, 0, 0x14000
	v_add_u32_e32 v154, s61, v170
	v_add_u32_e32 v173, s33, v170
	ds_read_b128 v[104:107], v154
	ds_read_b128 v[108:111], v154 offset:1024
	ds_read_b128 v[150:153], v154 offset:2048
	ds_read_b128 v[154:157], v154 offset:3072
	ds_read_b128 v[158:161], v173
	ds_read_b128 v[162:165], v173 offset:1024
	ds_read_b128 v[166:169], v173 offset:2048
	ds_read_b128 v[174:177], v173 offset:3072
	v_lshl_add_u64 v[182:183], s[34:35], 0, v[146:147]
	s_add_i32 m0, s31, 0xc000
	ds_read_b128 v[178:181], v172
	ds_read_b128 v[200:203], v172 offset:1024
	ds_read_b128 v[204:207], v172 offset:2048
	ds_read_b128 v[208:211], v172 offset:3072
	ds_read_b128 v[212:215], v172 offset:4096
	ds_read_b128 v[216:219], v172 offset:5120
	ds_read_b128 v[220:223], v172 offset:6144
	ds_read_b128 v[234:237], v172 offset:7168
	global_load_lds_dwordx4 v[182:183], off
	s_add_i32 m0, s31, 0xe000
	v_lshl_add_u64 v[182:183], s[34:35], 0, v[148:149]
	global_load_lds_dwordx4 v[182:183], off
	s_waitcnt vmcnt(8) lgkmcnt(0)
	s_barrier
	v_mfma_f32_16x16x32_bf16 v[132:135], v[104:107], v[178:181], 0
	v_mfma_f32_16x16x32_bf16 v[128:131], v[150:153], v[178:181], 0
	v_mfma_f32_16x16x32_bf16 v[124:127], v[104:107], v[204:207], 0
	v_mfma_f32_16x16x32_bf16 v[120:123], v[150:153], v[204:207], 0
	v_mfma_f32_16x16x32_bf16 v[116:119], v[104:107], v[212:215], 0
	v_mfma_f32_16x16x32_bf16 v[112:115], v[150:153], v[212:215], 0
	v_mfma_f32_16x16x32_bf16 v[100:103], v[104:107], v[220:223], 0
	v_mfma_f32_16x16x32_bf16 v[96:99], v[150:153], v[220:223], 0
	v_mfma_f32_16x16x32_bf16 v[132:135], v[108:111], v[200:203], v[132:135]
	v_mfma_f32_16x16x32_bf16 v[128:131], v[154:157], v[200:203], v[128:131]
	v_mfma_f32_16x16x32_bf16 v[124:127], v[108:111], v[208:211], v[124:127]
	v_mfma_f32_16x16x32_bf16 v[120:123], v[154:157], v[208:211], v[120:123]
	v_mfma_f32_16x16x32_bf16 v[116:119], v[108:111], v[216:219], v[116:119]
	v_mfma_f32_16x16x32_bf16 v[112:115], v[154:157], v[216:219], v[112:115]
	v_mfma_f32_16x16x32_bf16 v[100:103], v[108:111], v[234:237], v[100:103]
	v_mfma_f32_16x16x32_bf16 v[96:99], v[154:157], v[234:237], v[96:99]
	v_mfma_f32_16x16x32_bf16 v[60:63], v[158:161], v[178:181], 0
	v_mfma_f32_16x16x32_bf16 v[56:59], v[166:169], v[178:181], 0
	v_mfma_f32_16x16x32_bf16 v[52:55], v[158:161], v[204:207], 0
	v_mfma_f32_16x16x32_bf16 v[48:51], v[166:169], v[204:207], 0
	v_mfma_f32_16x16x32_bf16 v[44:47], v[158:161], v[212:215], 0
	v_mfma_f32_16x16x32_bf16 v[40:43], v[166:169], v[212:215], 0
	v_mfma_f32_16x16x32_bf16 v[36:39], v[158:161], v[220:223], 0
	v_mfma_f32_16x16x32_bf16 v[32:35], v[166:169], v[220:223], 0
	v_mfma_f32_16x16x32_bf16 v[60:63], v[162:165], v[200:203], v[60:63]
	v_mfma_f32_16x16x32_bf16 v[56:59], v[174:177], v[200:203], v[56:59]
	v_mfma_f32_16x16x32_bf16 v[52:55], v[162:165], v[208:211], v[52:55]
	v_mfma_f32_16x16x32_bf16 v[48:51], v[174:177], v[208:211], v[48:51]
	v_mfma_f32_16x16x32_bf16 v[44:47], v[162:165], v[216:219], v[44:47]
	v_mfma_f32_16x16x32_bf16 v[40:43], v[174:177], v[216:219], v[40:43]
	v_mfma_f32_16x16x32_bf16 v[36:39], v[162:165], v[234:237], v[36:39]
	v_mfma_f32_16x16x32_bf16 v[32:35], v[174:177], v[234:237], v[32:35]
	s_barrier
	s_add_i32 s61, s61, s47
	v_lshl_add_u64 v[182:183], s[36:37], 0, v[138:139]
	s_mov_b32 m0, s61
	ds_read_b128 v[178:181], v172 offset:16384
	ds_read_b128 v[200:203], v172 offset:17408
	ds_read_b128 v[204:207], v172 offset:18432
	ds_read_b128 v[208:211], v172 offset:19456
	ds_read_b128 v[212:215], v172 offset:20480
	ds_read_b128 v[216:219], v172 offset:21504
	ds_read_b128 v[220:223], v172 offset:22528
	ds_read_b128 v[234:237], v172 offset:23552
	global_load_lds_dwordx4 v[182:183], off
	s_add_i32 m0, s61, 0x2000
	s_add_u32 s62, s36, 0x80000
	v_lshl_add_u64 v[188:189], s[36:37], 0, v[142:143]
	s_addc_u32 s63, s37, 0
	s_add_i32 s33, s33, s47
	global_load_lds_dwordx4 v[188:189], off
	v_lshl_add_u64 v[190:191], s[62:63], 0, v[138:139]
	s_mov_b32 m0, s33
	v_lshl_add_u64 v[196:197], s[38:39], 0, v[140:141]
	global_load_lds_dwordx4 v[190:191], off
	s_add_i32 m0, s33, 0x2000
	v_lshl_add_u64 v[190:191], s[62:63], 0, v[142:143]
	global_load_lds_dwordx4 v[190:191], off
	s_mov_b32 m0, s31
	v_lshl_add_u64 v[190:191], s[38:39], 0, v[136:137]
	global_load_lds_dwordx4 v[190:191], off
	s_mov_b32 m0, s48
	s_nop 0
	global_load_lds_dwordx4 v[196:197], off
	s_waitcnt vmcnt(8) lgkmcnt(0)
	s_barrier
; #define PG8_STAGE(bufoff, gbase, voff) do { _Pragma("unroll") for (int _i = 0; _i < 2; ++_i) \
;         __builtin_amdgcn_global_load_lds((const unsigned*)((const char*)(gbase) + (voff)[_i]), (LAS unsigned*)(lds + (bufoff) + ldsw + _i * 8192), 16, 0, 0); } while (0)
; #define PG8_LDA(dst, b, h) do { _Pragma("unroll") for (int m = 0; m < 4; ++m) _Pragma("unroll") for (int k = 0; k < 2; ++k) dst[m][k] = *(const LAS bf16x8*)(lds + PG8_SA(b, h) + aoff + m * 2048 + k * 1024); } while (0)
; #define PG8_LDB(dst, b, h) do { _Pragma("unroll") for (int n = 0; n < 2; ++n) _Pragma("unroll") for (int k = 0; k < 2; ++k) dst[n][k] = *(const LAS bf16x8*)(lds + PG8_SB(b, h) + boff + n * 2048 + k * 1024); } while (0)
; #define PG8_MMA(ai, bj, At, Bt) do { __builtin_amdgcn_s_setprio(1); _Pragma("unroll") for (int m = 0; m < 4; ++m) _Pragma("unroll") for (int n = 0; n < 2; ++n) _Pragma("unroll") for (int k = 0; k < 2; ++k) \
;         acc[ai][bj][m][n] = __builtin_amdgcn_mfma_f32_16x16x32_bf16(Bt[n][k], At[m][k], acc[ai][bj][m][n], 0, 0, 0); __builtin_amdgcn_s_setprio(0); } while (0)
; #define PG8_WAIT_V(n) asm volatile("s_waitcnt vmcnt(" #n ")" ::: "memory")
; #define PG8_WAIT_L(n) asm volatile("s_waitcnt lgkmcnt(" #n ")" ::: "memory")
; #define PG8_BAR __builtin_amdgcn_s_barrier()
; #define PG8_SCHED __builtin_amdgcn_sched_barrier(0)
; template <class Epi, class Sched>
; DI void gemm_phase(LAS unsigned char* lds, const int wv, const int lda, const int ldb, const Sched& S, const Epi& E) {
;     ...
;             PG8_WAIT_V(8); PG8_WAIT_L(0); PG8_BAR; PG8_MMA(1, 0, At, B0); PG8_MMA(1, 1, At, B1); PG8_BAR; PG8_SCHED;
;             PG8_LDB(B0, 1, 0); PG8_LDB(B1, 1, 1); PG8_SCHED; PG8_LDA(At, 1, 0); PG8_STAGE(PG8_SA(0, 1), a2 + hstepA, voffA);
;             PG8_WAIT_V(8); PG8_WAIT_L(0); PG8_BAR; PG8_MMA(0, 0, At, B0); PG8_MMA(0, 1, At, B1); PG8_BAR; PG8_SCHED;
	v_mfma_f32_16x16x32_bf16 v[92:95], v[104:107], v[178:181], 0
	v_mfma_f32_16x16x32_bf16 v[88:91], v[150:153], v[178:181], 0
	v_mfma_f32_16x16x32_bf16 v[84:87], v[104:107], v[204:207], 0
	v_mfma_f32_16x16x32_bf16 v[80:83], v[150:153], v[204:207], 0
	v_mfma_f32_16x16x32_bf16 v[76:79], v[104:107], v[212:215], 0
	v_mfma_f32_16x16x32_bf16 v[72:75], v[150:153], v[212:215], 0
	v_mfma_f32_16x16x32_bf16 v[68:71], v[104:107], v[220:223], 0
	v_mfma_f32_16x16x32_bf16 v[64:67], v[150:153], v[220:223], 0
	v_mfma_f32_16x16x32_bf16 v[92:95], v[108:111], v[200:203], v[92:95]
	v_mfma_f32_16x16x32_bf16 v[88:91], v[154:157], v[200:203], v[88:91]
	v_mfma_f32_16x16x32_bf16 v[84:87], v[108:111], v[208:211], v[84:87]
	v_mfma_f32_16x16x32_bf16 v[80:83], v[154:157], v[208:211], v[80:83]
	v_mfma_f32_16x16x32_bf16 v[76:79], v[108:111], v[216:219], v[76:79]
	v_mfma_f32_16x16x32_bf16 v[72:75], v[154:157], v[216:219], v[72:75]
	v_mfma_f32_16x16x32_bf16 v[68:71], v[108:111], v[234:237], v[68:71]
	v_mfma_f32_16x16x32_bf16 v[64:67], v[154:157], v[234:237], v[64:67]
	v_mfma_f32_16x16x32_bf16 v[28:31], v[158:161], v[178:181], 0
	v_mfma_f32_16x16x32_bf16 v[24:27], v[166:169], v[178:181], 0
	v_mfma_f32_16x16x32_bf16 v[20:23], v[158:161], v[204:207], 0
	v_mfma_f32_16x16x32_bf16 v[16:19], v[166:169], v[204:207], 0
	v_mfma_f32_16x16x32_bf16 v[12:15], v[158:161], v[212:215], 0
	v_mfma_f32_16x16x32_bf16 v[8:11], v[166:169], v[212:215], 0
	v_mfma_f32_16x16x32_bf16 v[4:7], v[158:161], v[220:223], 0
	v_mfma_f32_16x16x32_bf16 v[0:3], v[166:169], v[220:223], 0
	v_mfma_f32_16x16x32_bf16 v[28:31], v[162:165], v[200:203], v[28:31]
	v_mfma_f32_16x16x32_bf16 v[24:27], v[174:177], v[200:203], v[24:27]
	v_mfma_f32_16x16x32_bf16 v[20:23], v[162:165], v[208:211], v[20:23]
	v_mfma_f32_16x16x32_bf16 v[16:19], v[174:177], v[208:211], v[16:19]
	v_mfma_f32_16x16x32_bf16 v[12:15], v[162:165], v[216:219], v[12:15]
	v_mfma_f32_16x16x32_bf16 v[8:11], v[174:177], v[216:219], v[8:11]
	v_mfma_f32_16x16x32_bf16 v[4:7], v[162:165], v[234:237], v[4:7]
	v_mfma_f32_16x16x32_bf16 v[0:3], v[174:177], v[234:237], v[0:3]
	s_barrier
	s_add_i32 s33, 0, 0x18000
	s_add_i32 s61, 0, 0x1c000
	v_add_u32_e32 v154, s33, v170
	v_add_u32_e32 v173, s61, v170
	ds_read_b128 v[104:107], v154
	ds_read_b128 v[108:111], v154 offset:1024
	ds_read_b128 v[150:153], v154 offset:2048
	ds_read_b128 v[154:157], v154 offset:3072
	ds_read_b128 v[158:161], v173
	ds_read_b128 v[162:165], v173 offset:1024
	ds_read_b128 v[166:169], v173 offset:2048
	ds_read_b128 v[174:177], v173 offset:3072
	s_add_u32 s38, s38, 0x80000
	s_addc_u32 s39, s39, 0
	s_mov_b32 m0, s49
	v_lshl_add_u64 v[198:199], s[38:39], 0, v[136:137]
	ds_read_b128 v[178:181], v172 offset:32768
	ds_read_b128 v[200:203], v172 offset:33792
	ds_read_b128 v[204:207], v172 offset:34816
	ds_read_b128 v[208:211], v172 offset:35840
	ds_read_b128 v[212:215], v172 offset:36864
	ds_read_b128 v[216:219], v172 offset:37888
	ds_read_b128 v[220:223], v172 offset:38912
	ds_read_b128 v[234:237], v172 offset:39936
	global_load_lds_dwordx4 v[198:199], off
	s_mov_b32 m0, s50
	v_lshl_add_u64 v[198:199], s[38:39], 0, v[140:141]
	global_load_lds_dwordx4 v[198:199], off
	s_waitcnt vmcnt(8) lgkmcnt(0)
	s_barrier
	v_mfma_f32_16x16x32_bf16 v[132:135], v[104:107], v[178:181], v[132:135]
	v_mfma_f32_16x16x32_bf16 v[128:131], v[150:153], v[178:181], v[128:131]
	v_mfma_f32_16x16x32_bf16 v[124:127], v[104:107], v[204:207], v[124:127]
	v_mfma_f32_16x16x32_bf16 v[120:123], v[150:153], v[204:207], v[120:123]
	v_mfma_f32_16x16x32_bf16 v[116:119], v[104:107], v[212:215], v[116:119]
	v_mfma_f32_16x16x32_bf16 v[112:115], v[150:153], v[212:215], v[112:115]
	v_mfma_f32_16x16x32_bf16 v[100:103], v[104:107], v[220:223], v[100:103]
	v_mfma_f32_16x16x32_bf16 v[96:99], v[150:153], v[220:223], v[96:99]
	v_mfma_f32_16x16x32_bf16 v[132:135], v[108:111], v[200:203], v[132:135]
	v_mfma_f32_16x16x32_bf16 v[128:131], v[154:157], v[200:203], v[128:131]
	v_mfma_f32_16x16x32_bf16 v[124:127], v[108:111], v[208:211], v[124:127]
	v_mfma_f32_16x16x32_bf16 v[120:123], v[154:157], v[208:211], v[120:123]
	v_mfma_f32_16x16x32_bf16 v[116:119], v[108:111], v[216:219], v[116:119]
	v_mfma_f32_16x16x32_bf16 v[112:115], v[154:157], v[216:219], v[112:115]
	v_mfma_f32_16x16x32_bf16 v[100:103], v[108:111], v[234:237], v[100:103]
	v_mfma_f32_16x16x32_bf16 v[96:99], v[154:157], v[234:237], v[96:99]
	v_mfma_f32_16x16x32_bf16 v[60:63], v[158:161], v[178:181], v[60:63]
	v_mfma_f32_16x16x32_bf16 v[56:59], v[166:169], v[178:181], v[56:59]
	v_mfma_f32_16x16x32_bf16 v[52:55], v[158:161], v[204:207], v[52:55]
	v_mfma_f32_16x16x32_bf16 v[48:51], v[166:169], v[204:207], v[48:51]
	v_mfma_f32_16x16x32_bf16 v[44:47], v[158:161], v[212:215], v[44:47]
	v_mfma_f32_16x16x32_bf16 v[40:43], v[166:169], v[212:215], v[40:43]
	v_mfma_f32_16x16x32_bf16 v[36:39], v[158:161], v[220:223], v[36:39]
	v_mfma_f32_16x16x32_bf16 v[32:35], v[166:169], v[220:223], v[32:35]
	v_mfma_f32_16x16x32_bf16 v[60:63], v[162:165], v[200:203], v[60:63]
	v_mfma_f32_16x16x32_bf16 v[56:59], v[174:177], v[200:203], v[56:59]
	v_mfma_f32_16x16x32_bf16 v[52:55], v[162:165], v[208:211], v[52:55]
	v_mfma_f32_16x16x32_bf16 v[48:51], v[174:177], v[208:211], v[48:51]
	v_mfma_f32_16x16x32_bf16 v[44:47], v[162:165], v[216:219], v[44:47]
	v_mfma_f32_16x16x32_bf16 v[40:43], v[174:177], v[216:219], v[40:43]
	v_mfma_f32_16x16x32_bf16 v[36:39], v[162:165], v[234:237], v[36:39]
	v_mfma_f32_16x16x32_bf16 v[32:35], v[174:177], v[234:237], v[32:35]
	s_barrier
; #define PG8_STAGE(bufoff, gbase, voff) do { _Pragma("unroll") for (int _i = 0; _i < 2; ++_i) \
;         __builtin_amdgcn_global_load_lds((const unsigned*)((const char*)(gbase) + (voff)[_i]), (LAS unsigned*)(lds + (bufoff) + ldsw + _i * 8192), 16, 0, 0); } while (0)
; #define PG8_LDA(dst, b, h) do { _Pragma("unroll") for (int m = 0; m < 4; ++m) _Pragma("unroll") for (int k = 0; k < 2; ++k) dst[m][k] = *(const LAS bf16x8*)(lds + PG8_SA(b, h) + aoff + m * 2048 + k * 1024); } while (0)
; #define PG8_LDB(dst, b, h) do { _Pragma("unroll") for (int n = 0; n < 2; ++n) _Pragma("unroll") for (int k = 0; k < 2; ++k) dst[n][k] = *(const LAS bf16x8*)(lds + PG8_SB(b, h) + boff + n * 2048 + k * 1024); } while (0)
; #define PG8_MMA(ai, bj, At, Bt) do { __builtin_amdgcn_s_setprio(1); _Pragma("unroll") for (int m = 0; m < 4; ++m) _Pragma("unroll") for (int n = 0; n < 2; ++n) _Pragma("unroll") for (int k = 0; k < 2; ++k) \
;         acc[ai][bj][m][n] = __builtin_amdgcn_mfma_f32_16x16x32_bf16(Bt[n][k], At[m][k], acc[ai][bj][m][n], 0, 0, 0); __builtin_amdgcn_s_setprio(0); } while (0)
; #define PG8_WAIT_V(n) asm volatile("s_waitcnt vmcnt(" #n ")" ::: "memory")
; #define PG8_WAIT_L(n) asm volatile("s_waitcnt lgkmcnt(" #n ")" ::: "memory")
; #define PG8_BAR __builtin_amdgcn_s_barrier()
; #define PG8_SCHED __builtin_amdgcn_sched_barrier(0)
; template <class Epi, class Sched>
; DI void gemm_phase(LAS unsigned char* lds, const int wv, const int lda, const int ldb, const Sched& S, const Epi& E) {
;     ...
;         for (int t = 0; t < nt; t += 2) {
;             const bool last = (t == nt - 2);
;             const char* a1 = cA + (size_t)(t + 1) * kstep;
;             const char* a2 = last ? nA : cA + (size_t)(t + 2) * kstep; const char* b2 = last ? nB : cB + (size_t)(t + 2) * kstep;
;             const char* a3 = a2 + kstep; const char* b3 = b2 + kstep;
;             PG8_LDB(B0, 0, 0); PG8_LDB(B1, 0, 1); PG8_SCHED; PG8_LDA(At, 0, 0); PG8_STAGE(PG8_SA(1, 1), a1 + hstepA, voffA);
;             PG8_WAIT_V(8); PG8_WAIT_L(0); PG8_BAR; PG8_MMA(0, 0, At, B0); PG8_MMA(0, 1, At, B1); PG8_BAR; PG8_SCHED;
;     ...
;             PG8_LDA(At, 1, 1); PG8_STAGE(PG8_SB(1, 0), b3, voffB); PG8_STAGE(PG8_SB(1, 1), b3 + hstepB, voffB); PG8_STAGE(PG8_SA(1, 0), a3, voffA);
;             PG8_WAIT_V(8); PG8_WAIT_L(0); PG8_BAR; PG8_MMA(1, 0, At, B0); PG8_MMA(1, 1, At, B1); PG8_BAR; PG8_SCHED;
;         }
	s_add_i32 s33, s33, s47
	v_lshl_add_u64 v[182:183], v[182:183], 0, s[28:29]
	s_mov_b32 m0, s33
	ds_read_b128 v[178:181], v172 offset:49152
	ds_read_b128 v[200:203], v172 offset:50176
	ds_read_b128 v[204:207], v172 offset:51200
	ds_read_b128 v[208:211], v172 offset:52224
	ds_read_b128 v[212:215], v172 offset:53248
	ds_read_b128 v[216:219], v172 offset:54272
	ds_read_b128 v[220:223], v172 offset:55296
	ds_read_b128 v[234:237], v172 offset:56320
	global_load_lds_dwordx4 v[182:183], off
	s_add_i32 m0, s33, 0x2000
	s_add_u32 s36, s36, 0x80080
	v_lshl_add_u64 v[182:183], v[188:189], 0, s[28:29]
	s_addc_u32 s37, s37, 0
	s_add_i32 s33, s61, s47
	global_load_lds_dwordx4 v[182:183], off
	s_mov_b32 m0, s33
	v_lshl_add_u64 v[182:183], s[36:37], 0, v[138:139]
	global_load_lds_dwordx4 v[182:183], off
	s_add_i32 m0, s33, 0x2000
	v_lshl_add_u64 v[182:183], s[36:37], 0, v[142:143]
	global_load_lds_dwordx4 v[182:183], off
	s_mov_b32 m0, s52
	v_lshl_add_u64 v[182:183], v[190:191], 0, s[28:29]
	global_load_lds_dwordx4 v[182:183], off
	s_mov_b32 m0, s53
	v_lshl_add_u64 v[182:183], v[196:197], 0, s[28:29]
	global_load_lds_dwordx4 v[182:183], off
	s_waitcnt vmcnt(8) lgkmcnt(0)
	s_barrier
	v_mfma_f32_16x16x32_bf16 v[92:95], v[104:107], v[178:181], v[92:95]
	v_mfma_f32_16x16x32_bf16 v[88:91], v[150:153], v[178:181], v[88:91]
	v_mfma_f32_16x16x32_bf16 v[84:87], v[104:107], v[204:207], v[84:87]
	v_mfma_f32_16x16x32_bf16 v[80:83], v[150:153], v[204:207], v[80:83]
	v_mfma_f32_16x16x32_bf16 v[76:79], v[104:107], v[212:215], v[76:79]
	v_mfma_f32_16x16x32_bf16 v[72:75], v[150:153], v[212:215], v[72:75]
	v_mfma_f32_16x16x32_bf16 v[68:71], v[104:107], v[220:223], v[68:71]
	v_mfma_f32_16x16x32_bf16 v[64:67], v[150:153], v[220:223], v[64:67]
	v_mfma_f32_16x16x32_bf16 v[92:95], v[108:111], v[200:203], v[92:95]
	v_mfma_f32_16x16x32_bf16 v[88:91], v[154:157], v[200:203], v[88:91]
	v_mfma_f32_16x16x32_bf16 v[84:87], v[108:111], v[208:211], v[84:87]
	v_mfma_f32_16x16x32_bf16 v[80:83], v[154:157], v[208:211], v[80:83]
	v_mfma_f32_16x16x32_bf16 v[76:79], v[108:111], v[216:219], v[76:79]
	v_mfma_f32_16x16x32_bf16 v[72:75], v[154:157], v[216:219], v[72:75]
	v_mfma_f32_16x16x32_bf16 v[68:71], v[108:111], v[234:237], v[68:71]
	v_mfma_f32_16x16x32_bf16 v[64:67], v[154:157], v[234:237], v[64:67]
	v_mfma_f32_16x16x32_bf16 v[28:31], v[158:161], v[178:181], v[28:31]
	v_mfma_f32_16x16x32_bf16 v[24:27], v[166:169], v[178:181], v[24:27]
	v_mfma_f32_16x16x32_bf16 v[20:23], v[158:161], v[204:207], v[20:23]
	v_mfma_f32_16x16x32_bf16 v[16:19], v[166:169], v[204:207], v[16:19]
	v_mfma_f32_16x16x32_bf16 v[12:15], v[158:161], v[212:215], v[12:15]
	v_mfma_f32_16x16x32_bf16 v[8:11], v[166:169], v[212:215], v[8:11]
	v_mfma_f32_16x16x32_bf16 v[4:7], v[158:161], v[220:223], v[4:7]
	v_mfma_f32_16x16x32_bf16 v[0:3], v[166:169], v[220:223], v[0:3]
	v_mfma_f32_16x16x32_bf16 v[28:31], v[162:165], v[200:203], v[28:31]
	v_mfma_f32_16x16x32_bf16 v[24:27], v[174:177], v[200:203], v[24:27]
	v_mfma_f32_16x16x32_bf16 v[20:23], v[162:165], v[208:211], v[20:23]
	v_mfma_f32_16x16x32_bf16 v[16:19], v[174:177], v[208:211], v[16:19]
	v_mfma_f32_16x16x32_bf16 v[12:15], v[162:165], v[216:219], v[12:15]
	v_mfma_f32_16x16x32_bf16 v[8:11], v[174:177], v[216:219], v[8:11]
	v_mfma_f32_16x16x32_bf16 v[4:7], v[162:165], v[234:237], v[4:7]
	v_mfma_f32_16x16x32_bf16 v[0:3], v[174:177], v[234:237], v[0:3]
	s_barrier
	s_add_i32 s23, s23, 2
	s_add_u32 s34, s34, 0x100
	s_addc_u32 s35, s35, 0
	s_add_u32 s17, s17, 0x100
	s_addc_u32 s19, s19, 0
.LBB0_378:
	s_add_u32 s33, s34, 0xfff80080
	s_addc_u32 s36, s35, -1
	s_add_i32 s61, 0, 0x10000
	s_cmp_eq_u32 s23, 28
	s_cselect_b32 s39, s0, s36
	s_cselect_b32 s38, s1, s33
	s_cselect_b32 s37, s5, s19
	s_cselect_b32 s36, s16, s17
	s_add_i32 s33, 0, 0x14000
	v_add_u32_e32 v154, s61, v170
	v_add_u32_e32 v173, s33, v170
	ds_read_b128 v[104:107], v154
	ds_read_b128 v[108:111], v154 offset:1024
	ds_read_b128 v[150:153], v154 offset:2048
	ds_read_b128 v[154:157], v154 offset:3072
	ds_read_b128 v[158:161], v173
	ds_read_b128 v[162:165], v173 offset:1024
	ds_read_b128 v[166:169], v173 offset:2048
	ds_read_b128 v[174:177], v173 offset:3072
	v_lshl_add_u64 v[182:183], s[34:35], 0, v[146:147]
	s_add_i32 m0, s31, 0xc000
	ds_read_b128 v[178:181], v172
	ds_read_b128 v[200:203], v172 offset:1024
	ds_read_b128 v[204:207], v172 offset:2048
	ds_read_b128 v[208:211], v172 offset:3072
	ds_read_b128 v[212:215], v172 offset:4096
	ds_read_b128 v[216:219], v172 offset:5120
	ds_read_b128 v[220:223], v172 offset:6144
	ds_read_b128 v[234:237], v172 offset:7168
	global_load_lds_dwordx4 v[182:183], off
	s_add_i32 m0, s31, 0xe000
	v_lshl_add_u64 v[182:183], s[34:35], 0, v[148:149]
	global_load_lds_dwordx4 v[182:183], off
	s_waitcnt vmcnt(8) lgkmcnt(0)
	s_barrier
; #define PG8_STAGE(bufoff, gbase, voff) do { _Pragma("unroll") for (int _i = 0; _i < 2; ++_i) \
;         __builtin_amdgcn_global_load_lds((const unsigned*)((const char*)(gbase) + (voff)[_i]), (LAS unsigned*)(lds + (bufoff) + ldsw + _i * 8192), 16, 0, 0); } while (0)
; #define PG8_LDA(dst, b, h) do { _Pragma("unroll") for (int m = 0; m < 4; ++m) _Pragma("unroll") for (int k = 0; k < 2; ++k) dst[m][k] = *(const LAS bf16x8*)(lds + PG8_SA(b, h) + aoff + m * 2048 + k * 1024); } while (0)
; #define PG8_LDB(dst, b, h) do { _Pragma("unroll") for (int n = 0; n < 2; ++n) _Pragma("unroll") for (int k = 0; k < 2; ++k) dst[n][k] = *(const LAS bf16x8*)(lds + PG8_SB(b, h) + boff + n * 2048 + k * 1024); } while (0)
; #define PG8_MMA(ai, bj, At, Bt) do { __builtin_amdgcn_s_setprio(1); _Pragma("unroll") for (int m = 0; m < 4; ++m) _Pragma("unroll") for (int n = 0; n < 2; ++n) _Pragma("unroll") for (int k = 0; k < 2; ++k) \
;         acc[ai][bj][m][n] = __builtin_amdgcn_mfma_f32_16x16x32_bf16(Bt[n][k], At[m][k], acc[ai][bj][m][n], 0, 0, 0); __builtin_amdgcn_s_setprio(0); } while (0)
; #define PG8_WAIT_V(n) asm volatile("s_waitcnt vmcnt(" #n ")" ::: "memory")
; #define PG8_WAIT_L(n) asm volatile("s_waitcnt lgkmcnt(" #n ")" ::: "memory")
; #define PG8_BAR __builtin_amdgcn_s_barrier()
; #define PG8_SCHED __builtin_amdgcn_sched_barrier(0)
; template <class Epi, class Sched>
; DI void gemm_phase(LAS unsigned char* lds, const int wv, const int lda, const int ldb, const Sched& S, const Epi& E) {
;     ...
;             PG8_WAIT_V(8); PG8_WAIT_L(0); PG8_BAR; PG8_MMA(0, 0, At, B0); PG8_MMA(0, 1, At, B1); PG8_BAR; PG8_SCHED;
;             PG8_LDA(At, 0, 1); PG8_STAGE(PG8_SB(0, 0), b2, voffB); PG8_STAGE(PG8_SB(0, 1), b2 + hstepB, voffB); PG8_STAGE(PG8_SA(0, 0), a2, voffA);
;             PG8_WAIT_V(8); PG8_WAIT_L(0); PG8_BAR; PG8_MMA(1, 0, At, B0); PG8_MMA(1, 1, At, B1); PG8_BAR; PG8_SCHED;
;             PG8_LDB(B0, 1, 0); PG8_LDB(B1, 1, 1); PG8_SCHED; PG8_LDA(At, 1, 0); PG8_STAGE(PG8_SA(0, 1), a2 + hstepA, voffA);
;             PG8_WAIT_V(8); PG8_WAIT_L(0); PG8_BAR; PG8_MMA(0, 0, At, B0); PG8_MMA(0, 1, At, B1); PG8_BAR; PG8_SCHED;
	v_mfma_f32_16x16x32_bf16 v[132:135], v[104:107], v[178:181], v[132:135]
	v_mfma_f32_16x16x32_bf16 v[128:131], v[150:153], v[178:181], v[128:131]
	v_mfma_f32_16x16x32_bf16 v[124:127], v[104:107], v[204:207], v[124:127]
	v_mfma_f32_16x16x32_bf16 v[120:123], v[150:153], v[204:207], v[120:123]
	v_mfma_f32_16x16x32_bf16 v[116:119], v[104:107], v[212:215], v[116:119]
	v_mfma_f32_16x16x32_bf16 v[112:115], v[150:153], v[212:215], v[112:115]
	v_mfma_f32_16x16x32_bf16 v[100:103], v[104:107], v[220:223], v[100:103]
	v_mfma_f32_16x16x32_bf16 v[96:99], v[150:153], v[220:223], v[96:99]
	v_mfma_f32_16x16x32_bf16 v[132:135], v[108:111], v[200:203], v[132:135]
	v_mfma_f32_16x16x32_bf16 v[128:131], v[154:157], v[200:203], v[128:131]
	v_mfma_f32_16x16x32_bf16 v[124:127], v[108:111], v[208:211], v[124:127]
	v_mfma_f32_16x16x32_bf16 v[120:123], v[154:157], v[208:211], v[120:123]
	v_mfma_f32_16x16x32_bf16 v[116:119], v[108:111], v[216:219], v[116:119]
	v_mfma_f32_16x16x32_bf16 v[112:115], v[154:157], v[216:219], v[112:115]
	v_mfma_f32_16x16x32_bf16 v[100:103], v[108:111], v[234:237], v[100:103]
	v_mfma_f32_16x16x32_bf16 v[96:99], v[154:157], v[234:237], v[96:99]
	v_mfma_f32_16x16x32_bf16 v[60:63], v[158:161], v[178:181], v[60:63]
	v_mfma_f32_16x16x32_bf16 v[56:59], v[166:169], v[178:181], v[56:59]
	v_mfma_f32_16x16x32_bf16 v[52:55], v[158:161], v[204:207], v[52:55]
	v_mfma_f32_16x16x32_bf16 v[48:51], v[166:169], v[204:207], v[48:51]
	v_mfma_f32_16x16x32_bf16 v[44:47], v[158:161], v[212:215], v[44:47]
	v_mfma_f32_16x16x32_bf16 v[40:43], v[166:169], v[212:215], v[40:43]
	v_mfma_f32_16x16x32_bf16 v[36:39], v[158:161], v[220:223], v[36:39]
	v_mfma_f32_16x16x32_bf16 v[32:35], v[166:169], v[220:223], v[32:35]
	v_mfma_f32_16x16x32_bf16 v[60:63], v[162:165], v[200:203], v[60:63]
	v_mfma_f32_16x16x32_bf16 v[56:59], v[174:177], v[200:203], v[56:59]
	v_mfma_f32_16x16x32_bf16 v[52:55], v[162:165], v[208:211], v[52:55]
	v_mfma_f32_16x16x32_bf16 v[48:51], v[174:177], v[208:211], v[48:51]
	v_mfma_f32_16x16x32_bf16 v[44:47], v[162:165], v[216:219], v[44:47]
	v_mfma_f32_16x16x32_bf16 v[40:43], v[174:177], v[216:219], v[40:43]
	v_mfma_f32_16x16x32_bf16 v[36:39], v[162:165], v[234:237], v[36:39]
	v_mfma_f32_16x16x32_bf16 v[32:35], v[174:177], v[234:237], v[32:35]
	s_barrier
	s_add_i32 s61, s61, s47
	v_lshl_add_u64 v[182:183], s[36:37], 0, v[138:139]
	s_mov_b32 m0, s61
	ds_read_b128 v[178:181], v172 offset:16384
	ds_read_b128 v[200:203], v172 offset:17408
	ds_read_b128 v[204:207], v172 offset:18432
	ds_read_b128 v[208:211], v172 offset:19456
	ds_read_b128 v[212:215], v172 offset:20480
	ds_read_b128 v[216:219], v172 offset:21504
	ds_read_b128 v[220:223], v172 offset:22528
	ds_read_b128 v[234:237], v172 offset:23552
	global_load_lds_dwordx4 v[182:183], off
	s_add_i32 m0, s61, 0x2000
	s_add_u32 s62, s36, 0x80000
	v_lshl_add_u64 v[188:189], s[36:37], 0, v[142:143]
	s_addc_u32 s63, s37, 0
	s_add_i32 s33, s33, s47
	global_load_lds_dwordx4 v[188:189], off
	v_lshl_add_u64 v[190:191], s[62:63], 0, v[138:139]
	s_mov_b32 m0, s33
	v_lshl_add_u64 v[196:197], s[38:39], 0, v[140:141]
	global_load_lds_dwordx4 v[190:191], off
	s_add_i32 m0, s33, 0x2000
	v_lshl_add_u64 v[190:191], s[62:63], 0, v[142:143]
	global_load_lds_dwordx4 v[190:191], off
	s_mov_b32 m0, s31
	v_lshl_add_u64 v[190:191], s[38:39], 0, v[136:137]
	global_load_lds_dwordx4 v[190:191], off
	s_mov_b32 m0, s48
	s_nop 0
	global_load_lds_dwordx4 v[196:197], off
	s_waitcnt vmcnt(8) lgkmcnt(0)
	s_barrier
	v_mfma_f32_16x16x32_bf16 v[92:95], v[104:107], v[178:181], v[92:95]
	v_mfma_f32_16x16x32_bf16 v[88:91], v[150:153], v[178:181], v[88:91]
	v_mfma_f32_16x16x32_bf16 v[84:87], v[104:107], v[204:207], v[84:87]
	v_mfma_f32_16x16x32_bf16 v[80:83], v[150:153], v[204:207], v[80:83]
	v_mfma_f32_16x16x32_bf16 v[76:79], v[104:107], v[212:215], v[76:79]
	v_mfma_f32_16x16x32_bf16 v[72:75], v[150:153], v[212:215], v[72:75]
	v_mfma_f32_16x16x32_bf16 v[68:71], v[104:107], v[220:223], v[68:71]
	v_mfma_f32_16x16x32_bf16 v[64:67], v[150:153], v[220:223], v[64:67]
	v_mfma_f32_16x16x32_bf16 v[92:95], v[108:111], v[200:203], v[92:95]
	v_mfma_f32_16x16x32_bf16 v[88:91], v[154:157], v[200:203], v[88:91]
	v_mfma_f32_16x16x32_bf16 v[84:87], v[108:111], v[208:211], v[84:87]
	v_mfma_f32_16x16x32_bf16 v[80:83], v[154:157], v[208:211], v[80:83]
	v_mfma_f32_16x16x32_bf16 v[76:79], v[108:111], v[216:219], v[76:79]
	v_mfma_f32_16x16x32_bf16 v[72:75], v[154:157], v[216:219], v[72:75]
	v_mfma_f32_16x16x32_bf16 v[68:71], v[108:111], v[234:237], v[68:71]
	v_mfma_f32_16x16x32_bf16 v[64:67], v[154:157], v[234:237], v[64:67]
	v_mfma_f32_16x16x32_bf16 v[28:31], v[158:161], v[178:181], v[28:31]
	v_mfma_f32_16x16x32_bf16 v[24:27], v[166:169], v[178:181], v[24:27]
	v_mfma_f32_16x16x32_bf16 v[20:23], v[158:161], v[204:207], v[20:23]
	v_mfma_f32_16x16x32_bf16 v[16:19], v[166:169], v[204:207], v[16:19]
	v_mfma_f32_16x16x32_bf16 v[12:15], v[158:161], v[212:215], v[12:15]
	v_mfma_f32_16x16x32_bf16 v[8:11], v[166:169], v[212:215], v[8:11]
	v_mfma_f32_16x16x32_bf16 v[4:7], v[158:161], v[220:223], v[4:7]
	v_mfma_f32_16x16x32_bf16 v[0:3], v[166:169], v[220:223], v[0:3]
	v_mfma_f32_16x16x32_bf16 v[28:31], v[162:165], v[200:203], v[28:31]
	v_mfma_f32_16x16x32_bf16 v[24:27], v[174:177], v[200:203], v[24:27]
	v_mfma_f32_16x16x32_bf16 v[20:23], v[162:165], v[208:211], v[20:23]
	v_mfma_f32_16x16x32_bf16 v[16:19], v[174:177], v[208:211], v[16:19]
	v_mfma_f32_16x16x32_bf16 v[12:15], v[162:165], v[216:219], v[12:15]
	v_mfma_f32_16x16x32_bf16 v[8:11], v[174:177], v[216:219], v[8:11]
	v_mfma_f32_16x16x32_bf16 v[4:7], v[162:165], v[234:237], v[4:7]
	v_mfma_f32_16x16x32_bf16 v[0:3], v[174:177], v[234:237], v[0:3]
	s_barrier
; #define PG8_STAGE(bufoff, gbase, voff) do { _Pragma("unroll") for (int _i = 0; _i < 2; ++_i) \
;         __builtin_amdgcn_global_load_lds((const unsigned*)((const char*)(gbase) + (voff)[_i]), (LAS unsigned*)(lds + (bufoff) + ldsw + _i * 8192), 16, 0, 0); } while (0)
; #define PG8_LDA(dst, b, h) do { _Pragma("unroll") for (int m = 0; m < 4; ++m) _Pragma("unroll") for (int k = 0; k < 2; ++k) dst[m][k] = *(const LAS bf16x8*)(lds + PG8_SA(b, h) + aoff + m * 2048 + k * 1024); } while (0)
; #define PG8_LDB(dst, b, h) do { _Pragma("unroll") for (int n = 0; n < 2; ++n) _Pragma("unroll") for (int k = 0; k < 2; ++k) dst[n][k] = *(const LAS bf16x8*)(lds + PG8_SB(b, h) + boff + n * 2048 + k * 1024); } while (0)
; #define PG8_MMA(ai, bj, At, Bt) do { __builtin_amdgcn_s_setprio(1); _Pragma("unroll") for (int m = 0; m < 4; ++m) _Pragma("unroll") for (int n = 0; n < 2; ++n) _Pragma("unroll") for (int k = 0; k < 2; ++k) \
;         acc[ai][bj][m][n] = __builtin_amdgcn_mfma_f32_16x16x32_bf16(Bt[n][k], At[m][k], acc[ai][bj][m][n], 0, 0, 0); __builtin_amdgcn_s_setprio(0); } while (0)
; #define PG8_WAIT_V(n) asm volatile("s_waitcnt vmcnt(" #n ")" ::: "memory")
; #define PG8_WAIT_L(n) asm volatile("s_waitcnt lgkmcnt(" #n ")" ::: "memory")
; #define PG8_BAR __builtin_amdgcn_s_barrier()
; #define PG8_SCHED __builtin_amdgcn_sched_barrier(0)
; template <class Epi, class Sched>
; DI void gemm_phase(LAS unsigned char* lds, const int wv, const int lda, const int ldb, const Sched& S, const Epi& E) {
;     ...
;             PG8_LDB(B0, 1, 0); PG8_LDB(B1, 1, 1); PG8_SCHED; PG8_LDA(At, 1, 0); PG8_STAGE(PG8_SA(0, 1), a2 + hstepA, voffA);
;             PG8_WAIT_V(8); PG8_WAIT_L(0); PG8_BAR; PG8_MMA(0, 0, At, B0); PG8_MMA(0, 1, At, B1); PG8_BAR; PG8_SCHED;
;             PG8_LDA(At, 1, 1); PG8_STAGE(PG8_SB(1, 0), b3, voffB); PG8_STAGE(PG8_SB(1, 1), b3 + hstepB, voffB); PG8_STAGE(PG8_SA(1, 0), a3, voffA);
;             PG8_WAIT_V(8); PG8_WAIT_L(0); PG8_BAR; PG8_MMA(1, 0, At, B0); PG8_MMA(1, 1, At, B1); PG8_BAR; PG8_SCHED;
;         }
;         if (wr == 0) PG8_BAR;
	s_add_i32 s33, 0, 0x18000
	s_add_i32 s61, 0, 0x1c000
	v_add_u32_e32 v154, s33, v170
	v_add_u32_e32 v173, s61, v170
	ds_read_b128 v[104:107], v154
	ds_read_b128 v[108:111], v154 offset:1024
	ds_read_b128 v[150:153], v154 offset:2048
	ds_read_b128 v[154:157], v154 offset:3072
	ds_read_b128 v[158:161], v173
	ds_read_b128 v[162:165], v173 offset:1024
	ds_read_b128 v[166:169], v173 offset:2048
	ds_read_b128 v[174:177], v173 offset:3072
	s_add_u32 s38, s38, 0x80000
	s_addc_u32 s39, s39, 0
	s_mov_b32 m0, s49
	v_lshl_add_u64 v[198:199], s[38:39], 0, v[136:137]
	ds_read_b128 v[178:181], v172 offset:32768
	ds_read_b128 v[200:203], v172 offset:33792
	ds_read_b128 v[204:207], v172 offset:34816
	ds_read_b128 v[208:211], v172 offset:35840
	ds_read_b128 v[212:215], v172 offset:36864
	ds_read_b128 v[216:219], v172 offset:37888
	ds_read_b128 v[220:223], v172 offset:38912
	ds_read_b128 v[234:237], v172 offset:39936
	global_load_lds_dwordx4 v[198:199], off
	s_mov_b32 m0, s50
	v_lshl_add_u64 v[198:199], s[38:39], 0, v[140:141]
	global_load_lds_dwordx4 v[198:199], off
	s_waitcnt vmcnt(8) lgkmcnt(0)
	s_barrier
	v_mfma_f32_16x16x32_bf16 v[132:135], v[104:107], v[178:181], v[132:135]
	v_mfma_f32_16x16x32_bf16 v[128:131], v[150:153], v[178:181], v[128:131]
	v_mfma_f32_16x16x32_bf16 v[124:127], v[104:107], v[204:207], v[124:127]
	v_mfma_f32_16x16x32_bf16 v[120:123], v[150:153], v[204:207], v[120:123]
	v_mfma_f32_16x16x32_bf16 v[116:119], v[104:107], v[212:215], v[116:119]
	v_mfma_f32_16x16x32_bf16 v[112:115], v[150:153], v[212:215], v[112:115]
	v_mfma_f32_16x16x32_bf16 v[100:103], v[104:107], v[220:223], v[100:103]
	v_mfma_f32_16x16x32_bf16 v[96:99], v[150:153], v[220:223], v[96:99]
	v_mfma_f32_16x16x32_bf16 v[132:135], v[108:111], v[200:203], v[132:135]
	v_mfma_f32_16x16x32_bf16 v[128:131], v[154:157], v[200:203], v[128:131]
	v_mfma_f32_16x16x32_bf16 v[124:127], v[108:111], v[208:211], v[124:127]
	v_mfma_f32_16x16x32_bf16 v[120:123], v[154:157], v[208:211], v[120:123]
	v_mfma_f32_16x16x32_bf16 v[116:119], v[108:111], v[216:219], v[116:119]
	v_mfma_f32_16x16x32_bf16 v[112:115], v[154:157], v[216:219], v[112:115]
	v_mfma_f32_16x16x32_bf16 v[100:103], v[108:111], v[234:237], v[100:103]
	v_mfma_f32_16x16x32_bf16 v[96:99], v[154:157], v[234:237], v[96:99]
	v_mfma_f32_16x16x32_bf16 v[60:63], v[158:161], v[178:181], v[60:63]
	v_mfma_f32_16x16x32_bf16 v[56:59], v[166:169], v[178:181], v[56:59]
	v_mfma_f32_16x16x32_bf16 v[52:55], v[158:161], v[204:207], v[52:55]
	v_mfma_f32_16x16x32_bf16 v[48:51], v[166:169], v[204:207], v[48:51]
	v_mfma_f32_16x16x32_bf16 v[44:47], v[158:161], v[212:215], v[44:47]
	v_mfma_f32_16x16x32_bf16 v[40:43], v[166:169], v[212:215], v[40:43]
	v_mfma_f32_16x16x32_bf16 v[36:39], v[158:161], v[220:223], v[36:39]
	v_mfma_f32_16x16x32_bf16 v[32:35], v[166:169], v[220:223], v[32:35]
	v_mfma_f32_16x16x32_bf16 v[60:63], v[162:165], v[200:203], v[60:63]
	v_mfma_f32_16x16x32_bf16 v[56:59], v[174:177], v[200:203], v[56:59]
	v_mfma_f32_16x16x32_bf16 v[52:55], v[162:165], v[208:211], v[52:55]
	v_mfma_f32_16x16x32_bf16 v[48:51], v[174:177], v[208:211], v[48:51]
	v_mfma_f32_16x16x32_bf16 v[44:47], v[162:165], v[216:219], v[44:47]
	v_mfma_f32_16x16x32_bf16 v[40:43], v[174:177], v[216:219], v[40:43]
	v_mfma_f32_16x16x32_bf16 v[36:39], v[162:165], v[234:237], v[36:39]
	v_mfma_f32_16x16x32_bf16 v[32:35], v[174:177], v[234:237], v[32:35]
	s_barrier
	s_add_i32 s33, s33, s47
	v_lshl_add_u64 v[182:183], v[182:183], 0, s[28:29]
	s_mov_b32 m0, s33
	ds_read_b128 v[178:181], v172 offset:49152
	ds_read_b128 v[200:203], v172 offset:50176
	ds_read_b128 v[204:207], v172 offset:51200
	ds_read_b128 v[208:211], v172 offset:52224
	ds_read_b128 v[212:215], v172 offset:53248
	ds_read_b128 v[216:219], v172 offset:54272
	ds_read_b128 v[220:223], v172 offset:55296
	ds_read_b128 v[234:237], v172 offset:56320
	global_load_lds_dwordx4 v[182:183], off
	s_add_i32 m0, s33, 0x2000
	s_add_u32 s36, s36, 0x80080
	v_lshl_add_u64 v[182:183], v[188:189], 0, s[28:29]
	s_addc_u32 s37, s37, 0
	s_add_i32 s33, s61, s47
	global_load_lds_dwordx4 v[182:183], off
	s_mov_b32 m0, s33
	v_lshl_add_u64 v[182:183], s[36:37], 0, v[138:139]
	global_load_lds_dwordx4 v[182:183], off
	s_add_i32 m0, s33, 0x2000
	v_lshl_add_u64 v[182:183], s[36:37], 0, v[142:143]
	global_load_lds_dwordx4 v[182:183], off
	s_mov_b32 m0, s52
	v_lshl_add_u64 v[182:183], v[190:191], 0, s[28:29]
	global_load_lds_dwordx4 v[182:183], off
	s_mov_b32 m0, s53
	v_lshl_add_u64 v[182:183], v[196:197], 0, s[28:29]
	global_load_lds_dwordx4 v[182:183], off
	s_waitcnt vmcnt(8) lgkmcnt(0)
	s_barrier
	v_mfma_f32_16x16x32_bf16 v[92:95], v[104:107], v[178:181], v[92:95]
	v_mfma_f32_16x16x32_bf16 v[88:91], v[150:153], v[178:181], v[88:91]
	v_mfma_f32_16x16x32_bf16 v[84:87], v[104:107], v[204:207], v[84:87]
	v_mfma_f32_16x16x32_bf16 v[80:83], v[150:153], v[204:207], v[80:83]
	v_mfma_f32_16x16x32_bf16 v[76:79], v[104:107], v[212:215], v[76:79]
	v_mfma_f32_16x16x32_bf16 v[72:75], v[150:153], v[212:215], v[72:75]
	v_mfma_f32_16x16x32_bf16 v[68:71], v[104:107], v[220:223], v[68:71]
	v_mfma_f32_16x16x32_bf16 v[64:67], v[150:153], v[220:223], v[64:67]
	v_mfma_f32_16x16x32_bf16 v[92:95], v[108:111], v[200:203], v[92:95]
	v_mfma_f32_16x16x32_bf16 v[88:91], v[154:157], v[200:203], v[88:91]
	v_mfma_f32_16x16x32_bf16 v[84:87], v[108:111], v[208:211], v[84:87]
	v_mfma_f32_16x16x32_bf16 v[80:83], v[154:157], v[208:211], v[80:83]
	v_mfma_f32_16x16x32_bf16 v[76:79], v[108:111], v[216:219], v[76:79]
	v_mfma_f32_16x16x32_bf16 v[72:75], v[154:157], v[216:219], v[72:75]
	v_mfma_f32_16x16x32_bf16 v[68:71], v[108:111], v[234:237], v[68:71]
	v_mfma_f32_16x16x32_bf16 v[64:67], v[154:157], v[234:237], v[64:67]
	v_mfma_f32_16x16x32_bf16 v[28:31], v[158:161], v[178:181], v[28:31]
	v_mfma_f32_16x16x32_bf16 v[24:27], v[166:169], v[178:181], v[24:27]
	v_mfma_f32_16x16x32_bf16 v[20:23], v[158:161], v[204:207], v[20:23]
	v_mfma_f32_16x16x32_bf16 v[16:19], v[166:169], v[204:207], v[16:19]
	v_mfma_f32_16x16x32_bf16 v[12:15], v[158:161], v[212:215], v[12:15]
	v_mfma_f32_16x16x32_bf16 v[8:11], v[166:169], v[212:215], v[8:11]
	v_mfma_f32_16x16x32_bf16 v[4:7], v[158:161], v[220:223], v[4:7]
	v_mfma_f32_16x16x32_bf16 v[0:3], v[166:169], v[220:223], v[0:3]
	v_mfma_f32_16x16x32_bf16 v[28:31], v[162:165], v[200:203], v[28:31]
	v_mfma_f32_16x16x32_bf16 v[24:27], v[174:177], v[200:203], v[24:27]
	v_mfma_f32_16x16x32_bf16 v[20:23], v[162:165], v[208:211], v[20:23]
	v_mfma_f32_16x16x32_bf16 v[16:19], v[174:177], v[208:211], v[16:19]
	v_mfma_f32_16x16x32_bf16 v[12:15], v[162:165], v[216:219], v[12:15]
	v_mfma_f32_16x16x32_bf16 v[8:11], v[174:177], v[216:219], v[8:11]
	v_mfma_f32_16x16x32_bf16 v[4:7], v[162:165], v[234:237], v[4:7]
	v_mfma_f32_16x16x32_bf16 v[0:3], v[174:177], v[234:237], v[0:3]
	s_barrier
	s_add_i32 s23, s23, 2
	s_add_u32 s34, s34, 0x100
	s_addc_u32 s35, s35, 0
	s_add_u32 s17, s17, 0x100
	s_addc_u32 s19, s19, 0
	s_cmp_gt_u32 s23, 29
	s_cbranch_scc0 .LBB0_378
	s_and_b64 vcc, exec, s[14:15]
	s_cbranch_vccz .LBB0_381
	s_barrier

; DI void rwkv_scan_phase(const Frame& F, int h, int vs) {
;     ...
;         for (int cc = 0; cc < SC_NS - 1; ++cc) SC_DMA(cc);
.LBB0_821:
	s_add_u32 s0, s2, 0x78a00
	s_addc_u32 s1, s3, 0
	v_readlane_b32 s4, v254, 21
	s_add_i32 m0, s4, 0x2a00
	v_lshl_add_u64 v[8:9], s[0:1], 0, v[0:1]
	global_load_lds_dwordx4 v[8:9], off
	v_lshl_add_u64 v[8:9], s[0:1], 0, v[2:3]
	s_add_i32 m0, s10, 0x2a00
	v_readlane_b32 s0, v253, 61
	global_load_lds_dwordx4 v[8:9], off
	v_readlane_b32 s1, v253, 62
	s_andn2_b64 vcc, exec, s[0:1]
	s_nop 0
	v_cndmask_b32_e64 v8, 0, 1, s[0:1]
	v_cmp_ne_u32_e64 s[4:5], 1, v8
	s_mov_b64 s[0:1], -1
	s_cbranch_vccnz .LBB0_823
	s_mov_b64 s[0:1], 0x84a00
	v_lshl_add_u64 v[8:9], v[6:7], 0, s[0:1]
	v_readlane_b32 s0, v253, 52
	s_add_i32 s0, s0, 0
	s_add_i32 m0, s0, 0x4c00
	s_mov_b64 s[0:1], 0
	global_load_lds_dword v[8:9], off

;     DI bool next(int i, Unit& u) const { const long L = (long)i * G + c; if (L >= T.nwg) return false; T.map((int)L, u.pm, u.pn); u.seg = 0; return true; }
;     DI bool next(int i, Unit& u) const { const int ti = i / 3; const long L = (long)ti * G + c; if (L >= T.nwg) return false; T.map((int)L, u.pm, u.pn); u.seg = i - 3 * ti; return true; }
;     DI const char* aptr(const Unit& u) const { return A + (size_t)u.pm * ta + (size_t)kofs(u.seg) * 2; }
;     DI const char* bptr(const Unit& u) const { return B + (size_t)u.pn * tb + (size_t)kofs(u.seg) * 2; }
; #define PG8_STAGE(bufoff, gbase, voff) do { _Pragma("unroll") for (int _i = 0; _i < 2; ++_i) \
;         __builtin_amdgcn_global_load_lds((const unsigned*)((const char*)(gbase) + (voff)[_i]), (LAS unsigned*)(lds + (bufoff) + ldsw + _i * 8192), 16, 0, 0); } while (0)
; #define PG8_LDA(dst, b, h) do { _Pragma("unroll") for (int m = 0; m < 4; ++m) _Pragma("unroll") for (int k = 0; k < 2; ++k) dst[m][k] = *(const LAS bf16x8*)(lds + PG8_SA(b, h) + aoff + m * 2048 + k * 1024); } while (0)
; #define PG8_WAIT_V(n) asm volatile("s_waitcnt vmcnt(" #n ")" ::: "memory")
; #define PG8_WAIT_L(n) asm volatile("s_waitcnt lgkmcnt(" #n ")" ::: "memory")
; template <class Epi, class Sched>
; DI void gemm_phase(LAS unsigned char* lds, const int wv, const int lda, const int ldb, const Sched& S, const Epi& E) {
;     ...
;         const bool has_next = S.next(ui + 1, nxt);
;         const char* nA = has_next ? S.aptr(nxt) : cA; const char* nB = has_next ? S.bptr(nxt) : cB;
;         for (int t = 0; t < nt; t += 2) {
;             const bool last = (t == nt - 2);
;             const char* a1 = cA + (size_t)(t + 1) * kstep;
;             const char* a2 = last ? nA : cA + (size_t)(t + 2) * kstep; const char* b2 = last ? nB : cB + (size_t)(t + 2) * kstep;
;             const char* a3 = a2 + kstep; const char* b3 = b2 + kstep;
;             PG8_LDB(B0, 0, 0); PG8_LDB(B1, 0, 1); PG8_SCHED; PG8_LDA(At, 0, 0); PG8_STAGE(PG8_SA(1, 1), a1 + hstepA, voffA);
;             PG8_WAIT_V(8); PG8_WAIT_L(0); PG8_BAR; PG8_MMA(0, 0, At, B0); PG8_MMA(0, 1, At, B1); PG8_BAR; PG8_SCHED;
;             PG8_LDA(At, 0, 1); PG8_STAGE(PG8_SB(0, 0), b2, voffB); PG8_STAGE(PG8_SB(0, 1), b2 + hstepB, voffB); PG8_STAGE(PG8_SA(0, 0), a2, voffA);
;             PG8_WAIT_V(8); PG8_WAIT_L(0); PG8_BAR; PG8_MMA(1, 0, At, B0); PG8_MMA(1, 1, At, B1); PG8_BAR; PG8_SCHED;
.LBB0_1098:
	s_add_u32 s0, s24, 0x100
	s_addc_u32 s1, s25, 0
	s_mov_b32 s49, -2
	s_add_u32 s24, s22, 0x100
	s_addc_u32 s25, s23, 0
	s_add_i32 s50, 0, 0x10000
	s_cmp_eq_u32 s49, 8
	s_cselect_b32 s31, s7, s25
	s_cselect_b32 s30, s6, s24
	s_cselect_b32 s27, s19, s1
	s_cselect_b32 s26, s18, s0
	s_add_i32 s51, 0, 0x14000
	v_add_u32_e32 v108, s50, v204
	v_add_u32_e32 v156, s51, v204
	ds_read_b128 v[64:67], v108
	ds_read_b128 v[68:71], v108 offset:1024
	ds_read_b128 v[104:107], v108 offset:2048
	ds_read_b128 v[108:111], v108 offset:3072
	ds_read_b128 v[144:147], v156
	ds_read_b128 v[148:151], v156 offset:1024
	ds_read_b128 v[152:155], v156 offset:2048
	ds_read_b128 v[156:159], v156 offset:3072
	v_lshl_add_u64 v[182:183], s[22:23], 0, v[174:175]
	s_add_i32 m0, s38, 0xc000
	ds_read_b128 v[160:163], v206
	ds_read_b128 v[164:167], v206 offset:1024
	ds_read_b128 v[178:181], v206 offset:2048
	ds_read_b128 v[188:191], v206 offset:3072
	ds_read_b128 v[196:199], v206 offset:4096
	ds_read_b128 v[200:203], v206 offset:5120
	ds_read_b128 v[208:211], v206 offset:6144
	ds_read_b128 v[212:215], v206 offset:7168
	global_load_lds_dwordx4 v[182:183], off
	s_add_i32 m0, s38, 0xe000
	v_lshl_add_u64 v[182:183], s[22:23], 0, v[176:177]
	global_load_lds_dwordx4 v[182:183], off
	s_waitcnt vmcnt(8) lgkmcnt(0)
	s_barrier
	v_mfma_f32_16x16x32_bf16 v[140:143], v[64:67], v[160:163], 0
	v_mfma_f32_16x16x32_bf16 v[136:139], v[104:107], v[160:163], 0
	v_mfma_f32_16x16x32_bf16 v[132:135], v[64:67], v[178:181], 0
	v_mfma_f32_16x16x32_bf16 v[128:131], v[104:107], v[178:181], 0
	v_mfma_f32_16x16x32_bf16 v[124:127], v[64:67], v[196:199], 0
	v_mfma_f32_16x16x32_bf16 v[120:123], v[104:107], v[196:199], 0
	v_mfma_f32_16x16x32_bf16 v[116:119], v[64:67], v[208:211], 0
	v_mfma_f32_16x16x32_bf16 v[112:115], v[104:107], v[208:211], 0
	v_mfma_f32_16x16x32_bf16 v[140:143], v[68:71], v[164:167], v[140:143]
	v_mfma_f32_16x16x32_bf16 v[136:139], v[108:111], v[164:167], v[136:139]
	v_mfma_f32_16x16x32_bf16 v[132:135], v[68:71], v[188:191], v[132:135]
	v_mfma_f32_16x16x32_bf16 v[128:131], v[108:111], v[188:191], v[128:131]
	v_mfma_f32_16x16x32_bf16 v[124:127], v[68:71], v[200:203], v[124:127]
	v_mfma_f32_16x16x32_bf16 v[120:123], v[108:111], v[200:203], v[120:123]
	v_mfma_f32_16x16x32_bf16 v[116:119], v[68:71], v[212:215], v[116:119]
	v_mfma_f32_16x16x32_bf16 v[112:115], v[108:111], v[212:215], v[112:115]
	v_mfma_f32_16x16x32_bf16 v[100:103], v[144:147], v[160:163], 0
	v_mfma_f32_16x16x32_bf16 v[96:99], v[152:155], v[160:163], 0
	v_mfma_f32_16x16x32_bf16 v[92:95], v[144:147], v[178:181], 0
	v_mfma_f32_16x16x32_bf16 v[88:91], v[152:155], v[178:181], 0
	v_mfma_f32_16x16x32_bf16 v[84:87], v[144:147], v[196:199], 0
	v_mfma_f32_16x16x32_bf16 v[80:83], v[152:155], v[196:199], 0
	v_mfma_f32_16x16x32_bf16 v[76:79], v[144:147], v[208:211], 0
	v_mfma_f32_16x16x32_bf16 v[72:75], v[152:155], v[208:211], 0
	v_mfma_f32_16x16x32_bf16 v[100:103], v[148:151], v[164:167], v[100:103]
	v_mfma_f32_16x16x32_bf16 v[96:99], v[156:159], v[164:167], v[96:99]
	v_mfma_f32_16x16x32_bf16 v[92:95], v[148:151], v[188:191], v[92:95]
	v_mfma_f32_16x16x32_bf16 v[88:91], v[156:159], v[188:191], v[88:91]
	v_mfma_f32_16x16x32_bf16 v[84:87], v[148:151], v[200:203], v[84:87]
	v_mfma_f32_16x16x32_bf16 v[80:83], v[156:159], v[200:203], v[80:83]
	v_mfma_f32_16x16x32_bf16 v[76:79], v[148:151], v[212:215], v[76:79]
	v_mfma_f32_16x16x32_bf16 v[72:75], v[156:159], v[212:215], v[72:75]
	s_barrier
	s_add_i32 s22, s50, s36
	v_lshl_add_u64 v[182:183], s[26:27], 0, v[184:185]
	s_mov_b32 m0, s22
	ds_read_b128 v[160:163], v206 offset:16384
	ds_read_b128 v[164:167], v206 offset:17408
	ds_read_b128 v[178:181], v206 offset:18432
	ds_read_b128 v[188:191], v206 offset:19456
	ds_read_b128 v[196:199], v206 offset:20480
	ds_read_b128 v[200:203], v206 offset:21504
	ds_read_b128 v[208:211], v206 offset:22528
	ds_read_b128 v[212:215], v206 offset:23552
	global_load_lds_dwordx4 v[182:183], off
	s_add_i32 m0, s22, 0x2000
	s_add_u32 s22, s26, 0x30000
	v_lshl_add_u64 v[216:217], s[26:27], 0, v[168:169]
	s_addc_u32 s23, s27, 0
	s_add_i32 s50, s51, s36
	global_load_lds_dwordx4 v[216:217], off
	v_lshl_add_u64 v[218:219], s[22:23], 0, v[184:185]
	s_mov_b32 m0, s50
	v_lshl_add_u64 v[220:221], s[30:31], 0, v[170:171]
	global_load_lds_dwordx4 v[218:219], off
	s_add_i32 m0, s50, 0x2000
	v_lshl_add_u64 v[218:219], s[22:23], 0, v[168:169]
	global_load_lds_dwordx4 v[218:219], off
	s_mov_b32 m0, s38
	v_lshl_add_u64 v[218:219], s[30:31], 0, v[172:173]
	global_load_lds_dwordx4 v[218:219], off
	s_mov_b32 m0, s39
	s_nop 0
	global_load_lds_dwordx4 v[220:221], off
	s_waitcnt vmcnt(8) lgkmcnt(0)
	s_barrier
; #define PG8_STAGE(bufoff, gbase, voff) do { _Pragma("unroll") for (int _i = 0; _i < 2; ++_i) \
;         __builtin_amdgcn_global_load_lds((const unsigned*)((const char*)(gbase) + (voff)[_i]), (LAS unsigned*)(lds + (bufoff) + ldsw + _i * 8192), 16, 0, 0); } while (0)
; #define PG8_LDA(dst, b, h) do { _Pragma("unroll") for (int m = 0; m < 4; ++m) _Pragma("unroll") for (int k = 0; k < 2; ++k) dst[m][k] = *(const LAS bf16x8*)(lds + PG8_SA(b, h) + aoff + m * 2048 + k * 1024); } while (0)
; #define PG8_LDB(dst, b, h) do { _Pragma("unroll") for (int n = 0; n < 2; ++n) _Pragma("unroll") for (int k = 0; k < 2; ++k) dst[n][k] = *(const LAS bf16x8*)(lds + PG8_SB(b, h) + boff + n * 2048 + k * 1024); } while (0)
; #define PG8_MMA(ai, bj, At, Bt) do { __builtin_amdgcn_s_setprio(1); _Pragma("unroll") for (int m = 0; m < 4; ++m) _Pragma("unroll") for (int n = 0; n < 2; ++n) _Pragma("unroll") for (int k = 0; k < 2; ++k) \
;         acc[ai][bj][m][n] = __builtin_amdgcn_mfma_f32_16x16x32_bf16(Bt[n][k], At[m][k], acc[ai][bj][m][n], 0, 0, 0); __builtin_amdgcn_s_setprio(0); } while (0)
; #define PG8_WAIT_V(n) asm volatile("s_waitcnt vmcnt(" #n ")" ::: "memory")
; #define PG8_WAIT_L(n) asm volatile("s_waitcnt lgkmcnt(" #n ")" ::: "memory")
; #define PG8_BAR __builtin_amdgcn_s_barrier()
; #define PG8_SCHED __builtin_amdgcn_sched_barrier(0)
; template <class Epi, class Sched>
; DI void gemm_phase(LAS unsigned char* lds, const int wv, const int lda, const int ldb, const Sched& S, const Epi& E) {
;     ...
;             PG8_WAIT_V(8); PG8_WAIT_L(0); PG8_BAR; PG8_MMA(1, 0, At, B0); PG8_MMA(1, 1, At, B1); PG8_BAR; PG8_SCHED;
;             PG8_LDB(B0, 1, 0); PG8_LDB(B1, 1, 1); PG8_SCHED; PG8_LDA(At, 1, 0); PG8_STAGE(PG8_SA(0, 1), a2 + hstepA, voffA);
;             PG8_WAIT_V(8); PG8_WAIT_L(0); PG8_BAR; PG8_MMA(0, 0, At, B0); PG8_MMA(0, 1, At, B1); PG8_BAR; PG8_SCHED;
	v_mfma_f32_16x16x32_bf16 v[60:63], v[64:67], v[160:163], 0
	v_mfma_f32_16x16x32_bf16 v[56:59], v[104:107], v[160:163], 0
	v_mfma_f32_16x16x32_bf16 v[52:55], v[64:67], v[178:181], 0
	v_mfma_f32_16x16x32_bf16 v[48:51], v[104:107], v[178:181], 0
	v_mfma_f32_16x16x32_bf16 v[44:47], v[64:67], v[196:199], 0
	v_mfma_f32_16x16x32_bf16 v[40:43], v[104:107], v[196:199], 0
	v_mfma_f32_16x16x32_bf16 v[36:39], v[64:67], v[208:211], 0
	v_mfma_f32_16x16x32_bf16 v[32:35], v[104:107], v[208:211], 0
	v_mfma_f32_16x16x32_bf16 v[60:63], v[68:71], v[164:167], v[60:63]
	v_mfma_f32_16x16x32_bf16 v[56:59], v[108:111], v[164:167], v[56:59]
	v_mfma_f32_16x16x32_bf16 v[52:55], v[68:71], v[188:191], v[52:55]
	v_mfma_f32_16x16x32_bf16 v[48:51], v[108:111], v[188:191], v[48:51]
	v_mfma_f32_16x16x32_bf16 v[44:47], v[68:71], v[200:203], v[44:47]
	v_mfma_f32_16x16x32_bf16 v[40:43], v[108:111], v[200:203], v[40:43]
	v_mfma_f32_16x16x32_bf16 v[36:39], v[68:71], v[212:215], v[36:39]
	v_mfma_f32_16x16x32_bf16 v[32:35], v[108:111], v[212:215], v[32:35]
	v_mfma_f32_16x16x32_bf16 v[28:31], v[144:147], v[160:163], 0
	v_mfma_f32_16x16x32_bf16 v[24:27], v[152:155], v[160:163], 0
	v_mfma_f32_16x16x32_bf16 v[20:23], v[144:147], v[178:181], 0
	v_mfma_f32_16x16x32_bf16 v[16:19], v[152:155], v[178:181], 0
	v_mfma_f32_16x16x32_bf16 v[12:15], v[144:147], v[196:199], 0
	v_mfma_f32_16x16x32_bf16 v[8:11], v[152:155], v[196:199], 0
	v_mfma_f32_16x16x32_bf16 v[4:7], v[144:147], v[208:211], 0
	v_mfma_f32_16x16x32_bf16 v[0:3], v[152:155], v[208:211], 0
	v_mfma_f32_16x16x32_bf16 v[28:31], v[148:151], v[164:167], v[28:31]
	v_mfma_f32_16x16x32_bf16 v[24:27], v[156:159], v[164:167], v[24:27]
	v_mfma_f32_16x16x32_bf16 v[20:23], v[148:151], v[188:191], v[20:23]
	v_mfma_f32_16x16x32_bf16 v[16:19], v[156:159], v[188:191], v[16:19]
	v_mfma_f32_16x16x32_bf16 v[12:15], v[148:151], v[200:203], v[12:15]
	v_mfma_f32_16x16x32_bf16 v[8:11], v[156:159], v[200:203], v[8:11]
	v_mfma_f32_16x16x32_bf16 v[4:7], v[148:151], v[212:215], v[4:7]
	v_mfma_f32_16x16x32_bf16 v[0:3], v[156:159], v[212:215], v[0:3]
	s_barrier
	s_add_i32 s50, 0, 0x18000
	s_add_i32 s51, 0, 0x1c000
	v_add_u32_e32 v108, s50, v204
	v_add_u32_e32 v156, s51, v204
	ds_read_b128 v[64:67], v108
	ds_read_b128 v[68:71], v108 offset:1024
	ds_read_b128 v[104:107], v108 offset:2048
	ds_read_b128 v[108:111], v108 offset:3072
	ds_read_b128 v[144:147], v156
	ds_read_b128 v[148:151], v156 offset:1024
	ds_read_b128 v[152:155], v156 offset:2048
	ds_read_b128 v[156:159], v156 offset:3072
	s_add_u32 s22, s30, 0x30000
	s_addc_u32 s23, s31, 0
	s_mov_b32 m0, s40
	v_lshl_add_u64 v[222:223], s[22:23], 0, v[172:173]
	ds_read_b128 v[160:163], v206 offset:32768
	ds_read_b128 v[164:167], v206 offset:33792
	ds_read_b128 v[178:181], v206 offset:34816
	ds_read_b128 v[188:191], v206 offset:35840
	ds_read_b128 v[196:199], v206 offset:36864
	ds_read_b128 v[200:203], v206 offset:37888
	ds_read_b128 v[208:211], v206 offset:38912
	ds_read_b128 v[212:215], v206 offset:39936
	global_load_lds_dwordx4 v[222:223], off
	s_mov_b32 m0, s41
	v_lshl_add_u64 v[222:223], s[22:23], 0, v[170:171]
	global_load_lds_dwordx4 v[222:223], off
	s_waitcnt vmcnt(8) lgkmcnt(0)
	s_barrier
	v_mfma_f32_16x16x32_bf16 v[140:143], v[64:67], v[160:163], v[140:143]
	v_mfma_f32_16x16x32_bf16 v[136:139], v[104:107], v[160:163], v[136:139]
	v_mfma_f32_16x16x32_bf16 v[132:135], v[64:67], v[178:181], v[132:135]
	v_mfma_f32_16x16x32_bf16 v[128:131], v[104:107], v[178:181], v[128:131]
	v_mfma_f32_16x16x32_bf16 v[124:127], v[64:67], v[196:199], v[124:127]
	v_mfma_f32_16x16x32_bf16 v[120:123], v[104:107], v[196:199], v[120:123]
	v_mfma_f32_16x16x32_bf16 v[116:119], v[64:67], v[208:211], v[116:119]
	v_mfma_f32_16x16x32_bf16 v[112:115], v[104:107], v[208:211], v[112:115]
	v_mfma_f32_16x16x32_bf16 v[140:143], v[68:71], v[164:167], v[140:143]
	v_mfma_f32_16x16x32_bf16 v[136:139], v[108:111], v[164:167], v[136:139]
	v_mfma_f32_16x16x32_bf16 v[132:135], v[68:71], v[188:191], v[132:135]
	v_mfma_f32_16x16x32_bf16 v[128:131], v[108:111], v[188:191], v[128:131]
	v_mfma_f32_16x16x32_bf16 v[124:127], v[68:71], v[200:203], v[124:127]
	v_mfma_f32_16x16x32_bf16 v[120:123], v[108:111], v[200:203], v[120:123]
	v_mfma_f32_16x16x32_bf16 v[116:119], v[68:71], v[212:215], v[116:119]
	v_mfma_f32_16x16x32_bf16 v[112:115], v[108:111], v[212:215], v[112:115]
	v_mfma_f32_16x16x32_bf16 v[100:103], v[144:147], v[160:163], v[100:103]
	v_mfma_f32_16x16x32_bf16 v[96:99], v[152:155], v[160:163], v[96:99]
	v_mfma_f32_16x16x32_bf16 v[92:95], v[144:147], v[178:181], v[92:95]
	v_mfma_f32_16x16x32_bf16 v[88:91], v[152:155], v[178:181], v[88:91]
	v_mfma_f32_16x16x32_bf16 v[84:87], v[144:147], v[196:199], v[84:87]
	v_mfma_f32_16x16x32_bf16 v[80:83], v[152:155], v[196:199], v[80:83]
	v_mfma_f32_16x16x32_bf16 v[76:79], v[144:147], v[208:211], v[76:79]
	v_mfma_f32_16x16x32_bf16 v[72:75], v[152:155], v[208:211], v[72:75]
	v_mfma_f32_16x16x32_bf16 v[100:103], v[148:151], v[164:167], v[100:103]
	v_mfma_f32_16x16x32_bf16 v[96:99], v[156:159], v[164:167], v[96:99]
	v_mfma_f32_16x16x32_bf16 v[92:95], v[148:151], v[188:191], v[92:95]
	v_mfma_f32_16x16x32_bf16 v[88:91], v[156:159], v[188:191], v[88:91]
	v_mfma_f32_16x16x32_bf16 v[84:87], v[148:151], v[200:203], v[84:87]
	v_mfma_f32_16x16x32_bf16 v[80:83], v[156:159], v[200:203], v[80:83]
	v_mfma_f32_16x16x32_bf16 v[76:79], v[148:151], v[212:215], v[76:79]
	v_mfma_f32_16x16x32_bf16 v[72:75], v[156:159], v[212:215], v[72:75]
	s_barrier
; #define PG8_STAGE(bufoff, gbase, voff) do { _Pragma("unroll") for (int _i = 0; _i < 2; ++_i) \
;         __builtin_amdgcn_global_load_lds((const unsigned*)((const char*)(gbase) + (voff)[_i]), (LAS unsigned*)(lds + (bufoff) + ldsw + _i * 8192), 16, 0, 0); } while (0)
; #define PG8_LDA(dst, b, h) do { _Pragma("unroll") for (int m = 0; m < 4; ++m) _Pragma("unroll") for (int k = 0; k < 2; ++k) dst[m][k] = *(const LAS bf16x8*)(lds + PG8_SA(b, h) + aoff + m * 2048 + k * 1024); } while (0)
; #define PG8_LDB(dst, b, h) do { _Pragma("unroll") for (int n = 0; n < 2; ++n) _Pragma("unroll") for (int k = 0; k < 2; ++k) dst[n][k] = *(const LAS bf16x8*)(lds + PG8_SB(b, h) + boff + n * 2048 + k * 1024); } while (0)
; #define PG8_MMA(ai, bj, At, Bt) do { __builtin_amdgcn_s_setprio(1); _Pragma("unroll") for (int m = 0; m < 4; ++m) _Pragma("unroll") for (int n = 0; n < 2; ++n) _Pragma("unroll") for (int k = 0; k < 2; ++k) \
;         acc[ai][bj][m][n] = __builtin_amdgcn_mfma_f32_16x16x32_bf16(Bt[n][k], At[m][k], acc[ai][bj][m][n], 0, 0, 0); __builtin_amdgcn_s_setprio(0); } while (0)
; #define PG8_WAIT_V(n) asm volatile("s_waitcnt vmcnt(" #n ")" ::: "memory")
; #define PG8_WAIT_L(n) asm volatile("s_waitcnt lgkmcnt(" #n ")" ::: "memory")
; #define PG8_BAR __builtin_amdgcn_s_barrier()
; #define PG8_SCHED __builtin_amdgcn_sched_barrier(0)
; template <class Epi, class Sched>
; DI void gemm_phase(LAS unsigned char* lds, const int wv, const int lda, const int ldb, const Sched& S, const Epi& E) {
;     ...
;         for (int t = 0; t < nt; t += 2) {
;             const bool last = (t == nt - 2);
;             const char* a1 = cA + (size_t)(t + 1) * kstep;
;             const char* a2 = last ? nA : cA + (size_t)(t + 2) * kstep; const char* b2 = last ? nB : cB + (size_t)(t + 2) * kstep;
;             const char* a3 = a2 + kstep; const char* b3 = b2 + kstep;
;             PG8_LDB(B0, 0, 0); PG8_LDB(B1, 0, 1); PG8_SCHED; PG8_LDA(At, 0, 0); PG8_STAGE(PG8_SA(1, 1), a1 + hstepA, voffA);
;             PG8_WAIT_V(8); PG8_WAIT_L(0); PG8_BAR; PG8_MMA(0, 0, At, B0); PG8_MMA(0, 1, At, B1); PG8_BAR; PG8_SCHED;
;     ...
;             PG8_LDA(At, 1, 1); PG8_STAGE(PG8_SB(1, 0), b3, voffB); PG8_STAGE(PG8_SB(1, 1), b3 + hstepB, voffB); PG8_STAGE(PG8_SA(1, 0), a3, voffA);
;             PG8_WAIT_V(8); PG8_WAIT_L(0); PG8_BAR; PG8_MMA(1, 0, At, B0); PG8_MMA(1, 1, At, B1); PG8_BAR; PG8_SCHED;
	s_add_i32 s22, s50, s36
	v_lshl_add_u64 v[182:183], v[182:183], 0, s[28:29]
	s_mov_b32 m0, s22
	ds_read_b128 v[160:163], v206 offset:49152
	ds_read_b128 v[164:167], v206 offset:50176
	ds_read_b128 v[178:181], v206 offset:51200
	ds_read_b128 v[188:191], v206 offset:52224
	ds_read_b128 v[196:199], v206 offset:53248
	ds_read_b128 v[200:203], v206 offset:54272
	ds_read_b128 v[208:211], v206 offset:55296
	ds_read_b128 v[212:215], v206 offset:56320
	global_load_lds_dwordx4 v[182:183], off
	s_add_i32 m0, s22, 0x2000
	s_add_u32 s22, s26, 0x30080
	v_lshl_add_u64 v[182:183], v[216:217], 0, s[28:29]
	s_addc_u32 s23, s27, 0
	s_add_i32 s26, s51, s36
	global_load_lds_dwordx4 v[182:183], off
	s_mov_b32 m0, s26
	v_lshl_add_u64 v[182:183], s[22:23], 0, v[184:185]
	global_load_lds_dwordx4 v[182:183], off
	s_add_i32 m0, s26, 0x2000
	v_lshl_add_u64 v[182:183], s[22:23], 0, v[168:169]
	global_load_lds_dwordx4 v[182:183], off
	s_mov_b32 m0, s20
	v_lshl_add_u64 v[182:183], v[218:219], 0, s[28:29]
	global_load_lds_dwordx4 v[182:183], off
	s_mov_b32 m0, s42
	v_lshl_add_u64 v[182:183], v[220:221], 0, s[28:29]
	global_load_lds_dwordx4 v[182:183], off
	s_waitcnt vmcnt(8) lgkmcnt(0)
	s_barrier
	v_mfma_f32_16x16x32_bf16 v[60:63], v[64:67], v[160:163], v[60:63]
	v_mfma_f32_16x16x32_bf16 v[56:59], v[104:107], v[160:163], v[56:59]
	v_mfma_f32_16x16x32_bf16 v[52:55], v[64:67], v[178:181], v[52:55]
	v_mfma_f32_16x16x32_bf16 v[48:51], v[104:107], v[178:181], v[48:51]
	v_mfma_f32_16x16x32_bf16 v[44:47], v[64:67], v[196:199], v[44:47]
	v_mfma_f32_16x16x32_bf16 v[40:43], v[104:107], v[196:199], v[40:43]
	v_mfma_f32_16x16x32_bf16 v[36:39], v[64:67], v[208:211], v[36:39]
	v_mfma_f32_16x16x32_bf16 v[32:35], v[104:107], v[208:211], v[32:35]
	v_mfma_f32_16x16x32_bf16 v[60:63], v[68:71], v[164:167], v[60:63]
	v_mfma_f32_16x16x32_bf16 v[56:59], v[108:111], v[164:167], v[56:59]
	v_mfma_f32_16x16x32_bf16 v[52:55], v[68:71], v[188:191], v[52:55]
	v_mfma_f32_16x16x32_bf16 v[48:51], v[108:111], v[188:191], v[48:51]
	v_mfma_f32_16x16x32_bf16 v[44:47], v[68:71], v[200:203], v[44:47]
	v_mfma_f32_16x16x32_bf16 v[40:43], v[108:111], v[200:203], v[40:43]
	v_mfma_f32_16x16x32_bf16 v[36:39], v[68:71], v[212:215], v[36:39]
	v_mfma_f32_16x16x32_bf16 v[32:35], v[108:111], v[212:215], v[32:35]
	v_mfma_f32_16x16x32_bf16 v[28:31], v[144:147], v[160:163], v[28:31]
	v_mfma_f32_16x16x32_bf16 v[24:27], v[152:155], v[160:163], v[24:27]
	v_mfma_f32_16x16x32_bf16 v[20:23], v[144:147], v[178:181], v[20:23]
	v_mfma_f32_16x16x32_bf16 v[16:19], v[152:155], v[178:181], v[16:19]
	v_mfma_f32_16x16x32_bf16 v[12:15], v[144:147], v[196:199], v[12:15]
	v_mfma_f32_16x16x32_bf16 v[8:11], v[152:155], v[196:199], v[8:11]
	v_mfma_f32_16x16x32_bf16 v[4:7], v[144:147], v[208:211], v[4:7]
	v_mfma_f32_16x16x32_bf16 v[0:3], v[152:155], v[208:211], v[0:3]
	v_mfma_f32_16x16x32_bf16 v[28:31], v[148:151], v[164:167], v[28:31]
	v_mfma_f32_16x16x32_bf16 v[24:27], v[156:159], v[164:167], v[24:27]
	v_mfma_f32_16x16x32_bf16 v[20:23], v[148:151], v[188:191], v[20:23]
	v_mfma_f32_16x16x32_bf16 v[16:19], v[156:159], v[188:191], v[16:19]
	v_mfma_f32_16x16x32_bf16 v[12:15], v[148:151], v[200:203], v[12:15]
	v_mfma_f32_16x16x32_bf16 v[8:11], v[156:159], v[200:203], v[8:11]
	v_mfma_f32_16x16x32_bf16 v[4:7], v[148:151], v[212:215], v[4:7]
	v_mfma_f32_16x16x32_bf16 v[0:3], v[156:159], v[212:215], v[0:3]
	s_barrier
	s_add_i32 s49, s49, 2
	s_add_u32 s0, s0, 0x100
	s_addc_u32 s1, s1, 0
	s_mov_b64 s[22:23], s[24:25]
.LBB0_1099:
	s_add_u32 s24, s22, 0x100
	s_addc_u32 s25, s23, 0
	s_add_i32 s50, 0, 0x10000
	s_cmp_eq_u32 s49, 8
	s_cselect_b32 s31, s7, s25
	s_cselect_b32 s30, s6, s24
	s_cselect_b32 s27, s19, s1
	s_cselect_b32 s26, s18, s0
	s_add_i32 s51, 0, 0x14000
	v_add_u32_e32 v108, s50, v204
	v_add_u32_e32 v156, s51, v204
	ds_read_b128 v[64:67], v108
	ds_read_b128 v[68:71], v108 offset:1024
	ds_read_b128 v[104:107], v108 offset:2048
	ds_read_b128 v[108:111], v108 offset:3072
	ds_read_b128 v[144:147], v156
	ds_read_b128 v[148:151], v156 offset:1024
	ds_read_b128 v[152:155], v156 offset:2048
	ds_read_b128 v[156:159], v156 offset:3072
	v_lshl_add_u64 v[182:183], s[22:23], 0, v[174:175]
	s_add_i32 m0, s38, 0xc000
	ds_read_b128 v[160:163], v206
	ds_read_b128 v[164:167], v206 offset:1024
	ds_read_b128 v[178:181], v206 offset:2048
	ds_read_b128 v[188:191], v206 offset:3072
	ds_read_b128 v[196:199], v206 offset:4096
	ds_read_b128 v[200:203], v206 offset:5120
	ds_read_b128 v[208:211], v206 offset:6144
	ds_read_b128 v[212:215], v206 offset:7168
	global_load_lds_dwordx4 v[182:183], off
	s_add_i32 m0, s38, 0xe000
	v_lshl_add_u64 v[182:183], s[22:23], 0, v[176:177]
	global_load_lds_dwordx4 v[182:183], off
	s_waitcnt vmcnt(8) lgkmcnt(0)
	s_barrier
; #define PG8_STAGE(bufoff, gbase, voff) do { _Pragma("unroll") for (int _i = 0; _i < 2; ++_i) \
;         __builtin_amdgcn_global_load_lds((const unsigned*)((const char*)(gbase) + (voff)[_i]), (LAS unsigned*)(lds + (bufoff) + ldsw + _i * 8192), 16, 0, 0); } while (0)
; #define PG8_LDA(dst, b, h) do { _Pragma("unroll") for (int m = 0; m < 4; ++m) _Pragma("unroll") for (int k = 0; k < 2; ++k) dst[m][k] = *(const LAS bf16x8*)(lds + PG8_SA(b, h) + aoff + m * 2048 + k * 1024); } while (0)
; #define PG8_MMA(ai, bj, At, Bt) do { __builtin_amdgcn_s_setprio(1); _Pragma("unroll") for (int m = 0; m < 4; ++m) _Pragma("unroll") for (int n = 0; n < 2; ++n) _Pragma("unroll") for (int k = 0; k < 2; ++k) \
;         acc[ai][bj][m][n] = __builtin_amdgcn_mfma_f32_16x16x32_bf16(Bt[n][k], At[m][k], acc[ai][bj][m][n], 0, 0, 0); __builtin_amdgcn_s_setprio(0); } while (0)
; #define PG8_WAIT_V(n) asm volatile("s_waitcnt vmcnt(" #n ")" ::: "memory")
; #define PG8_WAIT_L(n) asm volatile("s_waitcnt lgkmcnt(" #n ")" ::: "memory")
; #define PG8_BAR __builtin_amdgcn_s_barrier()
; #define PG8_SCHED __builtin_amdgcn_sched_barrier(0)
; template <class Epi, class Sched>
; DI void gemm_phase(LAS unsigned char* lds, const int wv, const int lda, const int ldb, const Sched& S, const Epi& E) {
;     ...
;             PG8_WAIT_V(8); PG8_WAIT_L(0); PG8_BAR; PG8_MMA(0, 0, At, B0); PG8_MMA(0, 1, At, B1); PG8_BAR; PG8_SCHED;
;             PG8_LDA(At, 0, 1); PG8_STAGE(PG8_SB(0, 0), b2, voffB); PG8_STAGE(PG8_SB(0, 1), b2 + hstepB, voffB); PG8_STAGE(PG8_SA(0, 0), a2, voffA);
;             PG8_WAIT_V(8); PG8_WAIT_L(0); PG8_BAR; PG8_MMA(1, 0, At, B0); PG8_MMA(1, 1, At, B1); PG8_BAR; PG8_SCHED;
	v_mfma_f32_16x16x32_bf16 v[140:143], v[64:67], v[160:163], v[140:143]
	v_mfma_f32_16x16x32_bf16 v[136:139], v[104:107], v[160:163], v[136:139]
	v_mfma_f32_16x16x32_bf16 v[132:135], v[64:67], v[178:181], v[132:135]
	v_mfma_f32_16x16x32_bf16 v[128:131], v[104:107], v[178:181], v[128:131]
	v_mfma_f32_16x16x32_bf16 v[124:127], v[64:67], v[196:199], v[124:127]
	v_mfma_f32_16x16x32_bf16 v[120:123], v[104:107], v[196:199], v[120:123]
	v_mfma_f32_16x16x32_bf16 v[116:119], v[64:67], v[208:211], v[116:119]
	v_mfma_f32_16x16x32_bf16 v[112:115], v[104:107], v[208:211], v[112:115]
	v_mfma_f32_16x16x32_bf16 v[140:143], v[68:71], v[164:167], v[140:143]
	v_mfma_f32_16x16x32_bf16 v[136:139], v[108:111], v[164:167], v[136:139]
	v_mfma_f32_16x16x32_bf16 v[132:135], v[68:71], v[188:191], v[132:135]
	v_mfma_f32_16x16x32_bf16 v[128:131], v[108:111], v[188:191], v[128:131]
	v_mfma_f32_16x16x32_bf16 v[124:127], v[68:71], v[200:203], v[124:127]
	v_mfma_f32_16x16x32_bf16 v[120:123], v[108:111], v[200:203], v[120:123]
	v_mfma_f32_16x16x32_bf16 v[116:119], v[68:71], v[212:215], v[116:119]
	v_mfma_f32_16x16x32_bf16 v[112:115], v[108:111], v[212:215], v[112:115]
	v_mfma_f32_16x16x32_bf16 v[100:103], v[144:147], v[160:163], v[100:103]
	v_mfma_f32_16x16x32_bf16 v[96:99], v[152:155], v[160:163], v[96:99]
	v_mfma_f32_16x16x32_bf16 v[92:95], v[144:147], v[178:181], v[92:95]
	v_mfma_f32_16x16x32_bf16 v[88:91], v[152:155], v[178:181], v[88:91]
	v_mfma_f32_16x16x32_bf16 v[84:87], v[144:147], v[196:199], v[84:87]
	v_mfma_f32_16x16x32_bf16 v[80:83], v[152:155], v[196:199], v[80:83]
	v_mfma_f32_16x16x32_bf16 v[76:79], v[144:147], v[208:211], v[76:79]
	v_mfma_f32_16x16x32_bf16 v[72:75], v[152:155], v[208:211], v[72:75]
	v_mfma_f32_16x16x32_bf16 v[100:103], v[148:151], v[164:167], v[100:103]
	v_mfma_f32_16x16x32_bf16 v[96:99], v[156:159], v[164:167], v[96:99]
	v_mfma_f32_16x16x32_bf16 v[92:95], v[148:151], v[188:191], v[92:95]
	v_mfma_f32_16x16x32_bf16 v[88:91], v[156:159], v[188:191], v[88:91]
	v_mfma_f32_16x16x32_bf16 v[84:87], v[148:151], v[200:203], v[84:87]
	v_mfma_f32_16x16x32_bf16 v[80:83], v[156:159], v[200:203], v[80:83]
	v_mfma_f32_16x16x32_bf16 v[76:79], v[148:151], v[212:215], v[76:79]
	v_mfma_f32_16x16x32_bf16 v[72:75], v[156:159], v[212:215], v[72:75]
	s_barrier
	s_add_i32 s22, s50, s36
	v_lshl_add_u64 v[182:183], s[26:27], 0, v[184:185]
	s_mov_b32 m0, s22
	ds_read_b128 v[160:163], v206 offset:16384
	ds_read_b128 v[164:167], v206 offset:17408
	ds_read_b128 v[178:181], v206 offset:18432
	ds_read_b128 v[188:191], v206 offset:19456
	ds_read_b128 v[196:199], v206 offset:20480
	ds_read_b128 v[200:203], v206 offset:21504
	ds_read_b128 v[208:211], v206 offset:22528
	ds_read_b128 v[212:215], v206 offset:23552
	global_load_lds_dwordx4 v[182:183], off
	s_add_i32 m0, s22, 0x2000
	s_add_u32 s22, s26, 0x30000
	v_lshl_add_u64 v[216:217], s[26:27], 0, v[168:169]
	s_addc_u32 s23, s27, 0
	s_add_i32 s50, s51, s36
	global_load_lds_dwordx4 v[216:217], off
	v_lshl_add_u64 v[218:219], s[22:23], 0, v[184:185]
	s_mov_b32 m0, s50
	v_lshl_add_u64 v[220:221], s[30:31], 0, v[170:171]
	global_load_lds_dwordx4 v[218:219], off
	s_add_i32 m0, s50, 0x2000
	v_lshl_add_u64 v[218:219], s[22:23], 0, v[168:169]
	global_load_lds_dwordx4 v[218:219], off
	s_mov_b32 m0, s38
	v_lshl_add_u64 v[218:219], s[30:31], 0, v[172:173]
	global_load_lds_dwordx4 v[218:219], off
	s_mov_b32 m0, s39
	s_nop 0
	global_load_lds_dwordx4 v[220:221], off
	s_waitcnt vmcnt(8) lgkmcnt(0)
	s_barrier
	v_mfma_f32_16x16x32_bf16 v[60:63], v[64:67], v[160:163], v[60:63]
	v_mfma_f32_16x16x32_bf16 v[56:59], v[104:107], v[160:163], v[56:59]
	v_mfma_f32_16x16x32_bf16 v[52:55], v[64:67], v[178:181], v[52:55]
	v_mfma_f32_16x16x32_bf16 v[48:51], v[104:107], v[178:181], v[48:51]
	v_mfma_f32_16x16x32_bf16 v[44:47], v[64:67], v[196:199], v[44:47]
	v_mfma_f32_16x16x32_bf16 v[40:43], v[104:107], v[196:199], v[40:43]
	v_mfma_f32_16x16x32_bf16 v[36:39], v[64:67], v[208:211], v[36:39]
	v_mfma_f32_16x16x32_bf16 v[32:35], v[104:107], v[208:211], v[32:35]
	v_mfma_f32_16x16x32_bf16 v[60:63], v[68:71], v[164:167], v[60:63]
	v_mfma_f32_16x16x32_bf16 v[56:59], v[108:111], v[164:167], v[56:59]
	v_mfma_f32_16x16x32_bf16 v[52:55], v[68:71], v[188:191], v[52:55]
	v_mfma_f32_16x16x32_bf16 v[48:51], v[108:111], v[188:191], v[48:51]
	v_mfma_f32_16x16x32_bf16 v[44:47], v[68:71], v[200:203], v[44:47]
	v_mfma_f32_16x16x32_bf16 v[40:43], v[108:111], v[200:203], v[40:43]
	v_mfma_f32_16x16x32_bf16 v[36:39], v[68:71], v[212:215], v[36:39]
	v_mfma_f32_16x16x32_bf16 v[32:35], v[108:111], v[212:215], v[32:35]
	v_mfma_f32_16x16x32_bf16 v[28:31], v[144:147], v[160:163], v[28:31]
	v_mfma_f32_16x16x32_bf16 v[24:27], v[152:155], v[160:163], v[24:27]
	v_mfma_f32_16x16x32_bf16 v[20:23], v[144:147], v[178:181], v[20:23]
	v_mfma_f32_16x16x32_bf16 v[16:19], v[152:155], v[178:181], v[16:19]
	v_mfma_f32_16x16x32_bf16 v[12:15], v[144:147], v[196:199], v[12:15]
	v_mfma_f32_16x16x32_bf16 v[8:11], v[152:155], v[196:199], v[8:11]
	v_mfma_f32_16x16x32_bf16 v[4:7], v[144:147], v[208:211], v[4:7]
	v_mfma_f32_16x16x32_bf16 v[0:3], v[152:155], v[208:211], v[0:3]
	v_mfma_f32_16x16x32_bf16 v[28:31], v[148:151], v[164:167], v[28:31]
	v_mfma_f32_16x16x32_bf16 v[24:27], v[156:159], v[164:167], v[24:27]
	v_mfma_f32_16x16x32_bf16 v[20:23], v[148:151], v[188:191], v[20:23]
	v_mfma_f32_16x16x32_bf16 v[16:19], v[156:159], v[188:191], v[16:19]
	v_mfma_f32_16x16x32_bf16 v[12:15], v[148:151], v[200:203], v[12:15]
	v_mfma_f32_16x16x32_bf16 v[8:11], v[156:159], v[200:203], v[8:11]
	v_mfma_f32_16x16x32_bf16 v[4:7], v[148:151], v[212:215], v[4:7]
	v_mfma_f32_16x16x32_bf16 v[0:3], v[156:159], v[212:215], v[0:3]
	s_barrier
; #define PG8_STAGE(bufoff, gbase, voff) do { _Pragma("unroll") for (int _i = 0; _i < 2; ++_i) \
;         __builtin_amdgcn_global_load_lds((const unsigned*)((const char*)(gbase) + (voff)[_i]), (LAS unsigned*)(lds + (bufoff) + ldsw + _i * 8192), 16, 0, 0); } while (0)
; #define PG8_LDA(dst, b, h) do { _Pragma("unroll") for (int m = 0; m < 4; ++m) _Pragma("unroll") for (int k = 0; k < 2; ++k) dst[m][k] = *(const LAS bf16x8*)(lds + PG8_SA(b, h) + aoff + m * 2048 + k * 1024); } while (0)
; #define PG8_LDB(dst, b, h) do { _Pragma("unroll") for (int n = 0; n < 2; ++n) _Pragma("unroll") for (int k = 0; k < 2; ++k) dst[n][k] = *(const LAS bf16x8*)(lds + PG8_SB(b, h) + boff + n * 2048 + k * 1024); } while (0)
; #define PG8_MMA(ai, bj, At, Bt) do { __builtin_amdgcn_s_setprio(1); _Pragma("unroll") for (int m = 0; m < 4; ++m) _Pragma("unroll") for (int n = 0; n < 2; ++n) _Pragma("unroll") for (int k = 0; k < 2; ++k) \
;         acc[ai][bj][m][n] = __builtin_amdgcn_mfma_f32_16x16x32_bf16(Bt[n][k], At[m][k], acc[ai][bj][m][n], 0, 0, 0); __builtin_amdgcn_s_setprio(0); } while (0)
; #define PG8_WAIT_V(n) asm volatile("s_waitcnt vmcnt(" #n ")" ::: "memory")
; #define PG8_WAIT_L(n) asm volatile("s_waitcnt lgkmcnt(" #n ")" ::: "memory")
; #define PG8_BAR __builtin_amdgcn_s_barrier()
; #define PG8_SCHED __builtin_amdgcn_sched_barrier(0)
; template <class Epi, class Sched>
; DI void gemm_phase(LAS unsigned char* lds, const int wv, const int lda, const int ldb, const Sched& S, const Epi& E) {
;     ...
;             PG8_LDB(B0, 1, 0); PG8_LDB(B1, 1, 1); PG8_SCHED; PG8_LDA(At, 1, 0); PG8_STAGE(PG8_SA(0, 1), a2 + hstepA, voffA);
;             PG8_WAIT_V(8); PG8_WAIT_L(0); PG8_BAR; PG8_MMA(0, 0, At, B0); PG8_MMA(0, 1, At, B1); PG8_BAR; PG8_SCHED;
;             PG8_LDA(At, 1, 1); PG8_STAGE(PG8_SB(1, 0), b3, voffB); PG8_STAGE(PG8_SB(1, 1), b3 + hstepB, voffB); PG8_STAGE(PG8_SA(1, 0), a3, voffA);
;             PG8_WAIT_V(8); PG8_WAIT_L(0); PG8_BAR; PG8_MMA(1, 0, At, B0); PG8_MMA(1, 1, At, B1); PG8_BAR; PG8_SCHED;
;         }
;         if (wr == 0) PG8_BAR;
	s_add_i32 s50, 0, 0x18000
	s_add_i32 s51, 0, 0x1c000
	v_add_u32_e32 v108, s50, v204
	v_add_u32_e32 v156, s51, v204
	ds_read_b128 v[64:67], v108
	ds_read_b128 v[68:71], v108 offset:1024
	ds_read_b128 v[104:107], v108 offset:2048
	ds_read_b128 v[108:111], v108 offset:3072
	ds_read_b128 v[144:147], v156
	ds_read_b128 v[148:151], v156 offset:1024
	ds_read_b128 v[152:155], v156 offset:2048
	ds_read_b128 v[156:159], v156 offset:3072
	s_add_u32 s22, s30, 0x30000
	s_addc_u32 s23, s31, 0
	s_mov_b32 m0, s40
	v_lshl_add_u64 v[222:223], s[22:23], 0, v[172:173]
	ds_read_b128 v[160:163], v206 offset:32768
	ds_read_b128 v[164:167], v206 offset:33792
	ds_read_b128 v[178:181], v206 offset:34816
	ds_read_b128 v[188:191], v206 offset:35840
	ds_read_b128 v[196:199], v206 offset:36864
	ds_read_b128 v[200:203], v206 offset:37888
	ds_read_b128 v[208:211], v206 offset:38912
	ds_read_b128 v[212:215], v206 offset:39936
	global_load_lds_dwordx4 v[222:223], off
	s_mov_b32 m0, s41
	v_lshl_add_u64 v[222:223], s[22:23], 0, v[170:171]
	global_load_lds_dwordx4 v[222:223], off
	s_waitcnt vmcnt(8) lgkmcnt(0)
	s_barrier
	v_mfma_f32_16x16x32_bf16 v[140:143], v[64:67], v[160:163], v[140:143]
	v_mfma_f32_16x16x32_bf16 v[136:139], v[104:107], v[160:163], v[136:139]
	v_mfma_f32_16x16x32_bf16 v[132:135], v[64:67], v[178:181], v[132:135]
	v_mfma_f32_16x16x32_bf16 v[128:131], v[104:107], v[178:181], v[128:131]
	v_mfma_f32_16x16x32_bf16 v[124:127], v[64:67], v[196:199], v[124:127]
	v_mfma_f32_16x16x32_bf16 v[120:123], v[104:107], v[196:199], v[120:123]
	v_mfma_f32_16x16x32_bf16 v[116:119], v[64:67], v[208:211], v[116:119]
	v_mfma_f32_16x16x32_bf16 v[112:115], v[104:107], v[208:211], v[112:115]
	v_mfma_f32_16x16x32_bf16 v[140:143], v[68:71], v[164:167], v[140:143]
	v_mfma_f32_16x16x32_bf16 v[136:139], v[108:111], v[164:167], v[136:139]
	v_mfma_f32_16x16x32_bf16 v[132:135], v[68:71], v[188:191], v[132:135]
	v_mfma_f32_16x16x32_bf16 v[128:131], v[108:111], v[188:191], v[128:131]
	v_mfma_f32_16x16x32_bf16 v[124:127], v[68:71], v[200:203], v[124:127]
	v_mfma_f32_16x16x32_bf16 v[120:123], v[108:111], v[200:203], v[120:123]
	v_mfma_f32_16x16x32_bf16 v[116:119], v[68:71], v[212:215], v[116:119]
	v_mfma_f32_16x16x32_bf16 v[112:115], v[108:111], v[212:215], v[112:115]
	v_mfma_f32_16x16x32_bf16 v[100:103], v[144:147], v[160:163], v[100:103]
	v_mfma_f32_16x16x32_bf16 v[96:99], v[152:155], v[160:163], v[96:99]
	v_mfma_f32_16x16x32_bf16 v[92:95], v[144:147], v[178:181], v[92:95]
	v_mfma_f32_16x16x32_bf16 v[88:91], v[152:155], v[178:181], v[88:91]
	v_mfma_f32_16x16x32_bf16 v[84:87], v[144:147], v[196:199], v[84:87]
	v_mfma_f32_16x16x32_bf16 v[80:83], v[152:155], v[196:199], v[80:83]
	v_mfma_f32_16x16x32_bf16 v[76:79], v[144:147], v[208:211], v[76:79]
	v_mfma_f32_16x16x32_bf16 v[72:75], v[152:155], v[208:211], v[72:75]
	v_mfma_f32_16x16x32_bf16 v[100:103], v[148:151], v[164:167], v[100:103]
	v_mfma_f32_16x16x32_bf16 v[96:99], v[156:159], v[164:167], v[96:99]
	v_mfma_f32_16x16x32_bf16 v[92:95], v[148:151], v[188:191], v[92:95]
	v_mfma_f32_16x16x32_bf16 v[88:91], v[156:159], v[188:191], v[88:91]
	v_mfma_f32_16x16x32_bf16 v[84:87], v[148:151], v[200:203], v[84:87]
	v_mfma_f32_16x16x32_bf16 v[80:83], v[156:159], v[200:203], v[80:83]
	v_mfma_f32_16x16x32_bf16 v[76:79], v[148:151], v[212:215], v[76:79]
	v_mfma_f32_16x16x32_bf16 v[72:75], v[156:159], v[212:215], v[72:75]
	s_barrier
	s_add_i32 s22, s50, s36
	v_lshl_add_u64 v[182:183], v[182:183], 0, s[28:29]
	s_mov_b32 m0, s22
	ds_read_b128 v[160:163], v206 offset:49152
	ds_read_b128 v[164:167], v206 offset:50176
	ds_read_b128 v[178:181], v206 offset:51200
	ds_read_b128 v[188:191], v206 offset:52224
	ds_read_b128 v[196:199], v206 offset:53248
	ds_read_b128 v[200:203], v206 offset:54272
	ds_read_b128 v[208:211], v206 offset:55296
	ds_read_b128 v[212:215], v206 offset:56320
	global_load_lds_dwordx4 v[182:183], off
	s_add_i32 m0, s22, 0x2000
	s_add_u32 s22, s26, 0x30080
	v_lshl_add_u64 v[182:183], v[216:217], 0, s[28:29]
	s_addc_u32 s23, s27, 0
	s_add_i32 s26, s51, s36
	global_load_lds_dwordx4 v[182:183], off
	s_mov_b32 m0, s26
	v_lshl_add_u64 v[182:183], s[22:23], 0, v[184:185]
	global_load_lds_dwordx4 v[182:183], off
	s_add_i32 m0, s26, 0x2000
	v_lshl_add_u64 v[182:183], s[22:23], 0, v[168:169]
	global_load_lds_dwordx4 v[182:183], off
	s_mov_b32 m0, s20
	v_lshl_add_u64 v[182:183], v[218:219], 0, s[28:29]
	global_load_lds_dwordx4 v[182:183], off
	s_mov_b32 m0, s42
	v_lshl_add_u64 v[182:183], v[220:221], 0, s[28:29]
	global_load_lds_dwordx4 v[182:183], off
	s_waitcnt vmcnt(8) lgkmcnt(0)
	s_barrier
	v_mfma_f32_16x16x32_bf16 v[60:63], v[64:67], v[160:163], v[60:63]
	v_mfma_f32_16x16x32_bf16 v[56:59], v[104:107], v[160:163], v[56:59]
	v_mfma_f32_16x16x32_bf16 v[52:55], v[64:67], v[178:181], v[52:55]
	v_mfma_f32_16x16x32_bf16 v[48:51], v[104:107], v[178:181], v[48:51]
	v_mfma_f32_16x16x32_bf16 v[44:47], v[64:67], v[196:199], v[44:47]
	v_mfma_f32_16x16x32_bf16 v[40:43], v[104:107], v[196:199], v[40:43]
	v_mfma_f32_16x16x32_bf16 v[36:39], v[64:67], v[208:211], v[36:39]
	v_mfma_f32_16x16x32_bf16 v[32:35], v[104:107], v[208:211], v[32:35]
	v_mfma_f32_16x16x32_bf16 v[60:63], v[68:71], v[164:167], v[60:63]
	v_mfma_f32_16x16x32_bf16 v[56:59], v[108:111], v[164:167], v[56:59]
	v_mfma_f32_16x16x32_bf16 v[52:55], v[68:71], v[188:191], v[52:55]
	v_mfma_f32_16x16x32_bf16 v[48:51], v[108:111], v[188:191], v[48:51]
	v_mfma_f32_16x16x32_bf16 v[44:47], v[68:71], v[200:203], v[44:47]
	v_mfma_f32_16x16x32_bf16 v[40:43], v[108:111], v[200:203], v[40:43]
	v_mfma_f32_16x16x32_bf16 v[36:39], v[68:71], v[212:215], v[36:39]
	v_mfma_f32_16x16x32_bf16 v[32:35], v[108:111], v[212:215], v[32:35]
	v_mfma_f32_16x16x32_bf16 v[28:31], v[144:147], v[160:163], v[28:31]
	v_mfma_f32_16x16x32_bf16 v[24:27], v[152:155], v[160:163], v[24:27]
	v_mfma_f32_16x16x32_bf16 v[20:23], v[144:147], v[178:181], v[20:23]
	v_mfma_f32_16x16x32_bf16 v[16:19], v[152:155], v[178:181], v[16:19]
	v_mfma_f32_16x16x32_bf16 v[12:15], v[144:147], v[196:199], v[12:15]
	v_mfma_f32_16x16x32_bf16 v[8:11], v[152:155], v[196:199], v[8:11]
	v_mfma_f32_16x16x32_bf16 v[4:7], v[144:147], v[208:211], v[4:7]
	v_mfma_f32_16x16x32_bf16 v[0:3], v[152:155], v[208:211], v[0:3]
	v_mfma_f32_16x16x32_bf16 v[28:31], v[148:151], v[164:167], v[28:31]
	v_mfma_f32_16x16x32_bf16 v[24:27], v[156:159], v[164:167], v[24:27]
	v_mfma_f32_16x16x32_bf16 v[20:23], v[148:151], v[188:191], v[20:23]
	v_mfma_f32_16x16x32_bf16 v[16:19], v[156:159], v[188:191], v[16:19]
	v_mfma_f32_16x16x32_bf16 v[12:15], v[148:151], v[200:203], v[12:15]
	v_mfma_f32_16x16x32_bf16 v[8:11], v[156:159], v[200:203], v[8:11]
	v_mfma_f32_16x16x32_bf16 v[4:7], v[148:151], v[212:215], v[4:7]
	v_mfma_f32_16x16x32_bf16 v[0:3], v[156:159], v[212:215], v[0:3]
	s_barrier
	s_add_i32 s49, s49, 2
	s_add_u32 s0, s0, 0x100
	s_addc_u32 s1, s1, 0
	s_cmp_gt_u32 s49, 9
	s_mov_b64 s[22:23], s[24:25]
	s_cbranch_scc0 .LBB0_1099
	s_and_b64 vcc, exec, s[14:15]
	s_cbranch_vccz .LBB0_1102
	s_barrier

; #define PG8_STAGE(bufoff, gbase, voff) do { _Pragma("unroll") for (int _i = 0; _i < 2; ++_i) \
;         __builtin_amdgcn_global_load_lds((const unsigned*)((const char*)(gbase) + (voff)[_i]), (LAS unsigned*)(lds + (bufoff) + ldsw + _i * 8192), 16, 0, 0); } while (0)
; #define PG8_LDA(dst, b, h) do { _Pragma("unroll") for (int m = 0; m < 4; ++m) _Pragma("unroll") for (int k = 0; k < 2; ++k) dst[m][k] = *(const LAS bf16x8*)(lds + PG8_SA(b, h) + aoff + m * 2048 + k * 1024); } while (0)
; #define PG8_LDB(dst, b, h) do { _Pragma("unroll") for (int n = 0; n < 2; ++n) _Pragma("unroll") for (int k = 0; k < 2; ++k) dst[n][k] = *(const LAS bf16x8*)(lds + PG8_SB(b, h) + boff + n * 2048 + k * 1024); } while (0)
; #define PG8_MMA(ai, bj, At, Bt) do { __builtin_amdgcn_s_setprio(1); _Pragma("unroll") for (int m = 0; m < 4; ++m) _Pragma("unroll") for (int n = 0; n < 2; ++n) _Pragma("unroll") for (int k = 0; k < 2; ++k) \
;         acc[ai][bj][m][n] = __builtin_amdgcn_mfma_f32_16x16x32_bf16(Bt[n][k], At[m][k], acc[ai][bj][m][n], 0, 0, 0); __builtin_amdgcn_s_setprio(0); } while (0)
; #define PG8_WAIT_V(n) asm volatile("s_waitcnt vmcnt(" #n ")" ::: "memory")
; #define PG8_WAIT_L(n) asm volatile("s_waitcnt lgkmcnt(" #n ")" ::: "memory")
; #define PG8_BAR __builtin_amdgcn_s_barrier()
; #define PG8_SCHED __builtin_amdgcn_sched_barrier(0)
; template <class Epi, class Sched>
; DI void gemm_phase(LAS unsigned char* lds, const int wv, const int lda, const int ldb, const Sched& S, const Epi& E) {
;     ...
;         for (int t = 0; t < nt; t += 2) {
;             const bool last = (t == nt - 2);
;             const char* a1 = cA + (size_t)(t + 1) * kstep;
;             const char* a2 = last ? nA : cA + (size_t)(t + 2) * kstep; const char* b2 = last ? nB : cB + (size_t)(t + 2) * kstep;
;             const char* a3 = a2 + kstep; const char* b3 = b2 + kstep;
;             PG8_LDB(B0, 0, 0); PG8_LDB(B1, 0, 1); PG8_SCHED; PG8_LDA(At, 0, 0); PG8_STAGE(PG8_SA(1, 1), a1 + hstepA, voffA);
;             PG8_WAIT_V(8); PG8_WAIT_L(0); PG8_BAR; PG8_MMA(0, 0, At, B0); PG8_MMA(0, 1, At, B1); PG8_BAR; PG8_SCHED;
;             PG8_LDA(At, 0, 1); PG8_STAGE(PG8_SB(0, 0), b2, voffB); PG8_STAGE(PG8_SB(0, 1), b2 + hstepB, voffB); PG8_STAGE(PG8_SA(0, 0), a2, voffA);
;             PG8_WAIT_V(8); PG8_WAIT_L(0); PG8_BAR; PG8_MMA(1, 0, At, B0); PG8_MMA(1, 1, At, B1); PG8_BAR; PG8_SCHED;
.LBB0_1185:
	s_add_i32 s31, s19, 2
	s_add_u32 s34, s6, 0xfff80080
	s_addc_u32 s35, s7, -1
	s_add_i32 s40, 0, 0x10000
	s_cmp_eq_u32 s0, s19
	s_cselect_b32 s37, s23, s35
	s_cselect_b32 s36, s22, s34
	s_cselect_b32 s35, s25, s15
	s_cselect_b32 s34, s24, s1
	s_add_i32 s19, 0, 0x14000
	v_add_u32_e32 v140, s40, v233
	v_add_u32_e32 v156, s19, v233
	ds_read_b128 v[128:131], v140
	ds_read_b128 v[132:135], v140 offset:1024
	ds_read_b128 v[136:139], v140 offset:2048
	ds_read_b128 v[140:143], v140 offset:3072
	ds_read_b128 v[144:147], v156
	ds_read_b128 v[148:151], v156 offset:1024
	ds_read_b128 v[152:155], v156 offset:2048
	ds_read_b128 v[156:159], v156 offset:3072
	v_lshl_add_u64 v[210:211], s[6:7], 0, v[206:207]
	s_add_i32 m0, s45, 0xc000
	ds_read_b128 v[160:163], v235
	ds_read_b128 v[164:167], v235 offset:1024
	ds_read_b128 v[168:171], v235 offset:2048
	ds_read_b128 v[172:175], v235 offset:3072
	ds_read_b128 v[176:179], v235 offset:4096
	ds_read_b128 v[180:183], v235 offset:5120
	ds_read_b128 v[188:191], v235 offset:6144
	ds_read_b128 v[196:199], v235 offset:7168
	global_load_lds_dwordx4 v[210:211], off
	s_add_i32 m0, s45, 0xe000
	v_lshl_add_u64 v[210:211], s[6:7], 0, v[208:209]
	global_load_lds_dwordx4 v[210:211], off
	s_waitcnt vmcnt(8) lgkmcnt(0)
	s_barrier
	v_mfma_f32_16x16x32_bf16 v[124:127], v[128:131], v[160:163], v[124:127]
	v_mfma_f32_16x16x32_bf16 v[120:123], v[136:139], v[160:163], v[120:123]
	v_mfma_f32_16x16x32_bf16 v[116:119], v[128:131], v[168:171], v[116:119]
	v_mfma_f32_16x16x32_bf16 v[112:115], v[136:139], v[168:171], v[112:115]
	v_mfma_f32_16x16x32_bf16 v[108:111], v[128:131], v[176:179], v[108:111]
	v_mfma_f32_16x16x32_bf16 v[104:107], v[136:139], v[176:179], v[104:107]
	v_mfma_f32_16x16x32_bf16 v[100:103], v[128:131], v[188:191], v[100:103]
	v_mfma_f32_16x16x32_bf16 v[96:99], v[136:139], v[188:191], v[96:99]
	v_mfma_f32_16x16x32_bf16 v[124:127], v[132:135], v[164:167], v[124:127]
	v_mfma_f32_16x16x32_bf16 v[120:123], v[140:143], v[164:167], v[120:123]
	v_mfma_f32_16x16x32_bf16 v[116:119], v[132:135], v[172:175], v[116:119]
	v_mfma_f32_16x16x32_bf16 v[112:115], v[140:143], v[172:175], v[112:115]
	v_mfma_f32_16x16x32_bf16 v[108:111], v[132:135], v[180:183], v[108:111]
	v_mfma_f32_16x16x32_bf16 v[104:107], v[140:143], v[180:183], v[104:107]
	v_mfma_f32_16x16x32_bf16 v[100:103], v[132:135], v[196:199], v[100:103]
	v_mfma_f32_16x16x32_bf16 v[96:99], v[140:143], v[196:199], v[96:99]
	v_mfma_f32_16x16x32_bf16 v[92:95], v[144:147], v[160:163], v[92:95]
	v_mfma_f32_16x16x32_bf16 v[88:91], v[152:155], v[160:163], v[88:91]
	v_mfma_f32_16x16x32_bf16 v[84:87], v[144:147], v[168:171], v[84:87]
	v_mfma_f32_16x16x32_bf16 v[80:83], v[152:155], v[168:171], v[80:83]
	v_mfma_f32_16x16x32_bf16 v[76:79], v[144:147], v[176:179], v[76:79]
	v_mfma_f32_16x16x32_bf16 v[72:75], v[152:155], v[176:179], v[72:75]
	v_mfma_f32_16x16x32_bf16 v[68:71], v[144:147], v[188:191], v[68:71]
	v_mfma_f32_16x16x32_bf16 v[64:67], v[152:155], v[188:191], v[64:67]
	v_mfma_f32_16x16x32_bf16 v[92:95], v[148:151], v[164:167], v[92:95]
	v_mfma_f32_16x16x32_bf16 v[88:91], v[156:159], v[164:167], v[88:91]
	v_mfma_f32_16x16x32_bf16 v[84:87], v[148:151], v[172:175], v[84:87]
	v_mfma_f32_16x16x32_bf16 v[80:83], v[156:159], v[172:175], v[80:83]
	v_mfma_f32_16x16x32_bf16 v[76:79], v[148:151], v[180:183], v[76:79]
	v_mfma_f32_16x16x32_bf16 v[72:75], v[156:159], v[180:183], v[72:75]
	v_mfma_f32_16x16x32_bf16 v[68:71], v[148:151], v[196:199], v[68:71]
	v_mfma_f32_16x16x32_bf16 v[64:67], v[156:159], v[196:199], v[64:67]
	s_barrier
	s_add_i32 s40, s40, s44
	v_lshl_add_u64 v[210:211], s[34:35], 0, v[184:185]
	s_mov_b32 m0, s40
	ds_read_b128 v[160:163], v235 offset:16384
	ds_read_b128 v[164:167], v235 offset:17408
	ds_read_b128 v[168:171], v235 offset:18432
	ds_read_b128 v[172:175], v235 offset:19456
	ds_read_b128 v[176:179], v235 offset:20480
	ds_read_b128 v[180:183], v235 offset:21504
	ds_read_b128 v[188:191], v235 offset:22528
	ds_read_b128 v[196:199], v235 offset:23552
	global_load_lds_dwordx4 v[210:211], off
	s_add_i32 m0, s40, 0x2000
	s_add_u32 s40, s34, 0x80000
	v_lshl_add_u64 v[212:213], s[34:35], 0, v[204:205]
	s_addc_u32 s41, s35, 0
	s_add_i32 s19, s19, s44
	global_load_lds_dwordx4 v[212:213], off
	v_lshl_add_u64 v[214:215], s[40:41], 0, v[184:185]
	s_mov_b32 m0, s19
	v_lshl_add_u64 v[216:217], s[36:37], 0, v[202:203]
	global_load_lds_dwordx4 v[214:215], off
	s_add_i32 m0, s19, 0x2000
	v_lshl_add_u64 v[214:215], s[40:41], 0, v[204:205]
	global_load_lds_dwordx4 v[214:215], off
	s_mov_b32 m0, s45
	v_lshl_add_u64 v[214:215], s[36:37], 0, v[200:201]
	global_load_lds_dwordx4 v[214:215], off
	s_mov_b32 m0, s46
	s_nop 0
	global_load_lds_dwordx4 v[216:217], off
	s_waitcnt vmcnt(8) lgkmcnt(0)
	s_barrier
; #define PG8_STAGE(bufoff, gbase, voff) do { _Pragma("unroll") for (int _i = 0; _i < 2; ++_i) \
;         __builtin_amdgcn_global_load_lds((const unsigned*)((const char*)(gbase) + (voff)[_i]), (LAS unsigned*)(lds + (bufoff) + ldsw + _i * 8192), 16, 0, 0); } while (0)
; #define PG8_LDA(dst, b, h) do { _Pragma("unroll") for (int m = 0; m < 4; ++m) _Pragma("unroll") for (int k = 0; k < 2; ++k) dst[m][k] = *(const LAS bf16x8*)(lds + PG8_SA(b, h) + aoff + m * 2048 + k * 1024); } while (0)
; #define PG8_LDB(dst, b, h) do { _Pragma("unroll") for (int n = 0; n < 2; ++n) _Pragma("unroll") for (int k = 0; k < 2; ++k) dst[n][k] = *(const LAS bf16x8*)(lds + PG8_SB(b, h) + boff + n * 2048 + k * 1024); } while (0)
; #define PG8_MMA(ai, bj, At, Bt) do { __builtin_amdgcn_s_setprio(1); _Pragma("unroll") for (int m = 0; m < 4; ++m) _Pragma("unroll") for (int n = 0; n < 2; ++n) _Pragma("unroll") for (int k = 0; k < 2; ++k) \
;         acc[ai][bj][m][n] = __builtin_amdgcn_mfma_f32_16x16x32_bf16(Bt[n][k], At[m][k], acc[ai][bj][m][n], 0, 0, 0); __builtin_amdgcn_s_setprio(0); } while (0)
; #define PG8_WAIT_V(n) asm volatile("s_waitcnt vmcnt(" #n ")" ::: "memory")
; #define PG8_WAIT_L(n) asm volatile("s_waitcnt lgkmcnt(" #n ")" ::: "memory")
; #define PG8_BAR __builtin_amdgcn_s_barrier()
; #define PG8_SCHED __builtin_amdgcn_sched_barrier(0)
; template <class Epi, class Sched>
; DI void gemm_phase(LAS unsigned char* lds, const int wv, const int lda, const int ldb, const Sched& S, const Epi& E) {
;     ...
;             PG8_WAIT_V(8); PG8_WAIT_L(0); PG8_BAR; PG8_MMA(1, 0, At, B0); PG8_MMA(1, 1, At, B1); PG8_BAR; PG8_SCHED;
;             PG8_LDB(B0, 1, 0); PG8_LDB(B1, 1, 1); PG8_SCHED; PG8_LDA(At, 1, 0); PG8_STAGE(PG8_SA(0, 1), a2 + hstepA, voffA);
;             PG8_WAIT_V(8); PG8_WAIT_L(0); PG8_BAR; PG8_MMA(0, 0, At, B0); PG8_MMA(0, 1, At, B1); PG8_BAR; PG8_SCHED;
	v_mfma_f32_16x16x32_bf16 v[60:63], v[128:131], v[160:163], v[60:63]
	v_mfma_f32_16x16x32_bf16 v[56:59], v[136:139], v[160:163], v[56:59]
	v_mfma_f32_16x16x32_bf16 v[52:55], v[128:131], v[168:171], v[52:55]
	v_mfma_f32_16x16x32_bf16 v[48:51], v[136:139], v[168:171], v[48:51]
	v_mfma_f32_16x16x32_bf16 v[44:47], v[128:131], v[176:179], v[44:47]
	v_mfma_f32_16x16x32_bf16 v[40:43], v[136:139], v[176:179], v[40:43]
	v_mfma_f32_16x16x32_bf16 v[36:39], v[128:131], v[188:191], v[36:39]
	v_mfma_f32_16x16x32_bf16 v[32:35], v[136:139], v[188:191], v[32:35]
	v_mfma_f32_16x16x32_bf16 v[60:63], v[132:135], v[164:167], v[60:63]
	v_mfma_f32_16x16x32_bf16 v[56:59], v[140:143], v[164:167], v[56:59]
	v_mfma_f32_16x16x32_bf16 v[52:55], v[132:135], v[172:175], v[52:55]
	v_mfma_f32_16x16x32_bf16 v[48:51], v[140:143], v[172:175], v[48:51]
	v_mfma_f32_16x16x32_bf16 v[44:47], v[132:135], v[180:183], v[44:47]
	v_mfma_f32_16x16x32_bf16 v[40:43], v[140:143], v[180:183], v[40:43]
	v_mfma_f32_16x16x32_bf16 v[36:39], v[132:135], v[196:199], v[36:39]
	v_mfma_f32_16x16x32_bf16 v[32:35], v[140:143], v[196:199], v[32:35]
	v_mfma_f32_16x16x32_bf16 v[28:31], v[144:147], v[160:163], v[28:31]
	v_mfma_f32_16x16x32_bf16 v[24:27], v[152:155], v[160:163], v[24:27]
	v_mfma_f32_16x16x32_bf16 v[20:23], v[144:147], v[168:171], v[20:23]
	v_mfma_f32_16x16x32_bf16 v[16:19], v[152:155], v[168:171], v[16:19]
	v_mfma_f32_16x16x32_bf16 v[12:15], v[144:147], v[176:179], v[12:15]
	v_mfma_f32_16x16x32_bf16 v[8:11], v[152:155], v[176:179], v[8:11]
	v_mfma_f32_16x16x32_bf16 v[4:7], v[144:147], v[188:191], v[4:7]
	v_mfma_f32_16x16x32_bf16 v[0:3], v[152:155], v[188:191], v[0:3]
	v_mfma_f32_16x16x32_bf16 v[28:31], v[148:151], v[164:167], v[28:31]
	v_mfma_f32_16x16x32_bf16 v[24:27], v[156:159], v[164:167], v[24:27]
	v_mfma_f32_16x16x32_bf16 v[20:23], v[148:151], v[172:175], v[20:23]
	v_mfma_f32_16x16x32_bf16 v[16:19], v[156:159], v[172:175], v[16:19]
	v_mfma_f32_16x16x32_bf16 v[12:15], v[148:151], v[180:183], v[12:15]
	v_mfma_f32_16x16x32_bf16 v[8:11], v[156:159], v[180:183], v[8:11]
	v_mfma_f32_16x16x32_bf16 v[4:7], v[148:151], v[196:199], v[4:7]
	v_mfma_f32_16x16x32_bf16 v[0:3], v[156:159], v[196:199], v[0:3]
	s_barrier
	s_add_i32 s19, 0, 0x18000
	s_add_i32 s40, 0, 0x1c000
	v_add_u32_e32 v140, s19, v233
	v_add_u32_e32 v156, s40, v233
	ds_read_b128 v[128:131], v140
	ds_read_b128 v[132:135], v140 offset:1024
	ds_read_b128 v[136:139], v140 offset:2048
	ds_read_b128 v[140:143], v140 offset:3072
	ds_read_b128 v[144:147], v156
	ds_read_b128 v[148:151], v156 offset:1024
	ds_read_b128 v[152:155], v156 offset:2048
	ds_read_b128 v[156:159], v156 offset:3072
	s_add_u32 s36, s36, 0x80000
	s_addc_u32 s37, s37, 0
	s_mov_b32 m0, s47
	v_lshl_add_u64 v[218:219], s[36:37], 0, v[200:201]
	ds_read_b128 v[160:163], v235 offset:32768
	ds_read_b128 v[164:167], v235 offset:33792
	ds_read_b128 v[168:171], v235 offset:34816
	ds_read_b128 v[172:175], v235 offset:35840
	ds_read_b128 v[176:179], v235 offset:36864
	ds_read_b128 v[180:183], v235 offset:37888
	ds_read_b128 v[188:191], v235 offset:38912
	ds_read_b128 v[196:199], v235 offset:39936
	global_load_lds_dwordx4 v[218:219], off
	s_mov_b32 m0, s48
	v_lshl_add_u64 v[218:219], s[36:37], 0, v[202:203]
	global_load_lds_dwordx4 v[218:219], off
	s_waitcnt vmcnt(8) lgkmcnt(0)
	s_barrier
	v_mfma_f32_16x16x32_bf16 v[124:127], v[128:131], v[160:163], v[124:127]
	v_mfma_f32_16x16x32_bf16 v[120:123], v[136:139], v[160:163], v[120:123]
	v_mfma_f32_16x16x32_bf16 v[116:119], v[128:131], v[168:171], v[116:119]
	v_mfma_f32_16x16x32_bf16 v[112:115], v[136:139], v[168:171], v[112:115]
	v_mfma_f32_16x16x32_bf16 v[108:111], v[128:131], v[176:179], v[108:111]
	v_mfma_f32_16x16x32_bf16 v[104:107], v[136:139], v[176:179], v[104:107]
	v_mfma_f32_16x16x32_bf16 v[100:103], v[128:131], v[188:191], v[100:103]
	v_mfma_f32_16x16x32_bf16 v[96:99], v[136:139], v[188:191], v[96:99]
	v_mfma_f32_16x16x32_bf16 v[124:127], v[132:135], v[164:167], v[124:127]
	v_mfma_f32_16x16x32_bf16 v[120:123], v[140:143], v[164:167], v[120:123]
	v_mfma_f32_16x16x32_bf16 v[116:119], v[132:135], v[172:175], v[116:119]
	v_mfma_f32_16x16x32_bf16 v[112:115], v[140:143], v[172:175], v[112:115]
	v_mfma_f32_16x16x32_bf16 v[108:111], v[132:135], v[180:183], v[108:111]
	v_mfma_f32_16x16x32_bf16 v[104:107], v[140:143], v[180:183], v[104:107]
	v_mfma_f32_16x16x32_bf16 v[100:103], v[132:135], v[196:199], v[100:103]
	v_mfma_f32_16x16x32_bf16 v[96:99], v[140:143], v[196:199], v[96:99]
	v_mfma_f32_16x16x32_bf16 v[92:95], v[144:147], v[160:163], v[92:95]
	v_mfma_f32_16x16x32_bf16 v[88:91], v[152:155], v[160:163], v[88:91]
	v_mfma_f32_16x16x32_bf16 v[84:87], v[144:147], v[168:171], v[84:87]
	v_mfma_f32_16x16x32_bf16 v[80:83], v[152:155], v[168:171], v[80:83]
	v_mfma_f32_16x16x32_bf16 v[76:79], v[144:147], v[176:179], v[76:79]
	v_mfma_f32_16x16x32_bf16 v[72:75], v[152:155], v[176:179], v[72:75]
	v_mfma_f32_16x16x32_bf16 v[68:71], v[144:147], v[188:191], v[68:71]
	v_mfma_f32_16x16x32_bf16 v[64:67], v[152:155], v[188:191], v[64:67]
	v_mfma_f32_16x16x32_bf16 v[92:95], v[148:151], v[164:167], v[92:95]
	v_mfma_f32_16x16x32_bf16 v[88:91], v[156:159], v[164:167], v[88:91]
	v_mfma_f32_16x16x32_bf16 v[84:87], v[148:151], v[172:175], v[84:87]
	v_mfma_f32_16x16x32_bf16 v[80:83], v[156:159], v[172:175], v[80:83]
	v_mfma_f32_16x16x32_bf16 v[76:79], v[148:151], v[180:183], v[76:79]
	v_mfma_f32_16x16x32_bf16 v[72:75], v[156:159], v[180:183], v[72:75]
	v_mfma_f32_16x16x32_bf16 v[68:71], v[148:151], v[196:199], v[68:71]
	v_mfma_f32_16x16x32_bf16 v[64:67], v[156:159], v[196:199], v[64:67]
	s_barrier
; #define PG8_STAGE(bufoff, gbase, voff) do { _Pragma("unroll") for (int _i = 0; _i < 2; ++_i) \
;         __builtin_amdgcn_global_load_lds((const unsigned*)((const char*)(gbase) + (voff)[_i]), (LAS unsigned*)(lds + (bufoff) + ldsw + _i * 8192), 16, 0, 0); } while (0)
; #define PG8_LDA(dst, b, h) do { _Pragma("unroll") for (int m = 0; m < 4; ++m) _Pragma("unroll") for (int k = 0; k < 2; ++k) dst[m][k] = *(const LAS bf16x8*)(lds + PG8_SA(b, h) + aoff + m * 2048 + k * 1024); } while (0)
; #define PG8_MMA(ai, bj, At, Bt) do { __builtin_amdgcn_s_setprio(1); _Pragma("unroll") for (int m = 0; m < 4; ++m) _Pragma("unroll") for (int n = 0; n < 2; ++n) _Pragma("unroll") for (int k = 0; k < 2; ++k) \
;         acc[ai][bj][m][n] = __builtin_amdgcn_mfma_f32_16x16x32_bf16(Bt[n][k], At[m][k], acc[ai][bj][m][n], 0, 0, 0); __builtin_amdgcn_s_setprio(0); } while (0)
; #define PG8_WAIT_V(n) asm volatile("s_waitcnt vmcnt(" #n ")" ::: "memory")
; #define PG8_WAIT_L(n) asm volatile("s_waitcnt lgkmcnt(" #n ")" ::: "memory")
; #define PG8_BAR __builtin_amdgcn_s_barrier()
; #define PG8_SCHED __builtin_amdgcn_sched_barrier(0)
; template <class Epi, class Sched>
; DI void gemm_phase(LAS unsigned char* lds, const int wv, const int lda, const int ldb, const Sched& S, const Epi& E) {
;     ...
;             PG8_LDA(At, 1, 1); PG8_STAGE(PG8_SB(1, 0), b3, voffB); PG8_STAGE(PG8_SB(1, 1), b3 + hstepB, voffB); PG8_STAGE(PG8_SA(1, 0), a3, voffA);
;             PG8_WAIT_V(8); PG8_WAIT_L(0); PG8_BAR; PG8_MMA(1, 0, At, B0); PG8_MMA(1, 1, At, B1); PG8_BAR; PG8_SCHED;
;         }
;         if (wr == 0) PG8_BAR;
	s_add_i32 s19, s19, s44
	v_lshl_add_u64 v[210:211], v[210:211], 0, s[28:29]
	s_mov_b32 m0, s19
	ds_read_b128 v[160:163], v235 offset:49152
	ds_read_b128 v[164:167], v235 offset:50176
	ds_read_b128 v[168:171], v235 offset:51200
	ds_read_b128 v[172:175], v235 offset:52224
	ds_read_b128 v[176:179], v235 offset:53248
	ds_read_b128 v[180:183], v235 offset:54272
	ds_read_b128 v[188:191], v235 offset:55296
	ds_read_b128 v[196:199], v235 offset:56320
	global_load_lds_dwordx4 v[210:211], off
	s_add_i32 m0, s19, 0x2000
	s_add_u32 s34, s34, 0x80080
	v_lshl_add_u64 v[210:211], v[212:213], 0, s[28:29]
	s_addc_u32 s35, s35, 0
	s_add_i32 s19, s40, s44
	global_load_lds_dwordx4 v[210:211], off
	s_mov_b32 m0, s19
	v_lshl_add_u64 v[210:211], s[34:35], 0, v[184:185]
	global_load_lds_dwordx4 v[210:211], off
	s_add_i32 m0, s19, 0x2000
	v_lshl_add_u64 v[210:211], s[34:35], 0, v[204:205]
	global_load_lds_dwordx4 v[210:211], off
	s_mov_b32 m0, s49
	v_lshl_add_u64 v[210:211], v[214:215], 0, s[28:29]
	global_load_lds_dwordx4 v[210:211], off
	s_mov_b32 m0, s50
	v_lshl_add_u64 v[210:211], v[216:217], 0, s[28:29]
	global_load_lds_dwordx4 v[210:211], off
	s_waitcnt vmcnt(8) lgkmcnt(0)
	s_barrier
	v_mfma_f32_16x16x32_bf16 v[60:63], v[128:131], v[160:163], v[60:63]
	v_mfma_f32_16x16x32_bf16 v[56:59], v[136:139], v[160:163], v[56:59]
	v_mfma_f32_16x16x32_bf16 v[52:55], v[128:131], v[168:171], v[52:55]
	v_mfma_f32_16x16x32_bf16 v[48:51], v[136:139], v[168:171], v[48:51]
	v_mfma_f32_16x16x32_bf16 v[44:47], v[128:131], v[176:179], v[44:47]
	v_mfma_f32_16x16x32_bf16 v[40:43], v[136:139], v[176:179], v[40:43]
	v_mfma_f32_16x16x32_bf16 v[36:39], v[128:131], v[188:191], v[36:39]
	v_mfma_f32_16x16x32_bf16 v[32:35], v[136:139], v[188:191], v[32:35]
	v_mfma_f32_16x16x32_bf16 v[60:63], v[132:135], v[164:167], v[60:63]
	v_mfma_f32_16x16x32_bf16 v[56:59], v[140:143], v[164:167], v[56:59]
	v_mfma_f32_16x16x32_bf16 v[52:55], v[132:135], v[172:175], v[52:55]
	v_mfma_f32_16x16x32_bf16 v[48:51], v[140:143], v[172:175], v[48:51]
	v_mfma_f32_16x16x32_bf16 v[44:47], v[132:135], v[180:183], v[44:47]
	v_mfma_f32_16x16x32_bf16 v[40:43], v[140:143], v[180:183], v[40:43]
	v_mfma_f32_16x16x32_bf16 v[36:39], v[132:135], v[196:199], v[36:39]
	v_mfma_f32_16x16x32_bf16 v[32:35], v[140:143], v[196:199], v[32:35]
	v_mfma_f32_16x16x32_bf16 v[28:31], v[144:147], v[160:163], v[28:31]
	v_mfma_f32_16x16x32_bf16 v[24:27], v[152:155], v[160:163], v[24:27]
	v_mfma_f32_16x16x32_bf16 v[20:23], v[144:147], v[168:171], v[20:23]
	v_mfma_f32_16x16x32_bf16 v[16:19], v[152:155], v[168:171], v[16:19]
	v_mfma_f32_16x16x32_bf16 v[12:15], v[144:147], v[176:179], v[12:15]
	v_mfma_f32_16x16x32_bf16 v[8:11], v[152:155], v[176:179], v[8:11]
	v_mfma_f32_16x16x32_bf16 v[4:7], v[144:147], v[188:191], v[4:7]
	v_mfma_f32_16x16x32_bf16 v[0:3], v[152:155], v[188:191], v[0:3]
	v_mfma_f32_16x16x32_bf16 v[28:31], v[148:151], v[164:167], v[28:31]
	v_mfma_f32_16x16x32_bf16 v[24:27], v[156:159], v[164:167], v[24:27]
	v_mfma_f32_16x16x32_bf16 v[20:23], v[148:151], v[172:175], v[20:23]
	v_mfma_f32_16x16x32_bf16 v[16:19], v[156:159], v[172:175], v[16:19]
	v_mfma_f32_16x16x32_bf16 v[12:15], v[148:151], v[180:183], v[12:15]
	v_mfma_f32_16x16x32_bf16 v[8:11], v[156:159], v[180:183], v[8:11]
	v_mfma_f32_16x16x32_bf16 v[4:7], v[148:151], v[196:199], v[4:7]
	v_mfma_f32_16x16x32_bf16 v[0:3], v[156:159], v[196:199], v[0:3]
	s_barrier
	s_add_u32 s6, s6, 0x100
	s_addc_u32 s7, s7, 0
	s_add_u32 s1, s1, 0x100
	s_addc_u32 s15, s15, 0
	s_cmp_ge_u32 s31, s27
	s_mov_b32 s19, s31
	s_cbranch_scc0 .LBB0_1185
	s_and_b64 vcc, exec, s[12:13]
	s_cbranch_vccz .LBB0_1188
	s_barrier

;     DI bool next(int i, Unit& u) const { const long L = (long)i * G + c; if (L >= T.nwg) return false; T.map((int)L, u.pm, u.pn); u.seg = 0; return true; }
;     DI bool next(int i, Unit& u) const { const int ti = i / 3; const long L = (long)ti * G + c; if (L >= T.nwg) return false; T.map((int)L, u.pm, u.pn); u.seg = i - 3 * ti; return true; }
;     DI const char* aptr(const Unit& u) const { return A + (size_t)u.pm * ta + (size_t)kofs(u.seg) * 2; }
;     DI const char* bptr(const Unit& u) const { return B + (size_t)u.pn * tb + (size_t)kofs(u.seg) * 2; }
; #define PG8_STAGE(bufoff, gbase, voff) do { _Pragma("unroll") for (int _i = 0; _i < 2; ++_i) \
;         __builtin_amdgcn_global_load_lds((const unsigned*)((const char*)(gbase) + (voff)[_i]), (LAS unsigned*)(lds + (bufoff) + ldsw + _i * 8192), 16, 0, 0); } while (0)
; #define PG8_LDA(dst, b, h) do { _Pragma("unroll") for (int m = 0; m < 4; ++m) _Pragma("unroll") for (int k = 0; k < 2; ++k) dst[m][k] = *(const LAS bf16x8*)(lds + PG8_SA(b, h) + aoff + m * 2048 + k * 1024); } while (0)
; #define PG8_WAIT_V(n) asm volatile("s_waitcnt vmcnt(" #n ")" ::: "memory")
; #define PG8_WAIT_L(n) asm volatile("s_waitcnt lgkmcnt(" #n ")" ::: "memory")
; template <class Epi, class Sched>
; DI void gemm_phase(LAS unsigned char* lds, const int wv, const int lda, const int ldb, const Sched& S, const Epi& E) {
;     ...
;         const bool has_next = S.next(ui + 1, nxt);
;         const char* nA = has_next ? S.aptr(nxt) : cA; const char* nB = has_next ? S.bptr(nxt) : cB;
;         for (int t = 0; t < nt; t += 2) {
;             const bool last = (t == nt - 2);
;             const char* a1 = cA + (size_t)(t + 1) * kstep;
;             const char* a2 = last ? nA : cA + (size_t)(t + 2) * kstep; const char* b2 = last ? nB : cB + (size_t)(t + 2) * kstep;
;             const char* a3 = a2 + kstep; const char* b3 = b2 + kstep;
;             PG8_LDB(B0, 0, 0); PG8_LDB(B1, 0, 1); PG8_SCHED; PG8_LDA(At, 0, 0); PG8_STAGE(PG8_SA(1, 1), a1 + hstepA, voffA);
;             PG8_WAIT_V(8); PG8_WAIT_L(0); PG8_BAR; PG8_MMA(0, 0, At, B0); PG8_MMA(0, 1, At, B1); PG8_BAR; PG8_SCHED;
;             PG8_LDA(At, 0, 1); PG8_STAGE(PG8_SB(0, 0), b2, voffB); PG8_STAGE(PG8_SB(0, 1), b2 + hstepB, voffB); PG8_STAGE(PG8_SA(0, 0), a2, voffA);
;             PG8_WAIT_V(8); PG8_WAIT_L(0); PG8_BAR; PG8_MMA(1, 0, At, B0); PG8_MMA(1, 1, At, B1); PG8_BAR; PG8_SCHED;
.LBB0_1298:
	s_ashr_i32 s19, s18, 31
	s_lshl_b64 s[0:1], s[18:19], 20
	s_add_u32 s22, s33, s0
	s_addc_u32 s23, s38, s1
	s_and_b64 s[0:1], s[6:7], exec
	s_cselect_b32 s0, s23, s31
	s_cselect_b32 s1, s22, s30
	s_ashr_i32 s11, s10, 31
	s_lshl_b64 s[24:25], s[10:11], 20
	s_add_u32 s24, s39, s24
	s_addc_u32 s25, s40, s25
	s_and_b64 s[36:37], s[6:7], exec
	s_cselect_b32 s11, s25, s35
	s_cselect_b32 s15, s24, s34
	s_add_u32 s30, s30, 0x80080
	s_addc_u32 s31, s31, 0
	s_add_u32 s19, s34, 0x100
	s_addc_u32 s52, s35, 0
	s_mov_b32 s53, -2
	s_waitcnt lgkmcnt(0)
	s_add_u32 s34, s30, 0xfff80080
	s_addc_u32 s35, s31, -1
	s_add_i32 s54, 0, 0x10000
	s_cmp_eq_u32 s53, 28
	s_cselect_b32 s37, s0, s35
	s_cselect_b32 s36, s1, s34
	s_cselect_b32 s35, s11, s52
	s_cselect_b32 s34, s15, s19
	s_add_i32 s56, 0, 0x14000
	v_add_u32_e32 v150, s54, v155
	v_add_u32_e32 v172, s56, v155
	ds_read_b128 v[128:131], v150
	ds_read_b128 v[142:145], v150 offset:1024
	ds_read_b128 v[146:149], v150 offset:2048
	ds_read_b128 v[150:153], v150 offset:3072
	ds_read_b128 v[160:163], v172
	ds_read_b128 v[164:167], v172 offset:1024
	ds_read_b128 v[168:171], v172 offset:2048
	ds_read_b128 v[172:175], v172 offset:3072
	v_lshl_add_u64 v[216:217], s[30:31], 0, v[138:139]
	s_add_i32 m0, s27, 0xc000
	ds_read_b128 v[176:179], v159
	ds_read_b128 v[180:183], v159 offset:1024
	ds_read_b128 v[188:191], v159 offset:2048
	ds_read_b128 v[196:199], v159 offset:3072
	ds_read_b128 v[200:203], v159 offset:4096
	ds_read_b128 v[204:207], v159 offset:5120
	ds_read_b128 v[208:211], v159 offset:6144
	ds_read_b128 v[212:215], v159 offset:7168
	global_load_lds_dwordx4 v[216:217], off
	s_add_i32 m0, s27, 0xe000
	v_lshl_add_u64 v[216:217], s[30:31], 0, v[140:141]
	global_load_lds_dwordx4 v[216:217], off
	s_waitcnt vmcnt(8) lgkmcnt(0)
	s_barrier
	v_mfma_f32_16x16x32_bf16 v[124:127], v[128:131], v[176:179], 0
	v_mfma_f32_16x16x32_bf16 v[120:123], v[146:149], v[176:179], 0
	v_mfma_f32_16x16x32_bf16 v[108:111], v[128:131], v[188:191], 0
	v_mfma_f32_16x16x32_bf16 v[104:107], v[146:149], v[188:191], 0
	v_mfma_f32_16x16x32_bf16 v[96:99], v[128:131], v[200:203], 0
	v_mfma_f32_16x16x32_bf16 v[88:91], v[146:149], v[200:203], 0
	v_mfma_f32_16x16x32_bf16 v[80:83], v[128:131], v[208:211], 0
	v_mfma_f32_16x16x32_bf16 v[72:75], v[146:149], v[208:211], 0
	v_mfma_f32_16x16x32_bf16 v[124:127], v[142:145], v[180:183], v[124:127]
	v_mfma_f32_16x16x32_bf16 v[120:123], v[150:153], v[180:183], v[120:123]
	v_mfma_f32_16x16x32_bf16 v[108:111], v[142:145], v[196:199], v[108:111]
	v_mfma_f32_16x16x32_bf16 v[104:107], v[150:153], v[196:199], v[104:107]
	v_mfma_f32_16x16x32_bf16 v[96:99], v[142:145], v[204:207], v[96:99]
	v_mfma_f32_16x16x32_bf16 v[88:91], v[150:153], v[204:207], v[88:91]
	v_mfma_f32_16x16x32_bf16 v[80:83], v[142:145], v[212:215], v[80:83]
	v_mfma_f32_16x16x32_bf16 v[72:75], v[150:153], v[212:215], v[72:75]
	v_mfma_f32_16x16x32_bf16 v[116:119], v[160:163], v[176:179], 0
	v_mfma_f32_16x16x32_bf16 v[112:115], v[168:171], v[176:179], 0
	v_mfma_f32_16x16x32_bf16 v[100:103], v[160:163], v[188:191], 0
	v_mfma_f32_16x16x32_bf16 v[92:95], v[168:171], v[188:191], 0
	v_mfma_f32_16x16x32_bf16 v[84:87], v[160:163], v[200:203], 0
	v_mfma_f32_16x16x32_bf16 v[76:79], v[168:171], v[200:203], 0
	v_mfma_f32_16x16x32_bf16 v[68:71], v[160:163], v[208:211], 0
	v_mfma_f32_16x16x32_bf16 v[64:67], v[168:171], v[208:211], 0
	v_mfma_f32_16x16x32_bf16 v[116:119], v[164:167], v[180:183], v[116:119]
	v_mfma_f32_16x16x32_bf16 v[112:115], v[172:175], v[180:183], v[112:115]
	v_mfma_f32_16x16x32_bf16 v[100:103], v[164:167], v[196:199], v[100:103]
	v_mfma_f32_16x16x32_bf16 v[92:95], v[172:175], v[196:199], v[92:95]
	v_mfma_f32_16x16x32_bf16 v[84:87], v[164:167], v[204:207], v[84:87]
	v_mfma_f32_16x16x32_bf16 v[76:79], v[172:175], v[204:207], v[76:79]
	v_mfma_f32_16x16x32_bf16 v[68:71], v[164:167], v[212:215], v[68:71]
	v_mfma_f32_16x16x32_bf16 v[64:67], v[172:175], v[212:215], v[64:67]
	s_barrier
	s_add_i32 s54, s54, s41
	v_lshl_add_u64 v[216:217], s[34:35], 0, v[184:185]
	s_mov_b32 m0, s54
	ds_read_b128 v[176:179], v159 offset:16384
	ds_read_b128 v[180:183], v159 offset:17408
	ds_read_b128 v[188:191], v159 offset:18432
	ds_read_b128 v[196:199], v159 offset:19456
	ds_read_b128 v[200:203], v159 offset:20480
	ds_read_b128 v[204:207], v159 offset:21504
	ds_read_b128 v[208:211], v159 offset:22528
	ds_read_b128 v[212:215], v159 offset:23552
	global_load_lds_dwordx4 v[216:217], off
	s_add_i32 m0, s54, 0x2000
	s_add_u32 s54, s34, 0x80000
	v_lshl_add_u64 v[218:219], s[34:35], 0, v[136:137]
	s_addc_u32 s55, s35, 0
	s_add_i32 s56, s56, s41
	global_load_lds_dwordx4 v[218:219], off
	v_lshl_add_u64 v[220:221], s[54:55], 0, v[184:185]
	s_mov_b32 m0, s56
	v_lshl_add_u64 v[222:223], s[36:37], 0, v[134:135]
	global_load_lds_dwordx4 v[220:221], off
	s_add_i32 m0, s56, 0x2000
	v_lshl_add_u64 v[220:221], s[54:55], 0, v[136:137]
	global_load_lds_dwordx4 v[220:221], off
	s_mov_b32 m0, s27
	v_lshl_add_u64 v[220:221], s[36:37], 0, v[132:133]
	global_load_lds_dwordx4 v[220:221], off
	s_mov_b32 m0, s42
	s_nop 0
	global_load_lds_dwordx4 v[222:223], off
	s_waitcnt vmcnt(8) lgkmcnt(0)
	s_barrier
; #define PG8_STAGE(bufoff, gbase, voff) do { _Pragma("unroll") for (int _i = 0; _i < 2; ++_i) \
;         __builtin_amdgcn_global_load_lds((const unsigned*)((const char*)(gbase) + (voff)[_i]), (LAS unsigned*)(lds + (bufoff) + ldsw + _i * 8192), 16, 0, 0); } while (0)
; #define PG8_LDA(dst, b, h) do { _Pragma("unroll") for (int m = 0; m < 4; ++m) _Pragma("unroll") for (int k = 0; k < 2; ++k) dst[m][k] = *(const LAS bf16x8*)(lds + PG8_SA(b, h) + aoff + m * 2048 + k * 1024); } while (0)
; #define PG8_LDB(dst, b, h) do { _Pragma("unroll") for (int n = 0; n < 2; ++n) _Pragma("unroll") for (int k = 0; k < 2; ++k) dst[n][k] = *(const LAS bf16x8*)(lds + PG8_SB(b, h) + boff + n * 2048 + k * 1024); } while (0)
; #define PG8_MMA(ai, bj, At, Bt) do { __builtin_amdgcn_s_setprio(1); _Pragma("unroll") for (int m = 0; m < 4; ++m) _Pragma("unroll") for (int n = 0; n < 2; ++n) _Pragma("unroll") for (int k = 0; k < 2; ++k) \
;         acc[ai][bj][m][n] = __builtin_amdgcn_mfma_f32_16x16x32_bf16(Bt[n][k], At[m][k], acc[ai][bj][m][n], 0, 0, 0); __builtin_amdgcn_s_setprio(0); } while (0)
; #define PG8_WAIT_V(n) asm volatile("s_waitcnt vmcnt(" #n ")" ::: "memory")
; #define PG8_WAIT_L(n) asm volatile("s_waitcnt lgkmcnt(" #n ")" ::: "memory")
; #define PG8_BAR __builtin_amdgcn_s_barrier()
; #define PG8_SCHED __builtin_amdgcn_sched_barrier(0)
; template <class Epi, class Sched>
; DI void gemm_phase(LAS unsigned char* lds, const int wv, const int lda, const int ldb, const Sched& S, const Epi& E) {
;     ...
;             PG8_WAIT_V(8); PG8_WAIT_L(0); PG8_BAR; PG8_MMA(1, 0, At, B0); PG8_MMA(1, 1, At, B1); PG8_BAR; PG8_SCHED;
;             PG8_LDB(B0, 1, 0); PG8_LDB(B1, 1, 1); PG8_SCHED; PG8_LDA(At, 1, 0); PG8_STAGE(PG8_SA(0, 1), a2 + hstepA, voffA);
;             PG8_WAIT_V(8); PG8_WAIT_L(0); PG8_BAR; PG8_MMA(0, 0, At, B0); PG8_MMA(0, 1, At, B1); PG8_BAR; PG8_SCHED;
	v_mfma_f32_16x16x32_bf16 v[60:63], v[128:131], v[176:179], 0
	v_mfma_f32_16x16x32_bf16 v[56:59], v[146:149], v[176:179], 0
	v_mfma_f32_16x16x32_bf16 v[48:51], v[128:131], v[188:191], 0
	v_mfma_f32_16x16x32_bf16 v[40:43], v[146:149], v[188:191], 0
	v_mfma_f32_16x16x32_bf16 v[32:35], v[128:131], v[200:203], 0
	v_mfma_f32_16x16x32_bf16 v[24:27], v[146:149], v[200:203], 0
	v_mfma_f32_16x16x32_bf16 v[16:19], v[128:131], v[208:211], 0
	v_mfma_f32_16x16x32_bf16 v[8:11], v[146:149], v[208:211], 0
	v_mfma_f32_16x16x32_bf16 v[60:63], v[142:145], v[180:183], v[60:63]
	v_mfma_f32_16x16x32_bf16 v[56:59], v[150:153], v[180:183], v[56:59]
	v_mfma_f32_16x16x32_bf16 v[48:51], v[142:145], v[196:199], v[48:51]
	v_mfma_f32_16x16x32_bf16 v[40:43], v[150:153], v[196:199], v[40:43]
	v_mfma_f32_16x16x32_bf16 v[32:35], v[142:145], v[204:207], v[32:35]
	v_mfma_f32_16x16x32_bf16 v[24:27], v[150:153], v[204:207], v[24:27]
	v_mfma_f32_16x16x32_bf16 v[16:19], v[142:145], v[212:215], v[16:19]
	v_mfma_f32_16x16x32_bf16 v[8:11], v[150:153], v[212:215], v[8:11]
	v_mfma_f32_16x16x32_bf16 v[52:55], v[160:163], v[176:179], 0
	v_mfma_f32_16x16x32_bf16 v[44:47], v[168:171], v[176:179], 0
	v_mfma_f32_16x16x32_bf16 v[36:39], v[160:163], v[188:191], 0
	v_mfma_f32_16x16x32_bf16 v[28:31], v[168:171], v[188:191], 0
	v_mfma_f32_16x16x32_bf16 v[20:23], v[160:163], v[200:203], 0
	v_mfma_f32_16x16x32_bf16 v[12:15], v[168:171], v[200:203], 0
	v_mfma_f32_16x16x32_bf16 v[4:7], v[160:163], v[208:211], 0
	v_mfma_f32_16x16x32_bf16 v[0:3], v[168:171], v[208:211], 0
	v_mfma_f32_16x16x32_bf16 v[52:55], v[164:167], v[180:183], v[52:55]
	v_mfma_f32_16x16x32_bf16 v[44:47], v[172:175], v[180:183], v[44:47]
	v_mfma_f32_16x16x32_bf16 v[36:39], v[164:167], v[196:199], v[36:39]
	v_mfma_f32_16x16x32_bf16 v[28:31], v[172:175], v[196:199], v[28:31]
	v_mfma_f32_16x16x32_bf16 v[20:23], v[164:167], v[204:207], v[20:23]
	v_mfma_f32_16x16x32_bf16 v[12:15], v[172:175], v[204:207], v[12:15]
	v_mfma_f32_16x16x32_bf16 v[4:7], v[164:167], v[212:215], v[4:7]
	v_mfma_f32_16x16x32_bf16 v[0:3], v[172:175], v[212:215], v[0:3]
	s_barrier
	s_add_i32 s54, 0, 0x18000
	s_add_i32 s55, 0, 0x1c000
	v_add_u32_e32 v150, s54, v155
	v_add_u32_e32 v172, s55, v155
	ds_read_b128 v[128:131], v150
	ds_read_b128 v[142:145], v150 offset:1024
	ds_read_b128 v[146:149], v150 offset:2048
	ds_read_b128 v[150:153], v150 offset:3072
	ds_read_b128 v[160:163], v172
	ds_read_b128 v[164:167], v172 offset:1024
	ds_read_b128 v[168:171], v172 offset:2048
	ds_read_b128 v[172:175], v172 offset:3072
	s_add_u32 s36, s36, 0x80000
	s_addc_u32 s37, s37, 0
	s_mov_b32 m0, s43
	v_lshl_add_u64 v[234:235], s[36:37], 0, v[132:133]
	ds_read_b128 v[176:179], v159 offset:32768
	ds_read_b128 v[180:183], v159 offset:33792
	ds_read_b128 v[188:191], v159 offset:34816
	ds_read_b128 v[196:199], v159 offset:35840
	ds_read_b128 v[200:203], v159 offset:36864
	ds_read_b128 v[204:207], v159 offset:37888
	ds_read_b128 v[208:211], v159 offset:38912
	ds_read_b128 v[212:215], v159 offset:39936
	global_load_lds_dwordx4 v[234:235], off
	s_mov_b32 m0, s44
	v_lshl_add_u64 v[234:235], s[36:37], 0, v[134:135]
	global_load_lds_dwordx4 v[234:235], off
	s_waitcnt vmcnt(8) lgkmcnt(0)
	s_barrier
	v_mfma_f32_16x16x32_bf16 v[124:127], v[128:131], v[176:179], v[124:127]
	v_mfma_f32_16x16x32_bf16 v[120:123], v[146:149], v[176:179], v[120:123]
	v_mfma_f32_16x16x32_bf16 v[108:111], v[128:131], v[188:191], v[108:111]
	v_mfma_f32_16x16x32_bf16 v[104:107], v[146:149], v[188:191], v[104:107]
	v_mfma_f32_16x16x32_bf16 v[96:99], v[128:131], v[200:203], v[96:99]
	v_mfma_f32_16x16x32_bf16 v[88:91], v[146:149], v[200:203], v[88:91]
	v_mfma_f32_16x16x32_bf16 v[80:83], v[128:131], v[208:211], v[80:83]
	v_mfma_f32_16x16x32_bf16 v[72:75], v[146:149], v[208:211], v[72:75]
	v_mfma_f32_16x16x32_bf16 v[124:127], v[142:145], v[180:183], v[124:127]
	v_mfma_f32_16x16x32_bf16 v[120:123], v[150:153], v[180:183], v[120:123]
	v_mfma_f32_16x16x32_bf16 v[108:111], v[142:145], v[196:199], v[108:111]
	v_mfma_f32_16x16x32_bf16 v[104:107], v[150:153], v[196:199], v[104:107]
	v_mfma_f32_16x16x32_bf16 v[96:99], v[142:145], v[204:207], v[96:99]
	v_mfma_f32_16x16x32_bf16 v[88:91], v[150:153], v[204:207], v[88:91]
	v_mfma_f32_16x16x32_bf16 v[80:83], v[142:145], v[212:215], v[80:83]
	v_mfma_f32_16x16x32_bf16 v[72:75], v[150:153], v[212:215], v[72:75]
	v_mfma_f32_16x16x32_bf16 v[116:119], v[160:163], v[176:179], v[116:119]
	v_mfma_f32_16x16x32_bf16 v[112:115], v[168:171], v[176:179], v[112:115]
	v_mfma_f32_16x16x32_bf16 v[100:103], v[160:163], v[188:191], v[100:103]
	v_mfma_f32_16x16x32_bf16 v[92:95], v[168:171], v[188:191], v[92:95]
	v_mfma_f32_16x16x32_bf16 v[84:87], v[160:163], v[200:203], v[84:87]
	v_mfma_f32_16x16x32_bf16 v[76:79], v[168:171], v[200:203], v[76:79]
	v_mfma_f32_16x16x32_bf16 v[68:71], v[160:163], v[208:211], v[68:71]
	v_mfma_f32_16x16x32_bf16 v[64:67], v[168:171], v[208:211], v[64:67]
	v_mfma_f32_16x16x32_bf16 v[116:119], v[164:167], v[180:183], v[116:119]
	v_mfma_f32_16x16x32_bf16 v[112:115], v[172:175], v[180:183], v[112:115]
	v_mfma_f32_16x16x32_bf16 v[100:103], v[164:167], v[196:199], v[100:103]
	v_mfma_f32_16x16x32_bf16 v[92:95], v[172:175], v[196:199], v[92:95]
	v_mfma_f32_16x16x32_bf16 v[84:87], v[164:167], v[204:207], v[84:87]
	v_mfma_f32_16x16x32_bf16 v[76:79], v[172:175], v[204:207], v[76:79]
	v_mfma_f32_16x16x32_bf16 v[68:71], v[164:167], v[212:215], v[68:71]
	v_mfma_f32_16x16x32_bf16 v[64:67], v[172:175], v[212:215], v[64:67]
	s_barrier
; #define PG8_STAGE(bufoff, gbase, voff) do { _Pragma("unroll") for (int _i = 0; _i < 2; ++_i) \
;         __builtin_amdgcn_global_load_lds((const unsigned*)((const char*)(gbase) + (voff)[_i]), (LAS unsigned*)(lds + (bufoff) + ldsw + _i * 8192), 16, 0, 0); } while (0)
; #define PG8_LDA(dst, b, h) do { _Pragma("unroll") for (int m = 0; m < 4; ++m) _Pragma("unroll") for (int k = 0; k < 2; ++k) dst[m][k] = *(const LAS bf16x8*)(lds + PG8_SA(b, h) + aoff + m * 2048 + k * 1024); } while (0)
; #define PG8_LDB(dst, b, h) do { _Pragma("unroll") for (int n = 0; n < 2; ++n) _Pragma("unroll") for (int k = 0; k < 2; ++k) dst[n][k] = *(const LAS bf16x8*)(lds + PG8_SB(b, h) + boff + n * 2048 + k * 1024); } while (0)
; #define PG8_MMA(ai, bj, At, Bt) do { __builtin_amdgcn_s_setprio(1); _Pragma("unroll") for (int m = 0; m < 4; ++m) _Pragma("unroll") for (int n = 0; n < 2; ++n) _Pragma("unroll") for (int k = 0; k < 2; ++k) \
;         acc[ai][bj][m][n] = __builtin_amdgcn_mfma_f32_16x16x32_bf16(Bt[n][k], At[m][k], acc[ai][bj][m][n], 0, 0, 0); __builtin_amdgcn_s_setprio(0); } while (0)
; #define PG8_WAIT_V(n) asm volatile("s_waitcnt vmcnt(" #n ")" ::: "memory")
; #define PG8_WAIT_L(n) asm volatile("s_waitcnt lgkmcnt(" #n ")" ::: "memory")
; #define PG8_BAR __builtin_amdgcn_s_barrier()
; #define PG8_SCHED __builtin_amdgcn_sched_barrier(0)
; template <class Epi, class Sched>
; DI void gemm_phase(LAS unsigned char* lds, const int wv, const int lda, const int ldb, const Sched& S, const Epi& E) {
;     ...
;         for (int t = 0; t < nt; t += 2) {
;             const bool last = (t == nt - 2);
;             const char* a1 = cA + (size_t)(t + 1) * kstep;
;             const char* a2 = last ? nA : cA + (size_t)(t + 2) * kstep; const char* b2 = last ? nB : cB + (size_t)(t + 2) * kstep;
;             const char* a3 = a2 + kstep; const char* b3 = b2 + kstep;
;             PG8_LDB(B0, 0, 0); PG8_LDB(B1, 0, 1); PG8_SCHED; PG8_LDA(At, 0, 0); PG8_STAGE(PG8_SA(1, 1), a1 + hstepA, voffA);
;             PG8_WAIT_V(8); PG8_WAIT_L(0); PG8_BAR; PG8_MMA(0, 0, At, B0); PG8_MMA(0, 1, At, B1); PG8_BAR; PG8_SCHED;
;     ...
;             PG8_LDA(At, 1, 1); PG8_STAGE(PG8_SB(1, 0), b3, voffB); PG8_STAGE(PG8_SB(1, 1), b3 + hstepB, voffB); PG8_STAGE(PG8_SA(1, 0), a3, voffA);
;             PG8_WAIT_V(8); PG8_WAIT_L(0); PG8_BAR; PG8_MMA(1, 0, At, B0); PG8_MMA(1, 1, At, B1); PG8_BAR; PG8_SCHED;
	s_add_i32 s36, s54, s41
	v_lshl_add_u64 v[216:217], v[216:217], 0, s[28:29]
	s_mov_b32 m0, s36
	ds_read_b128 v[176:179], v159 offset:49152
	ds_read_b128 v[180:183], v159 offset:50176
	ds_read_b128 v[188:191], v159 offset:51200
	ds_read_b128 v[196:199], v159 offset:52224
	ds_read_b128 v[200:203], v159 offset:53248
	ds_read_b128 v[204:207], v159 offset:54272
	ds_read_b128 v[208:211], v159 offset:55296
	ds_read_b128 v[212:215], v159 offset:56320
	global_load_lds_dwordx4 v[216:217], off
	s_add_i32 m0, s36, 0x2000
	s_add_u32 s34, s34, 0x80080
	v_lshl_add_u64 v[216:217], v[218:219], 0, s[28:29]
	s_addc_u32 s35, s35, 0
	s_add_i32 s36, s55, s41
	global_load_lds_dwordx4 v[216:217], off
	s_mov_b32 m0, s36
	v_lshl_add_u64 v[216:217], s[34:35], 0, v[184:185]
	global_load_lds_dwordx4 v[216:217], off
	s_add_i32 m0, s36, 0x2000
	v_lshl_add_u64 v[216:217], s[34:35], 0, v[136:137]
	global_load_lds_dwordx4 v[216:217], off
	s_mov_b32 m0, s45
	v_lshl_add_u64 v[216:217], v[220:221], 0, s[28:29]
	global_load_lds_dwordx4 v[216:217], off
	s_mov_b32 m0, s46
	v_lshl_add_u64 v[216:217], v[222:223], 0, s[28:29]
	global_load_lds_dwordx4 v[216:217], off
	s_waitcnt vmcnt(8) lgkmcnt(0)
	s_barrier
	v_mfma_f32_16x16x32_bf16 v[60:63], v[128:131], v[176:179], v[60:63]
	v_mfma_f32_16x16x32_bf16 v[56:59], v[146:149], v[176:179], v[56:59]
	v_mfma_f32_16x16x32_bf16 v[48:51], v[128:131], v[188:191], v[48:51]
	v_mfma_f32_16x16x32_bf16 v[40:43], v[146:149], v[188:191], v[40:43]
	v_mfma_f32_16x16x32_bf16 v[32:35], v[128:131], v[200:203], v[32:35]
	v_mfma_f32_16x16x32_bf16 v[24:27], v[146:149], v[200:203], v[24:27]
	v_mfma_f32_16x16x32_bf16 v[16:19], v[128:131], v[208:211], v[16:19]
	v_mfma_f32_16x16x32_bf16 v[8:11], v[146:149], v[208:211], v[8:11]
	v_mfma_f32_16x16x32_bf16 v[60:63], v[142:145], v[180:183], v[60:63]
	v_mfma_f32_16x16x32_bf16 v[56:59], v[150:153], v[180:183], v[56:59]
	v_mfma_f32_16x16x32_bf16 v[48:51], v[142:145], v[196:199], v[48:51]
	v_mfma_f32_16x16x32_bf16 v[40:43], v[150:153], v[196:199], v[40:43]
	v_mfma_f32_16x16x32_bf16 v[32:35], v[142:145], v[204:207], v[32:35]
	v_mfma_f32_16x16x32_bf16 v[24:27], v[150:153], v[204:207], v[24:27]
	v_mfma_f32_16x16x32_bf16 v[16:19], v[142:145], v[212:215], v[16:19]
	v_mfma_f32_16x16x32_bf16 v[8:11], v[150:153], v[212:215], v[8:11]
	v_mfma_f32_16x16x32_bf16 v[52:55], v[160:163], v[176:179], v[52:55]
	v_mfma_f32_16x16x32_bf16 v[44:47], v[168:171], v[176:179], v[44:47]
	v_mfma_f32_16x16x32_bf16 v[36:39], v[160:163], v[188:191], v[36:39]
	v_mfma_f32_16x16x32_bf16 v[28:31], v[168:171], v[188:191], v[28:31]
	v_mfma_f32_16x16x32_bf16 v[20:23], v[160:163], v[200:203], v[20:23]
	v_mfma_f32_16x16x32_bf16 v[12:15], v[168:171], v[200:203], v[12:15]
	v_mfma_f32_16x16x32_bf16 v[4:7], v[160:163], v[208:211], v[4:7]
	v_mfma_f32_16x16x32_bf16 v[0:3], v[168:171], v[208:211], v[0:3]
	v_mfma_f32_16x16x32_bf16 v[52:55], v[164:167], v[180:183], v[52:55]
	v_mfma_f32_16x16x32_bf16 v[44:47], v[172:175], v[180:183], v[44:47]
	v_mfma_f32_16x16x32_bf16 v[36:39], v[164:167], v[196:199], v[36:39]
	v_mfma_f32_16x16x32_bf16 v[28:31], v[172:175], v[196:199], v[28:31]
	v_mfma_f32_16x16x32_bf16 v[20:23], v[164:167], v[204:207], v[20:23]
	v_mfma_f32_16x16x32_bf16 v[12:15], v[172:175], v[204:207], v[12:15]
	v_mfma_f32_16x16x32_bf16 v[4:7], v[164:167], v[212:215], v[4:7]
	v_mfma_f32_16x16x32_bf16 v[0:3], v[172:175], v[212:215], v[0:3]
	s_barrier
	s_add_i32 s53, s53, 2
	s_add_u32 s30, s30, 0x100
	s_addc_u32 s31, s31, 0
	s_add_u32 s19, s19, 0x100
	s_addc_u32 s52, s52, 0
.LBB0_1299:
	s_add_u32 s34, s30, 0xfff80080
	s_addc_u32 s35, s31, -1
	s_add_i32 s54, 0, 0x10000
	s_cmp_eq_u32 s53, 28
	s_cselect_b32 s37, s0, s35
	s_cselect_b32 s36, s1, s34
	s_cselect_b32 s35, s11, s52
	s_cselect_b32 s34, s15, s19
	s_add_i32 s56, 0, 0x14000
	v_add_u32_e32 v150, s54, v155
	v_add_u32_e32 v172, s56, v155
	ds_read_b128 v[128:131], v150
	ds_read_b128 v[142:145], v150 offset:1024
	ds_read_b128 v[146:149], v150 offset:2048
	ds_read_b128 v[150:153], v150 offset:3072
	ds_read_b128 v[160:163], v172
	ds_read_b128 v[164:167], v172 offset:1024
	ds_read_b128 v[168:171], v172 offset:2048
	ds_read_b128 v[172:175], v172 offset:3072
	v_lshl_add_u64 v[216:217], s[30:31], 0, v[138:139]
	s_add_i32 m0, s27, 0xc000
	ds_read_b128 v[176:179], v159
	ds_read_b128 v[180:183], v159 offset:1024
	ds_read_b128 v[188:191], v159 offset:2048
	ds_read_b128 v[196:199], v159 offset:3072
	ds_read_b128 v[200:203], v159 offset:4096
	ds_read_b128 v[204:207], v159 offset:5120
	ds_read_b128 v[208:211], v159 offset:6144
	ds_read_b128 v[212:215], v159 offset:7168
	global_load_lds_dwordx4 v[216:217], off
	s_add_i32 m0, s27, 0xe000
	v_lshl_add_u64 v[216:217], s[30:31], 0, v[140:141]
	global_load_lds_dwordx4 v[216:217], off
	s_waitcnt vmcnt(8) lgkmcnt(0)
	s_barrier
; #define PG8_STAGE(bufoff, gbase, voff) do { _Pragma("unroll") for (int _i = 0; _i < 2; ++_i) \
;         __builtin_amdgcn_global_load_lds((const unsigned*)((const char*)(gbase) + (voff)[_i]), (LAS unsigned*)(lds + (bufoff) + ldsw + _i * 8192), 16, 0, 0); } while (0)
; #define PG8_LDA(dst, b, h) do { _Pragma("unroll") for (int m = 0; m < 4; ++m) _Pragma("unroll") for (int k = 0; k < 2; ++k) dst[m][k] = *(const LAS bf16x8*)(lds + PG8_SA(b, h) + aoff + m * 2048 + k * 1024); } while (0)
; #define PG8_MMA(ai, bj, At, Bt) do { __builtin_amdgcn_s_setprio(1); _Pragma("unroll") for (int m = 0; m < 4; ++m) _Pragma("unroll") for (int n = 0; n < 2; ++n) _Pragma("unroll") for (int k = 0; k < 2; ++k) \
;         acc[ai][bj][m][n] = __builtin_amdgcn_mfma_f32_16x16x32_bf16(Bt[n][k], At[m][k], acc[ai][bj][m][n], 0, 0, 0); __builtin_amdgcn_s_setprio(0); } while (0)
; #define PG8_WAIT_V(n) asm volatile("s_waitcnt vmcnt(" #n ")" ::: "memory")
; #define PG8_WAIT_L(n) asm volatile("s_waitcnt lgkmcnt(" #n ")" ::: "memory")
; #define PG8_BAR __builtin_amdgcn_s_barrier()
; #define PG8_SCHED __builtin_amdgcn_sched_barrier(0)
; template <class Epi, class Sched>
; DI void gemm_phase(LAS unsigned char* lds, const int wv, const int lda, const int ldb, const Sched& S, const Epi& E) {
;     ...
;             PG8_WAIT_V(8); PG8_WAIT_L(0); PG8_BAR; PG8_MMA(0, 0, At, B0); PG8_MMA(0, 1, At, B1); PG8_BAR; PG8_SCHED;
;             PG8_LDA(At, 0, 1); PG8_STAGE(PG8_SB(0, 0), b2, voffB); PG8_STAGE(PG8_SB(0, 1), b2 + hstepB, voffB); PG8_STAGE(PG8_SA(0, 0), a2, voffA);
;             PG8_WAIT_V(8); PG8_WAIT_L(0); PG8_BAR; PG8_MMA(1, 0, At, B0); PG8_MMA(1, 1, At, B1); PG8_BAR; PG8_SCHED;
	v_mfma_f32_16x16x32_bf16 v[124:127], v[128:131], v[176:179], v[124:127]
	v_mfma_f32_16x16x32_bf16 v[120:123], v[146:149], v[176:179], v[120:123]
	v_mfma_f32_16x16x32_bf16 v[108:111], v[128:131], v[188:191], v[108:111]
	v_mfma_f32_16x16x32_bf16 v[104:107], v[146:149], v[188:191], v[104:107]
	v_mfma_f32_16x16x32_bf16 v[96:99], v[128:131], v[200:203], v[96:99]
	v_mfma_f32_16x16x32_bf16 v[88:91], v[146:149], v[200:203], v[88:91]
	v_mfma_f32_16x16x32_bf16 v[80:83], v[128:131], v[208:211], v[80:83]
	v_mfma_f32_16x16x32_bf16 v[72:75], v[146:149], v[208:211], v[72:75]
	v_mfma_f32_16x16x32_bf16 v[124:127], v[142:145], v[180:183], v[124:127]
	v_mfma_f32_16x16x32_bf16 v[120:123], v[150:153], v[180:183], v[120:123]
	v_mfma_f32_16x16x32_bf16 v[108:111], v[142:145], v[196:199], v[108:111]
	v_mfma_f32_16x16x32_bf16 v[104:107], v[150:153], v[196:199], v[104:107]
	v_mfma_f32_16x16x32_bf16 v[96:99], v[142:145], v[204:207], v[96:99]
	v_mfma_f32_16x16x32_bf16 v[88:91], v[150:153], v[204:207], v[88:91]
	v_mfma_f32_16x16x32_bf16 v[80:83], v[142:145], v[212:215], v[80:83]
	v_mfma_f32_16x16x32_bf16 v[72:75], v[150:153], v[212:215], v[72:75]
	v_mfma_f32_16x16x32_bf16 v[116:119], v[160:163], v[176:179], v[116:119]
	v_mfma_f32_16x16x32_bf16 v[112:115], v[168:171], v[176:179], v[112:115]
	v_mfma_f32_16x16x32_bf16 v[100:103], v[160:163], v[188:191], v[100:103]
	v_mfma_f32_16x16x32_bf16 v[92:95], v[168:171], v[188:191], v[92:95]
	v_mfma_f32_16x16x32_bf16 v[84:87], v[160:163], v[200:203], v[84:87]
	v_mfma_f32_16x16x32_bf16 v[76:79], v[168:171], v[200:203], v[76:79]
	v_mfma_f32_16x16x32_bf16 v[68:71], v[160:163], v[208:211], v[68:71]
	v_mfma_f32_16x16x32_bf16 v[64:67], v[168:171], v[208:211], v[64:67]
	v_mfma_f32_16x16x32_bf16 v[116:119], v[164:167], v[180:183], v[116:119]
	v_mfma_f32_16x16x32_bf16 v[112:115], v[172:175], v[180:183], v[112:115]
	v_mfma_f32_16x16x32_bf16 v[100:103], v[164:167], v[196:199], v[100:103]
	v_mfma_f32_16x16x32_bf16 v[92:95], v[172:175], v[196:199], v[92:95]
	v_mfma_f32_16x16x32_bf16 v[84:87], v[164:167], v[204:207], v[84:87]
	v_mfma_f32_16x16x32_bf16 v[76:79], v[172:175], v[204:207], v[76:79]
	v_mfma_f32_16x16x32_bf16 v[68:71], v[164:167], v[212:215], v[68:71]
	v_mfma_f32_16x16x32_bf16 v[64:67], v[172:175], v[212:215], v[64:67]
	s_barrier
	s_add_i32 s54, s54, s41
	v_lshl_add_u64 v[216:217], s[34:35], 0, v[184:185]
	s_mov_b32 m0, s54
	ds_read_b128 v[176:179], v159 offset:16384
	ds_read_b128 v[180:183], v159 offset:17408
	ds_read_b128 v[188:191], v159 offset:18432
	ds_read_b128 v[196:199], v159 offset:19456
	ds_read_b128 v[200:203], v159 offset:20480
	ds_read_b128 v[204:207], v159 offset:21504
	ds_read_b128 v[208:211], v159 offset:22528
	ds_read_b128 v[212:215], v159 offset:23552
	global_load_lds_dwordx4 v[216:217], off
	s_add_i32 m0, s54, 0x2000
	s_add_u32 s54, s34, 0x80000
	v_lshl_add_u64 v[218:219], s[34:35], 0, v[136:137]
	s_addc_u32 s55, s35, 0
	s_add_i32 s56, s56, s41
	global_load_lds_dwordx4 v[218:219], off
	v_lshl_add_u64 v[220:221], s[54:55], 0, v[184:185]
	s_mov_b32 m0, s56
	v_lshl_add_u64 v[222:223], s[36:37], 0, v[134:135]
	global_load_lds_dwordx4 v[220:221], off
	s_add_i32 m0, s56, 0x2000
	v_lshl_add_u64 v[220:221], s[54:55], 0, v[136:137]
	global_load_lds_dwordx4 v[220:221], off
	s_mov_b32 m0, s27
	v_lshl_add_u64 v[220:221], s[36:37], 0, v[132:133]
	global_load_lds_dwordx4 v[220:221], off
	s_mov_b32 m0, s42
	s_nop 0
	global_load_lds_dwordx4 v[222:223], off
	s_waitcnt vmcnt(8) lgkmcnt(0)
	s_barrier
	v_mfma_f32_16x16x32_bf16 v[60:63], v[128:131], v[176:179], v[60:63]
	v_mfma_f32_16x16x32_bf16 v[56:59], v[146:149], v[176:179], v[56:59]
	v_mfma_f32_16x16x32_bf16 v[48:51], v[128:131], v[188:191], v[48:51]
	v_mfma_f32_16x16x32_bf16 v[40:43], v[146:149], v[188:191], v[40:43]
	v_mfma_f32_16x16x32_bf16 v[32:35], v[128:131], v[200:203], v[32:35]
	v_mfma_f32_16x16x32_bf16 v[24:27], v[146:149], v[200:203], v[24:27]
	v_mfma_f32_16x16x32_bf16 v[16:19], v[128:131], v[208:211], v[16:19]
	v_mfma_f32_16x16x32_bf16 v[8:11], v[146:149], v[208:211], v[8:11]
	v_mfma_f32_16x16x32_bf16 v[60:63], v[142:145], v[180:183], v[60:63]
	v_mfma_f32_16x16x32_bf16 v[56:59], v[150:153], v[180:183], v[56:59]
	v_mfma_f32_16x16x32_bf16 v[48:51], v[142:145], v[196:199], v[48:51]
	v_mfma_f32_16x16x32_bf16 v[40:43], v[150:153], v[196:199], v[40:43]
	v_mfma_f32_16x16x32_bf16 v[32:35], v[142:145], v[204:207], v[32:35]
	v_mfma_f32_16x16x32_bf16 v[24:27], v[150:153], v[204:207], v[24:27]
	v_mfma_f32_16x16x32_bf16 v[16:19], v[142:145], v[212:215], v[16:19]
	v_mfma_f32_16x16x32_bf16 v[8:11], v[150:153], v[212:215], v[8:11]
	v_mfma_f32_16x16x32_bf16 v[52:55], v[160:163], v[176:179], v[52:55]
	v_mfma_f32_16x16x32_bf16 v[44:47], v[168:171], v[176:179], v[44:47]
	v_mfma_f32_16x16x32_bf16 v[36:39], v[160:163], v[188:191], v[36:39]
	v_mfma_f32_16x16x32_bf16 v[28:31], v[168:171], v[188:191], v[28:31]
	v_mfma_f32_16x16x32_bf16 v[20:23], v[160:163], v[200:203], v[20:23]
	v_mfma_f32_16x16x32_bf16 v[12:15], v[168:171], v[200:203], v[12:15]
	v_mfma_f32_16x16x32_bf16 v[4:7], v[160:163], v[208:211], v[4:7]
	v_mfma_f32_16x16x32_bf16 v[0:3], v[168:171], v[208:211], v[0:3]
	v_mfma_f32_16x16x32_bf16 v[52:55], v[164:167], v[180:183], v[52:55]
	v_mfma_f32_16x16x32_bf16 v[44:47], v[172:175], v[180:183], v[44:47]
	v_mfma_f32_16x16x32_bf16 v[36:39], v[164:167], v[196:199], v[36:39]
	v_mfma_f32_16x16x32_bf16 v[28:31], v[172:175], v[196:199], v[28:31]
	v_mfma_f32_16x16x32_bf16 v[20:23], v[164:167], v[204:207], v[20:23]
	v_mfma_f32_16x16x32_bf16 v[12:15], v[172:175], v[204:207], v[12:15]
	v_mfma_f32_16x16x32_bf16 v[4:7], v[164:167], v[212:215], v[4:7]
	v_mfma_f32_16x16x32_bf16 v[0:3], v[172:175], v[212:215], v[0:3]
	s_barrier
; #define PG8_STAGE(bufoff, gbase, voff) do { _Pragma("unroll") for (int _i = 0; _i < 2; ++_i) \
;         __builtin_amdgcn_global_load_lds((const unsigned*)((const char*)(gbase) + (voff)[_i]), (LAS unsigned*)(lds + (bufoff) + ldsw + _i * 8192), 16, 0, 0); } while (0)
; #define PG8_LDA(dst, b, h) do { _Pragma("unroll") for (int m = 0; m < 4; ++m) _Pragma("unroll") for (int k = 0; k < 2; ++k) dst[m][k] = *(const LAS bf16x8*)(lds + PG8_SA(b, h) + aoff + m * 2048 + k * 1024); } while (0)
; #define PG8_LDB(dst, b, h) do { _Pragma("unroll") for (int n = 0; n < 2; ++n) _Pragma("unroll") for (int k = 0; k < 2; ++k) dst[n][k] = *(const LAS bf16x8*)(lds + PG8_SB(b, h) + boff + n * 2048 + k * 1024); } while (0)
; #define PG8_MMA(ai, bj, At, Bt) do { __builtin_amdgcn_s_setprio(1); _Pragma("unroll") for (int m = 0; m < 4; ++m) _Pragma("unroll") for (int n = 0; n < 2; ++n) _Pragma("unroll") for (int k = 0; k < 2; ++k) \
;         acc[ai][bj][m][n] = __builtin_amdgcn_mfma_f32_16x16x32_bf16(Bt[n][k], At[m][k], acc[ai][bj][m][n], 0, 0, 0); __builtin_amdgcn_s_setprio(0); } while (0)
; #define PG8_WAIT_V(n) asm volatile("s_waitcnt vmcnt(" #n ")" ::: "memory")
; #define PG8_WAIT_L(n) asm volatile("s_waitcnt lgkmcnt(" #n ")" ::: "memory")
; #define PG8_BAR __builtin_amdgcn_s_barrier()
; #define PG8_SCHED __builtin_amdgcn_sched_barrier(0)
; template <class Epi, class Sched>
; DI void gemm_phase(LAS unsigned char* lds, const int wv, const int lda, const int ldb, const Sched& S, const Epi& E) {
;     ...
;             PG8_LDB(B0, 1, 0); PG8_LDB(B1, 1, 1); PG8_SCHED; PG8_LDA(At, 1, 0); PG8_STAGE(PG8_SA(0, 1), a2 + hstepA, voffA);
;             PG8_WAIT_V(8); PG8_WAIT_L(0); PG8_BAR; PG8_MMA(0, 0, At, B0); PG8_MMA(0, 1, At, B1); PG8_BAR; PG8_SCHED;
;             PG8_LDA(At, 1, 1); PG8_STAGE(PG8_SB(1, 0), b3, voffB); PG8_STAGE(PG8_SB(1, 1), b3 + hstepB, voffB); PG8_STAGE(PG8_SA(1, 0), a3, voffA);
;             PG8_WAIT_V(8); PG8_WAIT_L(0); PG8_BAR; PG8_MMA(1, 0, At, B0); PG8_MMA(1, 1, At, B1); PG8_BAR; PG8_SCHED;
;         }
;         if (wr == 0) PG8_BAR;
	s_add_i32 s54, 0, 0x18000
	s_add_i32 s55, 0, 0x1c000
	v_add_u32_e32 v150, s54, v155
	v_add_u32_e32 v172, s55, v155
	ds_read_b128 v[128:131], v150
	ds_read_b128 v[142:145], v150 offset:1024
	ds_read_b128 v[146:149], v150 offset:2048
	ds_read_b128 v[150:153], v150 offset:3072
	ds_read_b128 v[160:163], v172
	ds_read_b128 v[164:167], v172 offset:1024
	ds_read_b128 v[168:171], v172 offset:2048
	ds_read_b128 v[172:175], v172 offset:3072
	s_add_u32 s36, s36, 0x80000
	s_addc_u32 s37, s37, 0
	s_mov_b32 m0, s43
	v_lshl_add_u64 v[234:235], s[36:37], 0, v[132:133]
	ds_read_b128 v[176:179], v159 offset:32768
	ds_read_b128 v[180:183], v159 offset:33792
	ds_read_b128 v[188:191], v159 offset:34816
	ds_read_b128 v[196:199], v159 offset:35840
	ds_read_b128 v[200:203], v159 offset:36864
	ds_read_b128 v[204:207], v159 offset:37888
	ds_read_b128 v[208:211], v159 offset:38912
	ds_read_b128 v[212:215], v159 offset:39936
	global_load_lds_dwordx4 v[234:235], off
	s_mov_b32 m0, s44
	v_lshl_add_u64 v[234:235], s[36:37], 0, v[134:135]
	global_load_lds_dwordx4 v[234:235], off
	s_waitcnt vmcnt(8) lgkmcnt(0)
	s_barrier
	v_mfma_f32_16x16x32_bf16 v[124:127], v[128:131], v[176:179], v[124:127]
	v_mfma_f32_16x16x32_bf16 v[120:123], v[146:149], v[176:179], v[120:123]
	v_mfma_f32_16x16x32_bf16 v[108:111], v[128:131], v[188:191], v[108:111]
	v_mfma_f32_16x16x32_bf16 v[104:107], v[146:149], v[188:191], v[104:107]
	v_mfma_f32_16x16x32_bf16 v[96:99], v[128:131], v[200:203], v[96:99]
	v_mfma_f32_16x16x32_bf16 v[88:91], v[146:149], v[200:203], v[88:91]
	v_mfma_f32_16x16x32_bf16 v[80:83], v[128:131], v[208:211], v[80:83]
	v_mfma_f32_16x16x32_bf16 v[72:75], v[146:149], v[208:211], v[72:75]
	v_mfma_f32_16x16x32_bf16 v[124:127], v[142:145], v[180:183], v[124:127]
	v_mfma_f32_16x16x32_bf16 v[120:123], v[150:153], v[180:183], v[120:123]
	v_mfma_f32_16x16x32_bf16 v[108:111], v[142:145], v[196:199], v[108:111]
	v_mfma_f32_16x16x32_bf16 v[104:107], v[150:153], v[196:199], v[104:107]
	v_mfma_f32_16x16x32_bf16 v[96:99], v[142:145], v[204:207], v[96:99]
	v_mfma_f32_16x16x32_bf16 v[88:91], v[150:153], v[204:207], v[88:91]
	v_mfma_f32_16x16x32_bf16 v[80:83], v[142:145], v[212:215], v[80:83]
	v_mfma_f32_16x16x32_bf16 v[72:75], v[150:153], v[212:215], v[72:75]
	v_mfma_f32_16x16x32_bf16 v[116:119], v[160:163], v[176:179], v[116:119]
	v_mfma_f32_16x16x32_bf16 v[112:115], v[168:171], v[176:179], v[112:115]
	v_mfma_f32_16x16x32_bf16 v[100:103], v[160:163], v[188:191], v[100:103]
	v_mfma_f32_16x16x32_bf16 v[92:95], v[168:171], v[188:191], v[92:95]
	v_mfma_f32_16x16x32_bf16 v[84:87], v[160:163], v[200:203], v[84:87]
	v_mfma_f32_16x16x32_bf16 v[76:79], v[168:171], v[200:203], v[76:79]
	v_mfma_f32_16x16x32_bf16 v[68:71], v[160:163], v[208:211], v[68:71]
	v_mfma_f32_16x16x32_bf16 v[64:67], v[168:171], v[208:211], v[64:67]
	v_mfma_f32_16x16x32_bf16 v[116:119], v[164:167], v[180:183], v[116:119]
	v_mfma_f32_16x16x32_bf16 v[112:115], v[172:175], v[180:183], v[112:115]
	v_mfma_f32_16x16x32_bf16 v[100:103], v[164:167], v[196:199], v[100:103]
	v_mfma_f32_16x16x32_bf16 v[92:95], v[172:175], v[196:199], v[92:95]
	v_mfma_f32_16x16x32_bf16 v[84:87], v[164:167], v[204:207], v[84:87]
	v_mfma_f32_16x16x32_bf16 v[76:79], v[172:175], v[204:207], v[76:79]
	v_mfma_f32_16x16x32_bf16 v[68:71], v[164:167], v[212:215], v[68:71]
	v_mfma_f32_16x16x32_bf16 v[64:67], v[172:175], v[212:215], v[64:67]
	s_barrier
	s_add_i32 s36, s54, s41
	v_lshl_add_u64 v[216:217], v[216:217], 0, s[28:29]
	s_mov_b32 m0, s36
	ds_read_b128 v[176:179], v159 offset:49152
	ds_read_b128 v[180:183], v159 offset:50176
	ds_read_b128 v[188:191], v159 offset:51200
	ds_read_b128 v[196:199], v159 offset:52224
	ds_read_b128 v[200:203], v159 offset:53248
	ds_read_b128 v[204:207], v159 offset:54272
	ds_read_b128 v[208:211], v159 offset:55296
	ds_read_b128 v[212:215], v159 offset:56320
	global_load_lds_dwordx4 v[216:217], off
	s_add_i32 m0, s36, 0x2000
	s_add_u32 s34, s34, 0x80080
	v_lshl_add_u64 v[216:217], v[218:219], 0, s[28:29]
	s_addc_u32 s35, s35, 0
	s_add_i32 s36, s55, s41
	global_load_lds_dwordx4 v[216:217], off
	s_mov_b32 m0, s36
	v_lshl_add_u64 v[216:217], s[34:35], 0, v[184:185]
	global_load_lds_dwordx4 v[216:217], off
	s_add_i32 m0, s36, 0x2000
	v_lshl_add_u64 v[216:217], s[34:35], 0, v[136:137]
	global_load_lds_dwordx4 v[216:217], off
	s_mov_b32 m0, s45
	v_lshl_add_u64 v[216:217], v[220:221], 0, s[28:29]
	global_load_lds_dwordx4 v[216:217], off
	s_mov_b32 m0, s46
	v_lshl_add_u64 v[216:217], v[222:223], 0, s[28:29]
	global_load_lds_dwordx4 v[216:217], off
	s_waitcnt vmcnt(8) lgkmcnt(0)
	s_barrier
	v_mfma_f32_16x16x32_bf16 v[60:63], v[128:131], v[176:179], v[60:63]
	v_mfma_f32_16x16x32_bf16 v[56:59], v[146:149], v[176:179], v[56:59]
	v_mfma_f32_16x16x32_bf16 v[48:51], v[128:131], v[188:191], v[48:51]
	v_mfma_f32_16x16x32_bf16 v[40:43], v[146:149], v[188:191], v[40:43]
	v_mfma_f32_16x16x32_bf16 v[32:35], v[128:131], v[200:203], v[32:35]
	v_mfma_f32_16x16x32_bf16 v[24:27], v[146:149], v[200:203], v[24:27]
	v_mfma_f32_16x16x32_bf16 v[16:19], v[128:131], v[208:211], v[16:19]
	v_mfma_f32_16x16x32_bf16 v[8:11], v[146:149], v[208:211], v[8:11]
	v_mfma_f32_16x16x32_bf16 v[60:63], v[142:145], v[180:183], v[60:63]
	v_mfma_f32_16x16x32_bf16 v[56:59], v[150:153], v[180:183], v[56:59]
	v_mfma_f32_16x16x32_bf16 v[48:51], v[142:145], v[196:199], v[48:51]
	v_mfma_f32_16x16x32_bf16 v[40:43], v[150:153], v[196:199], v[40:43]
	v_mfma_f32_16x16x32_bf16 v[32:35], v[142:145], v[204:207], v[32:35]
	v_mfma_f32_16x16x32_bf16 v[24:27], v[150:153], v[204:207], v[24:27]
	v_mfma_f32_16x16x32_bf16 v[16:19], v[142:145], v[212:215], v[16:19]
	v_mfma_f32_16x16x32_bf16 v[8:11], v[150:153], v[212:215], v[8:11]
	v_mfma_f32_16x16x32_bf16 v[52:55], v[160:163], v[176:179], v[52:55]
	v_mfma_f32_16x16x32_bf16 v[44:47], v[168:171], v[176:179], v[44:47]
	v_mfma_f32_16x16x32_bf16 v[36:39], v[160:163], v[188:191], v[36:39]
	v_mfma_f32_16x16x32_bf16 v[28:31], v[168:171], v[188:191], v[28:31]
	v_mfma_f32_16x16x32_bf16 v[20:23], v[160:163], v[200:203], v[20:23]
	v_mfma_f32_16x16x32_bf16 v[12:15], v[168:171], v[200:203], v[12:15]
	v_mfma_f32_16x16x32_bf16 v[4:7], v[160:163], v[208:211], v[4:7]
	v_mfma_f32_16x16x32_bf16 v[0:3], v[168:171], v[208:211], v[0:3]
	v_mfma_f32_16x16x32_bf16 v[52:55], v[164:167], v[180:183], v[52:55]
	v_mfma_f32_16x16x32_bf16 v[44:47], v[172:175], v[180:183], v[44:47]
	v_mfma_f32_16x16x32_bf16 v[36:39], v[164:167], v[196:199], v[36:39]
	v_mfma_f32_16x16x32_bf16 v[28:31], v[172:175], v[196:199], v[28:31]
	v_mfma_f32_16x16x32_bf16 v[20:23], v[164:167], v[204:207], v[20:23]
	v_mfma_f32_16x16x32_bf16 v[12:15], v[172:175], v[204:207], v[12:15]
	v_mfma_f32_16x16x32_bf16 v[4:7], v[164:167], v[212:215], v[4:7]
	v_mfma_f32_16x16x32_bf16 v[0:3], v[172:175], v[212:215], v[0:3]
	s_barrier
	s_add_i32 s53, s53, 2
	s_add_u32 s30, s30, 0x100
	s_addc_u32 s31, s31, 0
	s_add_u32 s19, s19, 0x100
	s_addc_u32 s52, s52, 0
	s_cmp_gt_u32 s53, 29
	s_cbranch_scc0 .LBB0_1299
	s_and_b64 vcc, exec, s[12:13]
	s_cbranch_vccz .LBB0_1302
	s_barrier

;     DI bool next(int i, Unit& u) const { const long L = (long)i * G + c; if (L >= T.nwg) return false; T.map((int)L, u.pm, u.pn); u.seg = 0; return true; }
;     DI bool next(int i, Unit& u) const { const int ti = i / 3; const long L = (long)ti * G + c; if (L >= T.nwg) return false; T.map((int)L, u.pm, u.pn); u.seg = i - 3 * ti; return true; }
;     DI const char* aptr(const Unit& u) const { return A + (size_t)u.pm * ta + (size_t)kofs(u.seg) * 2; }
;     DI const char* bptr(const Unit& u) const { return B + (size_t)u.pn * tb + (size_t)kofs(u.seg) * 2; }
; #define PG8_STAGE(bufoff, gbase, voff) do { _Pragma("unroll") for (int _i = 0; _i < 2; ++_i) \
;         __builtin_amdgcn_global_load_lds((const unsigned*)((const char*)(gbase) + (voff)[_i]), (LAS unsigned*)(lds + (bufoff) + ldsw + _i * 8192), 16, 0, 0); } while (0)
; #define PG8_LDA(dst, b, h) do { _Pragma("unroll") for (int m = 0; m < 4; ++m) _Pragma("unroll") for (int k = 0; k < 2; ++k) dst[m][k] = *(const LAS bf16x8*)(lds + PG8_SA(b, h) + aoff + m * 2048 + k * 1024); } while (0)
; #define PG8_WAIT_V(n) asm volatile("s_waitcnt vmcnt(" #n ")" ::: "memory")
; #define PG8_WAIT_L(n) asm volatile("s_waitcnt lgkmcnt(" #n ")" ::: "memory")
; template <class Epi, class Sched>
; DI void gemm_phase(LAS unsigned char* lds, const int wv, const int lda, const int ldb, const Sched& S, const Epi& E) {
;     ...
;         const bool has_next = S.next(ui + 1, nxt);
;         const char* nA = has_next ? S.aptr(nxt) : cA; const char* nB = has_next ? S.bptr(nxt) : cB;
;         for (int t = 0; t < nt; t += 2) {
;             const bool last = (t == nt - 2);
;             const char* a1 = cA + (size_t)(t + 1) * kstep;
;             const char* a2 = last ? nA : cA + (size_t)(t + 2) * kstep; const char* b2 = last ? nB : cB + (size_t)(t + 2) * kstep;
;             const char* a3 = a2 + kstep; const char* b3 = b2 + kstep;
;             PG8_LDB(B0, 0, 0); PG8_LDB(B1, 0, 1); PG8_SCHED; PG8_LDA(At, 0, 0); PG8_STAGE(PG8_SA(1, 1), a1 + hstepA, voffA);
;             PG8_WAIT_V(8); PG8_WAIT_L(0); PG8_BAR; PG8_MMA(0, 0, At, B0); PG8_MMA(0, 1, At, B1); PG8_BAR; PG8_SCHED;
;             PG8_LDA(At, 0, 1); PG8_STAGE(PG8_SB(0, 0), b2, voffB); PG8_STAGE(PG8_SB(0, 1), b2 + hstepB, voffB); PG8_STAGE(PG8_SA(0, 0), a2, voffA);
;             PG8_WAIT_V(8); PG8_WAIT_L(0); PG8_BAR; PG8_MMA(1, 0, At, B0); PG8_MMA(1, 1, At, B1); PG8_BAR; PG8_SCHED;
.LBB0_1396:
	s_ashr_i32 s15, s14, 31
	s_lshl_b64 s[0:1], s[14:15], 20
	s_add_u32 s18, s8, s0
	s_addc_u32 s19, s9, s1
	s_and_b64 s[0:1], s[4:5], exec
	s_cselect_b32 s0, s19, s27
	s_cselect_b32 s1, s18, s26
	s_ashr_i32 s13, s12, 31
	s_lshl_b64 s[22:23], s[12:13], 20
	s_add_u32 s22, s36, s22
	s_addc_u32 s23, s37, s23
	s_and_b64 s[34:35], s[4:5], exec
	s_cselect_b32 s13, s23, s31
	s_cselect_b32 s15, s22, s30
	s_add_u32 s26, s26, 0x80080
	s_addc_u32 s27, s27, 0
	s_add_u32 s48, s30, 0x100
	s_addc_u32 s49, s31, 0
	s_mov_b32 s50, -2
	s_add_u32 s30, s26, 0xfff80080
	s_addc_u32 s31, s27, -1
	s_add_i32 s51, 0, 0x10000
	s_cmp_eq_u32 s50, 28
	s_cselect_b32 s35, s0, s31
	s_cselect_b32 s34, s1, s30
	v_add_u32_e32 v142, s51, v145
	s_cselect_b32 s31, s13, s49
	s_cselect_b32 s30, s15, s48
	s_add_i32 s54, 0, 0x14000
	ds_read_b128 v[138:141], v142
	ds_read_b128 v[148:151], v142 offset:1024
	ds_read_b128 v[152:155], v142 offset:2048
	ds_read_b128 v[156:159], v142 offset:3072
	v_add_u32_e32 v142, s54, v145
	ds_read_b128 v[160:163], v142
	ds_read_b128 v[164:167], v142 offset:1024
	ds_read_b128 v[168:171], v142 offset:2048
	ds_read_b128 v[172:175], v142 offset:3072
	v_lshl_add_u64 v[142:143], s[26:27], 0, v[134:135]
	s_add_i32 m0, s25, 0xc000
	ds_read_b128 v[176:179], v147
	ds_read_b128 v[180:183], v147 offset:1024
	ds_read_b128 v[188:191], v147 offset:2048
	ds_read_b128 v[196:199], v147 offset:3072
	ds_read_b128 v[200:203], v147 offset:4096
	ds_read_b128 v[204:207], v147 offset:5120
	ds_read_b128 v[208:211], v147 offset:6144
	ds_read_b128 v[212:215], v147 offset:7168
	global_load_lds_dwordx4 v[142:143], off
	s_add_i32 m0, s25, 0xe000
	v_lshl_add_u64 v[142:143], s[26:27], 0, v[136:137]
	global_load_lds_dwordx4 v[142:143], off
	s_waitcnt vmcnt(8) lgkmcnt(0)
	s_barrier
	v_mfma_f32_16x16x32_bf16 v[124:127], v[138:141], v[176:179], 0
	v_mfma_f32_16x16x32_bf16 v[120:123], v[152:155], v[176:179], 0
	v_mfma_f32_16x16x32_bf16 v[108:111], v[138:141], v[188:191], 0
	v_mfma_f32_16x16x32_bf16 v[104:107], v[152:155], v[188:191], 0
	v_mfma_f32_16x16x32_bf16 v[92:95], v[138:141], v[200:203], 0
	v_mfma_f32_16x16x32_bf16 v[88:91], v[152:155], v[200:203], 0
	v_mfma_f32_16x16x32_bf16 v[76:79], v[138:141], v[208:211], 0
	v_mfma_f32_16x16x32_bf16 v[72:75], v[152:155], v[208:211], 0
	v_mfma_f32_16x16x32_bf16 v[124:127], v[148:151], v[180:183], v[124:127]
	v_mfma_f32_16x16x32_bf16 v[120:123], v[156:159], v[180:183], v[120:123]
	v_mfma_f32_16x16x32_bf16 v[108:111], v[148:151], v[196:199], v[108:111]
	v_mfma_f32_16x16x32_bf16 v[104:107], v[156:159], v[196:199], v[104:107]
	v_mfma_f32_16x16x32_bf16 v[92:95], v[148:151], v[204:207], v[92:95]
	v_mfma_f32_16x16x32_bf16 v[88:91], v[156:159], v[204:207], v[88:91]
	v_mfma_f32_16x16x32_bf16 v[76:79], v[148:151], v[212:215], v[76:79]
	v_mfma_f32_16x16x32_bf16 v[72:75], v[156:159], v[212:215], v[72:75]
	v_mfma_f32_16x16x32_bf16 v[116:119], v[160:163], v[176:179], 0
	v_mfma_f32_16x16x32_bf16 v[112:115], v[168:171], v[176:179], 0
	v_mfma_f32_16x16x32_bf16 v[100:103], v[160:163], v[188:191], 0
	v_mfma_f32_16x16x32_bf16 v[96:99], v[168:171], v[188:191], 0
	v_mfma_f32_16x16x32_bf16 v[84:87], v[160:163], v[200:203], 0
	v_mfma_f32_16x16x32_bf16 v[80:83], v[168:171], v[200:203], 0
	v_mfma_f32_16x16x32_bf16 v[68:71], v[160:163], v[208:211], 0
	v_mfma_f32_16x16x32_bf16 v[64:67], v[168:171], v[208:211], 0
	v_mfma_f32_16x16x32_bf16 v[116:119], v[164:167], v[180:183], v[116:119]
	v_mfma_f32_16x16x32_bf16 v[112:115], v[172:175], v[180:183], v[112:115]
	v_mfma_f32_16x16x32_bf16 v[100:103], v[164:167], v[196:199], v[100:103]
	v_mfma_f32_16x16x32_bf16 v[96:99], v[172:175], v[196:199], v[96:99]
	v_mfma_f32_16x16x32_bf16 v[84:87], v[164:167], v[204:207], v[84:87]
	v_mfma_f32_16x16x32_bf16 v[80:83], v[172:175], v[204:207], v[80:83]
	v_mfma_f32_16x16x32_bf16 v[68:71], v[164:167], v[212:215], v[68:71]
	v_mfma_f32_16x16x32_bf16 v[64:67], v[172:175], v[212:215], v[64:67]
	s_barrier
	s_add_i32 s51, s51, s38
	v_lshl_add_u64 v[142:143], s[30:31], 0, v[184:185]
	s_mov_b32 m0, s51
	ds_read_b128 v[176:179], v147 offset:16384
	ds_read_b128 v[180:183], v147 offset:17408
	ds_read_b128 v[188:191], v147 offset:18432
	ds_read_b128 v[196:199], v147 offset:19456
	ds_read_b128 v[200:203], v147 offset:20480
	ds_read_b128 v[204:207], v147 offset:21504
	ds_read_b128 v[208:211], v147 offset:22528
	ds_read_b128 v[212:215], v147 offset:23552
	global_load_lds_dwordx4 v[142:143], off
	s_add_i32 m0, s51, 0x2000
	s_add_u32 s52, s30, 0x80000
	v_lshl_add_u64 v[216:217], s[30:31], 0, v[132:133]
	s_addc_u32 s53, s31, 0
	s_add_i32 s51, s54, s38
	global_load_lds_dwordx4 v[216:217], off
	v_lshl_add_u64 v[218:219], s[52:53], 0, v[184:185]
	s_mov_b32 m0, s51
	v_lshl_add_u64 v[220:221], s[34:35], 0, v[130:131]
	global_load_lds_dwordx4 v[218:219], off
	s_add_i32 m0, s51, 0x2000
	v_lshl_add_u64 v[218:219], s[52:53], 0, v[132:133]
	global_load_lds_dwordx4 v[218:219], off
	s_mov_b32 m0, s25
	v_lshl_add_u64 v[218:219], s[34:35], 0, v[128:129]
	global_load_lds_dwordx4 v[218:219], off
	s_mov_b32 m0, s39
	s_nop 0
	global_load_lds_dwordx4 v[220:221], off
	s_waitcnt vmcnt(8) lgkmcnt(0)
	s_barrier
; #define PG8_STAGE(bufoff, gbase, voff) do { _Pragma("unroll") for (int _i = 0; _i < 2; ++_i) \
;         __builtin_amdgcn_global_load_lds((const unsigned*)((const char*)(gbase) + (voff)[_i]), (LAS unsigned*)(lds + (bufoff) + ldsw + _i * 8192), 16, 0, 0); } while (0)
; #define PG8_LDA(dst, b, h) do { _Pragma("unroll") for (int m = 0; m < 4; ++m) _Pragma("unroll") for (int k = 0; k < 2; ++k) dst[m][k] = *(const LAS bf16x8*)(lds + PG8_SA(b, h) + aoff + m * 2048 + k * 1024); } while (0)
; #define PG8_LDB(dst, b, h) do { _Pragma("unroll") for (int n = 0; n < 2; ++n) _Pragma("unroll") for (int k = 0; k < 2; ++k) dst[n][k] = *(const LAS bf16x8*)(lds + PG8_SB(b, h) + boff + n * 2048 + k * 1024); } while (0)
; #define PG8_MMA(ai, bj, At, Bt) do { __builtin_amdgcn_s_setprio(1); _Pragma("unroll") for (int m = 0; m < 4; ++m) _Pragma("unroll") for (int n = 0; n < 2; ++n) _Pragma("unroll") for (int k = 0; k < 2; ++k) \
;         acc[ai][bj][m][n] = __builtin_amdgcn_mfma_f32_16x16x32_bf16(Bt[n][k], At[m][k], acc[ai][bj][m][n], 0, 0, 0); __builtin_amdgcn_s_setprio(0); } while (0)
; #define PG8_WAIT_V(n) asm volatile("s_waitcnt vmcnt(" #n ")" ::: "memory")
; #define PG8_WAIT_L(n) asm volatile("s_waitcnt lgkmcnt(" #n ")" ::: "memory")
; #define PG8_BAR __builtin_amdgcn_s_barrier()
; #define PG8_SCHED __builtin_amdgcn_sched_barrier(0)
; template <class Epi, class Sched>
; DI void gemm_phase(LAS unsigned char* lds, const int wv, const int lda, const int ldb, const Sched& S, const Epi& E) {
;     ...
;             PG8_WAIT_V(8); PG8_WAIT_L(0); PG8_BAR; PG8_MMA(1, 0, At, B0); PG8_MMA(1, 1, At, B1); PG8_BAR; PG8_SCHED;
;             PG8_LDB(B0, 1, 0); PG8_LDB(B1, 1, 1); PG8_SCHED; PG8_LDA(At, 1, 0); PG8_STAGE(PG8_SA(0, 1), a2 + hstepA, voffA);
;             PG8_WAIT_V(8); PG8_WAIT_L(0); PG8_BAR; PG8_MMA(0, 0, At, B0); PG8_MMA(0, 1, At, B1); PG8_BAR; PG8_SCHED;
	v_mfma_f32_16x16x32_bf16 v[60:63], v[138:141], v[176:179], 0
	v_mfma_f32_16x16x32_bf16 v[56:59], v[152:155], v[176:179], 0
	v_mfma_f32_16x16x32_bf16 v[44:47], v[138:141], v[188:191], 0
	v_mfma_f32_16x16x32_bf16 v[40:43], v[152:155], v[188:191], 0
	v_mfma_f32_16x16x32_bf16 v[28:31], v[138:141], v[200:203], 0
	v_mfma_f32_16x16x32_bf16 v[24:27], v[152:155], v[200:203], 0
	v_mfma_f32_16x16x32_bf16 v[12:15], v[138:141], v[208:211], 0
	v_mfma_f32_16x16x32_bf16 v[8:11], v[152:155], v[208:211], 0
	v_mfma_f32_16x16x32_bf16 v[60:63], v[148:151], v[180:183], v[60:63]
	v_mfma_f32_16x16x32_bf16 v[56:59], v[156:159], v[180:183], v[56:59]
	v_mfma_f32_16x16x32_bf16 v[44:47], v[148:151], v[196:199], v[44:47]
	v_mfma_f32_16x16x32_bf16 v[40:43], v[156:159], v[196:199], v[40:43]
	v_mfma_f32_16x16x32_bf16 v[28:31], v[148:151], v[204:207], v[28:31]
	v_mfma_f32_16x16x32_bf16 v[24:27], v[156:159], v[204:207], v[24:27]
	v_mfma_f32_16x16x32_bf16 v[12:15], v[148:151], v[212:215], v[12:15]
	v_mfma_f32_16x16x32_bf16 v[8:11], v[156:159], v[212:215], v[8:11]
	v_mfma_f32_16x16x32_bf16 v[52:55], v[160:163], v[176:179], 0
	v_mfma_f32_16x16x32_bf16 v[48:51], v[168:171], v[176:179], 0
	v_mfma_f32_16x16x32_bf16 v[36:39], v[160:163], v[188:191], 0
	v_mfma_f32_16x16x32_bf16 v[32:35], v[168:171], v[188:191], 0
	v_mfma_f32_16x16x32_bf16 v[20:23], v[160:163], v[200:203], 0
	v_mfma_f32_16x16x32_bf16 v[16:19], v[168:171], v[200:203], 0
	v_mfma_f32_16x16x32_bf16 v[4:7], v[160:163], v[208:211], 0
	v_mfma_f32_16x16x32_bf16 v[0:3], v[168:171], v[208:211], 0
	v_mfma_f32_16x16x32_bf16 v[52:55], v[164:167], v[180:183], v[52:55]
	v_mfma_f32_16x16x32_bf16 v[48:51], v[172:175], v[180:183], v[48:51]
	v_mfma_f32_16x16x32_bf16 v[36:39], v[164:167], v[196:199], v[36:39]
	v_mfma_f32_16x16x32_bf16 v[32:35], v[172:175], v[196:199], v[32:35]
	v_mfma_f32_16x16x32_bf16 v[20:23], v[164:167], v[204:207], v[20:23]
	v_mfma_f32_16x16x32_bf16 v[16:19], v[172:175], v[204:207], v[16:19]
	v_mfma_f32_16x16x32_bf16 v[4:7], v[164:167], v[212:215], v[4:7]
	v_mfma_f32_16x16x32_bf16 v[0:3], v[172:175], v[212:215], v[0:3]
	s_barrier
	s_add_i32 s51, 0, 0x18000
	s_add_i32 s52, 0, 0x1c000
	v_add_u32_e32 v156, s51, v145
	v_add_u32_e32 v172, s52, v145
	ds_read_b128 v[138:141], v156
	ds_read_b128 v[148:151], v156 offset:1024
	ds_read_b128 v[152:155], v156 offset:2048
	ds_read_b128 v[156:159], v156 offset:3072
	ds_read_b128 v[160:163], v172
	ds_read_b128 v[164:167], v172 offset:1024
	ds_read_b128 v[168:171], v172 offset:2048
	ds_read_b128 v[172:175], v172 offset:3072
	s_add_u32 s34, s34, 0x80000
	s_addc_u32 s35, s35, 0
	s_mov_b32 m0, s40
	v_lshl_add_u64 v[222:223], s[34:35], 0, v[128:129]
	ds_read_b128 v[176:179], v147 offset:32768
	ds_read_b128 v[180:183], v147 offset:33792
	ds_read_b128 v[188:191], v147 offset:34816
	ds_read_b128 v[196:199], v147 offset:35840
	ds_read_b128 v[200:203], v147 offset:36864
	ds_read_b128 v[204:207], v147 offset:37888
	ds_read_b128 v[208:211], v147 offset:38912
	ds_read_b128 v[212:215], v147 offset:39936
	global_load_lds_dwordx4 v[222:223], off
	s_mov_b32 m0, s41
	v_lshl_add_u64 v[222:223], s[34:35], 0, v[130:131]
	global_load_lds_dwordx4 v[222:223], off
	s_waitcnt vmcnt(8) lgkmcnt(0)
	s_barrier
	v_mfma_f32_16x16x32_bf16 v[124:127], v[138:141], v[176:179], v[124:127]
	v_mfma_f32_16x16x32_bf16 v[120:123], v[152:155], v[176:179], v[120:123]
	v_mfma_f32_16x16x32_bf16 v[108:111], v[138:141], v[188:191], v[108:111]
	v_mfma_f32_16x16x32_bf16 v[104:107], v[152:155], v[188:191], v[104:107]
	v_mfma_f32_16x16x32_bf16 v[92:95], v[138:141], v[200:203], v[92:95]
	v_mfma_f32_16x16x32_bf16 v[88:91], v[152:155], v[200:203], v[88:91]
	v_mfma_f32_16x16x32_bf16 v[76:79], v[138:141], v[208:211], v[76:79]
	v_mfma_f32_16x16x32_bf16 v[72:75], v[152:155], v[208:211], v[72:75]
	v_mfma_f32_16x16x32_bf16 v[124:127], v[148:151], v[180:183], v[124:127]
	v_mfma_f32_16x16x32_bf16 v[120:123], v[156:159], v[180:183], v[120:123]
	v_mfma_f32_16x16x32_bf16 v[108:111], v[148:151], v[196:199], v[108:111]
	v_mfma_f32_16x16x32_bf16 v[104:107], v[156:159], v[196:199], v[104:107]
	v_mfma_f32_16x16x32_bf16 v[92:95], v[148:151], v[204:207], v[92:95]
	v_mfma_f32_16x16x32_bf16 v[88:91], v[156:159], v[204:207], v[88:91]
	v_mfma_f32_16x16x32_bf16 v[76:79], v[148:151], v[212:215], v[76:79]
	v_mfma_f32_16x16x32_bf16 v[72:75], v[156:159], v[212:215], v[72:75]
	v_mfma_f32_16x16x32_bf16 v[116:119], v[160:163], v[176:179], v[116:119]
	v_mfma_f32_16x16x32_bf16 v[112:115], v[168:171], v[176:179], v[112:115]
	v_mfma_f32_16x16x32_bf16 v[100:103], v[160:163], v[188:191], v[100:103]
	v_mfma_f32_16x16x32_bf16 v[96:99], v[168:171], v[188:191], v[96:99]
	v_mfma_f32_16x16x32_bf16 v[84:87], v[160:163], v[200:203], v[84:87]
	v_mfma_f32_16x16x32_bf16 v[80:83], v[168:171], v[200:203], v[80:83]
	v_mfma_f32_16x16x32_bf16 v[68:71], v[160:163], v[208:211], v[68:71]
	v_mfma_f32_16x16x32_bf16 v[64:67], v[168:171], v[208:211], v[64:67]
	v_mfma_f32_16x16x32_bf16 v[116:119], v[164:167], v[180:183], v[116:119]
	v_mfma_f32_16x16x32_bf16 v[112:115], v[172:175], v[180:183], v[112:115]
	v_mfma_f32_16x16x32_bf16 v[100:103], v[164:167], v[196:199], v[100:103]
	v_mfma_f32_16x16x32_bf16 v[96:99], v[172:175], v[196:199], v[96:99]
	v_mfma_f32_16x16x32_bf16 v[84:87], v[164:167], v[204:207], v[84:87]
	v_mfma_f32_16x16x32_bf16 v[80:83], v[172:175], v[204:207], v[80:83]
	v_mfma_f32_16x16x32_bf16 v[68:71], v[164:167], v[212:215], v[68:71]
	v_mfma_f32_16x16x32_bf16 v[64:67], v[172:175], v[212:215], v[64:67]
	s_barrier
; #define PG8_STAGE(bufoff, gbase, voff) do { _Pragma("unroll") for (int _i = 0; _i < 2; ++_i) \
;         __builtin_amdgcn_global_load_lds((const unsigned*)((const char*)(gbase) + (voff)[_i]), (LAS unsigned*)(lds + (bufoff) + ldsw + _i * 8192), 16, 0, 0); } while (0)
; #define PG8_LDA(dst, b, h) do { _Pragma("unroll") for (int m = 0; m < 4; ++m) _Pragma("unroll") for (int k = 0; k < 2; ++k) dst[m][k] = *(const LAS bf16x8*)(lds + PG8_SA(b, h) + aoff + m * 2048 + k * 1024); } while (0)
; #define PG8_LDB(dst, b, h) do { _Pragma("unroll") for (int n = 0; n < 2; ++n) _Pragma("unroll") for (int k = 0; k < 2; ++k) dst[n][k] = *(const LAS bf16x8*)(lds + PG8_SB(b, h) + boff + n * 2048 + k * 1024); } while (0)
; #define PG8_MMA(ai, bj, At, Bt) do { __builtin_amdgcn_s_setprio(1); _Pragma("unroll") for (int m = 0; m < 4; ++m) _Pragma("unroll") for (int n = 0; n < 2; ++n) _Pragma("unroll") for (int k = 0; k < 2; ++k) \
;         acc[ai][bj][m][n] = __builtin_amdgcn_mfma_f32_16x16x32_bf16(Bt[n][k], At[m][k], acc[ai][bj][m][n], 0, 0, 0); __builtin_amdgcn_s_setprio(0); } while (0)
; #define PG8_WAIT_V(n) asm volatile("s_waitcnt vmcnt(" #n ")" ::: "memory")
; #define PG8_WAIT_L(n) asm volatile("s_waitcnt lgkmcnt(" #n ")" ::: "memory")
; #define PG8_BAR __builtin_amdgcn_s_barrier()
; #define PG8_SCHED __builtin_amdgcn_sched_barrier(0)
; template <class Epi, class Sched>
; DI void gemm_phase(LAS unsigned char* lds, const int wv, const int lda, const int ldb, const Sched& S, const Epi& E) {
;     ...
;         for (int t = 0; t < nt; t += 2) {
;             const bool last = (t == nt - 2);
;             const char* a1 = cA + (size_t)(t + 1) * kstep;
;             const char* a2 = last ? nA : cA + (size_t)(t + 2) * kstep; const char* b2 = last ? nB : cB + (size_t)(t + 2) * kstep;
;             const char* a3 = a2 + kstep; const char* b3 = b2 + kstep;
;             PG8_LDB(B0, 0, 0); PG8_LDB(B1, 0, 1); PG8_SCHED; PG8_LDA(At, 0, 0); PG8_STAGE(PG8_SA(1, 1), a1 + hstepA, voffA);
;             PG8_WAIT_V(8); PG8_WAIT_L(0); PG8_BAR; PG8_MMA(0, 0, At, B0); PG8_MMA(0, 1, At, B1); PG8_BAR; PG8_SCHED;
;     ...
;             PG8_LDA(At, 1, 1); PG8_STAGE(PG8_SB(1, 0), b3, voffB); PG8_STAGE(PG8_SB(1, 1), b3 + hstepB, voffB); PG8_STAGE(PG8_SA(1, 0), a3, voffA);
;             PG8_WAIT_V(8); PG8_WAIT_L(0); PG8_BAR; PG8_MMA(1, 0, At, B0); PG8_MMA(1, 1, At, B1); PG8_BAR; PG8_SCHED;
	s_add_i32 s34, s51, s38
	v_lshl_add_u64 v[142:143], v[142:143], 0, s[28:29]
	s_mov_b32 m0, s34
	ds_read_b128 v[176:179], v147 offset:49152
	ds_read_b128 v[180:183], v147 offset:50176
	ds_read_b128 v[188:191], v147 offset:51200
	ds_read_b128 v[196:199], v147 offset:52224
	ds_read_b128 v[200:203], v147 offset:53248
	ds_read_b128 v[204:207], v147 offset:54272
	ds_read_b128 v[208:211], v147 offset:55296
	ds_read_b128 v[212:215], v147 offset:56320
	global_load_lds_dwordx4 v[142:143], off
	s_add_i32 m0, s34, 0x2000
	s_add_u32 s30, s30, 0x80080
	v_lshl_add_u64 v[142:143], v[216:217], 0, s[28:29]
	s_addc_u32 s31, s31, 0
	s_add_i32 s34, s52, s38
	global_load_lds_dwordx4 v[142:143], off
	s_mov_b32 m0, s34
	v_lshl_add_u64 v[142:143], s[30:31], 0, v[184:185]
	global_load_lds_dwordx4 v[142:143], off
	s_add_i32 m0, s34, 0x2000
	v_lshl_add_u64 v[142:143], s[30:31], 0, v[132:133]
	global_load_lds_dwordx4 v[142:143], off
	s_mov_b32 m0, s43
	v_lshl_add_u64 v[142:143], v[218:219], 0, s[28:29]
	global_load_lds_dwordx4 v[142:143], off
	s_mov_b32 m0, s44
	v_lshl_add_u64 v[142:143], v[220:221], 0, s[28:29]
	global_load_lds_dwordx4 v[142:143], off
	s_waitcnt vmcnt(8) lgkmcnt(0)
	s_barrier
	v_mfma_f32_16x16x32_bf16 v[60:63], v[138:141], v[176:179], v[60:63]
	v_mfma_f32_16x16x32_bf16 v[56:59], v[152:155], v[176:179], v[56:59]
	v_mfma_f32_16x16x32_bf16 v[44:47], v[138:141], v[188:191], v[44:47]
	v_mfma_f32_16x16x32_bf16 v[40:43], v[152:155], v[188:191], v[40:43]
	v_mfma_f32_16x16x32_bf16 v[28:31], v[138:141], v[200:203], v[28:31]
	v_mfma_f32_16x16x32_bf16 v[24:27], v[152:155], v[200:203], v[24:27]
	v_mfma_f32_16x16x32_bf16 v[12:15], v[138:141], v[208:211], v[12:15]
	v_mfma_f32_16x16x32_bf16 v[8:11], v[152:155], v[208:211], v[8:11]
	v_mfma_f32_16x16x32_bf16 v[60:63], v[148:151], v[180:183], v[60:63]
	v_mfma_f32_16x16x32_bf16 v[56:59], v[156:159], v[180:183], v[56:59]
	v_mfma_f32_16x16x32_bf16 v[44:47], v[148:151], v[196:199], v[44:47]
	v_mfma_f32_16x16x32_bf16 v[40:43], v[156:159], v[196:199], v[40:43]
	v_mfma_f32_16x16x32_bf16 v[28:31], v[148:151], v[204:207], v[28:31]
	v_mfma_f32_16x16x32_bf16 v[24:27], v[156:159], v[204:207], v[24:27]
	v_mfma_f32_16x16x32_bf16 v[12:15], v[148:151], v[212:215], v[12:15]
	v_mfma_f32_16x16x32_bf16 v[8:11], v[156:159], v[212:215], v[8:11]
	v_mfma_f32_16x16x32_bf16 v[52:55], v[160:163], v[176:179], v[52:55]
	v_mfma_f32_16x16x32_bf16 v[48:51], v[168:171], v[176:179], v[48:51]
	v_mfma_f32_16x16x32_bf16 v[36:39], v[160:163], v[188:191], v[36:39]
	v_mfma_f32_16x16x32_bf16 v[32:35], v[168:171], v[188:191], v[32:35]
	v_mfma_f32_16x16x32_bf16 v[20:23], v[160:163], v[200:203], v[20:23]
	v_mfma_f32_16x16x32_bf16 v[16:19], v[168:171], v[200:203], v[16:19]
	v_mfma_f32_16x16x32_bf16 v[4:7], v[160:163], v[208:211], v[4:7]
	v_mfma_f32_16x16x32_bf16 v[0:3], v[168:171], v[208:211], v[0:3]
	v_mfma_f32_16x16x32_bf16 v[52:55], v[164:167], v[180:183], v[52:55]
	v_mfma_f32_16x16x32_bf16 v[48:51], v[172:175], v[180:183], v[48:51]
	v_mfma_f32_16x16x32_bf16 v[36:39], v[164:167], v[196:199], v[36:39]
	v_mfma_f32_16x16x32_bf16 v[32:35], v[172:175], v[196:199], v[32:35]
	v_mfma_f32_16x16x32_bf16 v[20:23], v[164:167], v[204:207], v[20:23]
	v_mfma_f32_16x16x32_bf16 v[16:19], v[172:175], v[204:207], v[16:19]
	v_mfma_f32_16x16x32_bf16 v[4:7], v[164:167], v[212:215], v[4:7]
	v_mfma_f32_16x16x32_bf16 v[0:3], v[172:175], v[212:215], v[0:3]
	s_barrier
	s_add_i32 s50, s50, 2
	s_add_u32 s26, s26, 0x100
	s_addc_u32 s27, s27, 0
	s_add_u32 s48, s48, 0x100
	s_addc_u32 s49, s49, 0
.LBB0_1397:
	s_add_u32 s30, s26, 0xfff80080
	s_addc_u32 s31, s27, -1
	s_add_i32 s51, 0, 0x10000
	s_cmp_eq_u32 s50, 28
	s_cselect_b32 s35, s0, s31
	s_cselect_b32 s34, s1, s30
	v_add_u32_e32 v142, s51, v145
	s_cselect_b32 s31, s13, s49
	s_cselect_b32 s30, s15, s48
	s_add_i32 s54, 0, 0x14000
	ds_read_b128 v[138:141], v142
	ds_read_b128 v[148:151], v142 offset:1024
	ds_read_b128 v[152:155], v142 offset:2048
	ds_read_b128 v[156:159], v142 offset:3072
	v_add_u32_e32 v142, s54, v145
	ds_read_b128 v[160:163], v142
	ds_read_b128 v[164:167], v142 offset:1024
	ds_read_b128 v[168:171], v142 offset:2048
	ds_read_b128 v[172:175], v142 offset:3072
	v_lshl_add_u64 v[142:143], s[26:27], 0, v[134:135]
	s_add_i32 m0, s25, 0xc000
	ds_read_b128 v[176:179], v147
	ds_read_b128 v[180:183], v147 offset:1024
	ds_read_b128 v[188:191], v147 offset:2048
	ds_read_b128 v[196:199], v147 offset:3072
	ds_read_b128 v[200:203], v147 offset:4096
	ds_read_b128 v[204:207], v147 offset:5120
	ds_read_b128 v[208:211], v147 offset:6144
	ds_read_b128 v[212:215], v147 offset:7168
	global_load_lds_dwordx4 v[142:143], off
	s_add_i32 m0, s25, 0xe000
	v_lshl_add_u64 v[142:143], s[26:27], 0, v[136:137]
	global_load_lds_dwordx4 v[142:143], off
	s_waitcnt vmcnt(8) lgkmcnt(0)
	s_barrier
; #define PG8_STAGE(bufoff, gbase, voff) do { _Pragma("unroll") for (int _i = 0; _i < 2; ++_i) \
;         __builtin_amdgcn_global_load_lds((const unsigned*)((const char*)(gbase) + (voff)[_i]), (LAS unsigned*)(lds + (bufoff) + ldsw + _i * 8192), 16, 0, 0); } while (0)
; #define PG8_LDA(dst, b, h) do { _Pragma("unroll") for (int m = 0; m < 4; ++m) _Pragma("unroll") for (int k = 0; k < 2; ++k) dst[m][k] = *(const LAS bf16x8*)(lds + PG8_SA(b, h) + aoff + m * 2048 + k * 1024); } while (0)
; #define PG8_MMA(ai, bj, At, Bt) do { __builtin_amdgcn_s_setprio(1); _Pragma("unroll") for (int m = 0; m < 4; ++m) _Pragma("unroll") for (int n = 0; n < 2; ++n) _Pragma("unroll") for (int k = 0; k < 2; ++k) \
;         acc[ai][bj][m][n] = __builtin_amdgcn_mfma_f32_16x16x32_bf16(Bt[n][k], At[m][k], acc[ai][bj][m][n], 0, 0, 0); __builtin_amdgcn_s_setprio(0); } while (0)
; #define PG8_WAIT_V(n) asm volatile("s_waitcnt vmcnt(" #n ")" ::: "memory")
; #define PG8_WAIT_L(n) asm volatile("s_waitcnt lgkmcnt(" #n ")" ::: "memory")
; #define PG8_BAR __builtin_amdgcn_s_barrier()
; #define PG8_SCHED __builtin_amdgcn_sched_barrier(0)
; template <class Epi, class Sched>
; DI void gemm_phase(LAS unsigned char* lds, const int wv, const int lda, const int ldb, const Sched& S, const Epi& E) {
;     ...
;             PG8_WAIT_V(8); PG8_WAIT_L(0); PG8_BAR; PG8_MMA(0, 0, At, B0); PG8_MMA(0, 1, At, B1); PG8_BAR; PG8_SCHED;
;             PG8_LDA(At, 0, 1); PG8_STAGE(PG8_SB(0, 0), b2, voffB); PG8_STAGE(PG8_SB(0, 1), b2 + hstepB, voffB); PG8_STAGE(PG8_SA(0, 0), a2, voffA);
;             PG8_WAIT_V(8); PG8_WAIT_L(0); PG8_BAR; PG8_MMA(1, 0, At, B0); PG8_MMA(1, 1, At, B1); PG8_BAR; PG8_SCHED;
	v_mfma_f32_16x16x32_bf16 v[124:127], v[138:141], v[176:179], v[124:127]
	v_mfma_f32_16x16x32_bf16 v[120:123], v[152:155], v[176:179], v[120:123]
	v_mfma_f32_16x16x32_bf16 v[108:111], v[138:141], v[188:191], v[108:111]
	v_mfma_f32_16x16x32_bf16 v[104:107], v[152:155], v[188:191], v[104:107]
	v_mfma_f32_16x16x32_bf16 v[92:95], v[138:141], v[200:203], v[92:95]
	v_mfma_f32_16x16x32_bf16 v[88:91], v[152:155], v[200:203], v[88:91]
	v_mfma_f32_16x16x32_bf16 v[76:79], v[138:141], v[208:211], v[76:79]
	v_mfma_f32_16x16x32_bf16 v[72:75], v[152:155], v[208:211], v[72:75]
	v_mfma_f32_16x16x32_bf16 v[124:127], v[148:151], v[180:183], v[124:127]
	v_mfma_f32_16x16x32_bf16 v[120:123], v[156:159], v[180:183], v[120:123]
	v_mfma_f32_16x16x32_bf16 v[108:111], v[148:151], v[196:199], v[108:111]
	v_mfma_f32_16x16x32_bf16 v[104:107], v[156:159], v[196:199], v[104:107]
	v_mfma_f32_16x16x32_bf16 v[92:95], v[148:151], v[204:207], v[92:95]
	v_mfma_f32_16x16x32_bf16 v[88:91], v[156:159], v[204:207], v[88:91]
	v_mfma_f32_16x16x32_bf16 v[76:79], v[148:151], v[212:215], v[76:79]
	v_mfma_f32_16x16x32_bf16 v[72:75], v[156:159], v[212:215], v[72:75]
	v_mfma_f32_16x16x32_bf16 v[116:119], v[160:163], v[176:179], v[116:119]
	v_mfma_f32_16x16x32_bf16 v[112:115], v[168:171], v[176:179], v[112:115]
	v_mfma_f32_16x16x32_bf16 v[100:103], v[160:163], v[188:191], v[100:103]
	v_mfma_f32_16x16x32_bf16 v[96:99], v[168:171], v[188:191], v[96:99]
	v_mfma_f32_16x16x32_bf16 v[84:87], v[160:163], v[200:203], v[84:87]
	v_mfma_f32_16x16x32_bf16 v[80:83], v[168:171], v[200:203], v[80:83]
	v_mfma_f32_16x16x32_bf16 v[68:71], v[160:163], v[208:211], v[68:71]
	v_mfma_f32_16x16x32_bf16 v[64:67], v[168:171], v[208:211], v[64:67]
	v_mfma_f32_16x16x32_bf16 v[116:119], v[164:167], v[180:183], v[116:119]
	v_mfma_f32_16x16x32_bf16 v[112:115], v[172:175], v[180:183], v[112:115]
	v_mfma_f32_16x16x32_bf16 v[100:103], v[164:167], v[196:199], v[100:103]
	v_mfma_f32_16x16x32_bf16 v[96:99], v[172:175], v[196:199], v[96:99]
	v_mfma_f32_16x16x32_bf16 v[84:87], v[164:167], v[204:207], v[84:87]
	v_mfma_f32_16x16x32_bf16 v[80:83], v[172:175], v[204:207], v[80:83]
	v_mfma_f32_16x16x32_bf16 v[68:71], v[164:167], v[212:215], v[68:71]
	v_mfma_f32_16x16x32_bf16 v[64:67], v[172:175], v[212:215], v[64:67]
	s_barrier
	s_add_i32 s51, s51, s38
	v_lshl_add_u64 v[142:143], s[30:31], 0, v[184:185]
	s_mov_b32 m0, s51
	ds_read_b128 v[176:179], v147 offset:16384
	ds_read_b128 v[180:183], v147 offset:17408
	ds_read_b128 v[188:191], v147 offset:18432
	ds_read_b128 v[196:199], v147 offset:19456
	ds_read_b128 v[200:203], v147 offset:20480
	ds_read_b128 v[204:207], v147 offset:21504
	ds_read_b128 v[208:211], v147 offset:22528
	ds_read_b128 v[212:215], v147 offset:23552
	global_load_lds_dwordx4 v[142:143], off
	s_add_i32 m0, s51, 0x2000
	s_add_u32 s52, s30, 0x80000
	v_lshl_add_u64 v[216:217], s[30:31], 0, v[132:133]
	s_addc_u32 s53, s31, 0
	s_add_i32 s51, s54, s38
	global_load_lds_dwordx4 v[216:217], off
	v_lshl_add_u64 v[218:219], s[52:53], 0, v[184:185]
	s_mov_b32 m0, s51
	v_lshl_add_u64 v[220:221], s[34:35], 0, v[130:131]
	global_load_lds_dwordx4 v[218:219], off
	s_add_i32 m0, s51, 0x2000
	v_lshl_add_u64 v[218:219], s[52:53], 0, v[132:133]
	global_load_lds_dwordx4 v[218:219], off
	s_mov_b32 m0, s25
	v_lshl_add_u64 v[218:219], s[34:35], 0, v[128:129]
	global_load_lds_dwordx4 v[218:219], off
	s_mov_b32 m0, s39
	s_nop 0
	global_load_lds_dwordx4 v[220:221], off
	s_waitcnt vmcnt(8) lgkmcnt(0)
	s_barrier
	v_mfma_f32_16x16x32_bf16 v[60:63], v[138:141], v[176:179], v[60:63]
	v_mfma_f32_16x16x32_bf16 v[56:59], v[152:155], v[176:179], v[56:59]
	v_mfma_f32_16x16x32_bf16 v[44:47], v[138:141], v[188:191], v[44:47]
	v_mfma_f32_16x16x32_bf16 v[40:43], v[152:155], v[188:191], v[40:43]
	v_mfma_f32_16x16x32_bf16 v[28:31], v[138:141], v[200:203], v[28:31]
	v_mfma_f32_16x16x32_bf16 v[24:27], v[152:155], v[200:203], v[24:27]
	v_mfma_f32_16x16x32_bf16 v[12:15], v[138:141], v[208:211], v[12:15]
	v_mfma_f32_16x16x32_bf16 v[8:11], v[152:155], v[208:211], v[8:11]
	v_mfma_f32_16x16x32_bf16 v[60:63], v[148:151], v[180:183], v[60:63]
	v_mfma_f32_16x16x32_bf16 v[56:59], v[156:159], v[180:183], v[56:59]
	v_mfma_f32_16x16x32_bf16 v[44:47], v[148:151], v[196:199], v[44:47]
	v_mfma_f32_16x16x32_bf16 v[40:43], v[156:159], v[196:199], v[40:43]
	v_mfma_f32_16x16x32_bf16 v[28:31], v[148:151], v[204:207], v[28:31]
	v_mfma_f32_16x16x32_bf16 v[24:27], v[156:159], v[204:207], v[24:27]
	v_mfma_f32_16x16x32_bf16 v[12:15], v[148:151], v[212:215], v[12:15]
	v_mfma_f32_16x16x32_bf16 v[8:11], v[156:159], v[212:215], v[8:11]
	v_mfma_f32_16x16x32_bf16 v[52:55], v[160:163], v[176:179], v[52:55]
	v_mfma_f32_16x16x32_bf16 v[48:51], v[168:171], v[176:179], v[48:51]
	v_mfma_f32_16x16x32_bf16 v[36:39], v[160:163], v[188:191], v[36:39]
	v_mfma_f32_16x16x32_bf16 v[32:35], v[168:171], v[188:191], v[32:35]
	v_mfma_f32_16x16x32_bf16 v[20:23], v[160:163], v[200:203], v[20:23]
	v_mfma_f32_16x16x32_bf16 v[16:19], v[168:171], v[200:203], v[16:19]
	v_mfma_f32_16x16x32_bf16 v[4:7], v[160:163], v[208:211], v[4:7]
	v_mfma_f32_16x16x32_bf16 v[0:3], v[168:171], v[208:211], v[0:3]
	v_mfma_f32_16x16x32_bf16 v[52:55], v[164:167], v[180:183], v[52:55]
	v_mfma_f32_16x16x32_bf16 v[48:51], v[172:175], v[180:183], v[48:51]
	v_mfma_f32_16x16x32_bf16 v[36:39], v[164:167], v[196:199], v[36:39]
	v_mfma_f32_16x16x32_bf16 v[32:35], v[172:175], v[196:199], v[32:35]
	v_mfma_f32_16x16x32_bf16 v[20:23], v[164:167], v[204:207], v[20:23]
	v_mfma_f32_16x16x32_bf16 v[16:19], v[172:175], v[204:207], v[16:19]
	v_mfma_f32_16x16x32_bf16 v[4:7], v[164:167], v[212:215], v[4:7]
	v_mfma_f32_16x16x32_bf16 v[0:3], v[172:175], v[212:215], v[0:3]
	s_barrier
; #define PG8_STAGE(bufoff, gbase, voff) do { _Pragma("unroll") for (int _i = 0; _i < 2; ++_i) \
;         __builtin_amdgcn_global_load_lds((const unsigned*)((const char*)(gbase) + (voff)[_i]), (LAS unsigned*)(lds + (bufoff) + ldsw + _i * 8192), 16, 0, 0); } while (0)
; #define PG8_LDA(dst, b, h) do { _Pragma("unroll") for (int m = 0; m < 4; ++m) _Pragma("unroll") for (int k = 0; k < 2; ++k) dst[m][k] = *(const LAS bf16x8*)(lds + PG8_SA(b, h) + aoff + m * 2048 + k * 1024); } while (0)
; #define PG8_LDB(dst, b, h) do { _Pragma("unroll") for (int n = 0; n < 2; ++n) _Pragma("unroll") for (int k = 0; k < 2; ++k) dst[n][k] = *(const LAS bf16x8*)(lds + PG8_SB(b, h) + boff + n * 2048 + k * 1024); } while (0)
; #define PG8_MMA(ai, bj, At, Bt) do { __builtin_amdgcn_s_setprio(1); _Pragma("unroll") for (int m = 0; m < 4; ++m) _Pragma("unroll") for (int n = 0; n < 2; ++n) _Pragma("unroll") for (int k = 0; k < 2; ++k) \
;         acc[ai][bj][m][n] = __builtin_amdgcn_mfma_f32_16x16x32_bf16(Bt[n][k], At[m][k], acc[ai][bj][m][n], 0, 0, 0); __builtin_amdgcn_s_setprio(0); } while (0)
; #define PG8_WAIT_V(n) asm volatile("s_waitcnt vmcnt(" #n ")" ::: "memory")
; #define PG8_WAIT_L(n) asm volatile("s_waitcnt lgkmcnt(" #n ")" ::: "memory")
; #define PG8_BAR __builtin_amdgcn_s_barrier()
; #define PG8_SCHED __builtin_amdgcn_sched_barrier(0)
; template <class Epi, class Sched>
; DI void gemm_phase(LAS unsigned char* lds, const int wv, const int lda, const int ldb, const Sched& S, const Epi& E) {
;     ...
;             PG8_LDB(B0, 1, 0); PG8_LDB(B1, 1, 1); PG8_SCHED; PG8_LDA(At, 1, 0); PG8_STAGE(PG8_SA(0, 1), a2 + hstepA, voffA);
;             PG8_WAIT_V(8); PG8_WAIT_L(0); PG8_BAR; PG8_MMA(0, 0, At, B0); PG8_MMA(0, 1, At, B1); PG8_BAR; PG8_SCHED;
;             PG8_LDA(At, 1, 1); PG8_STAGE(PG8_SB(1, 0), b3, voffB); PG8_STAGE(PG8_SB(1, 1), b3 + hstepB, voffB); PG8_STAGE(PG8_SA(1, 0), a3, voffA);
;             PG8_WAIT_V(8); PG8_WAIT_L(0); PG8_BAR; PG8_MMA(1, 0, At, B0); PG8_MMA(1, 1, At, B1); PG8_BAR; PG8_SCHED;
;         }
;         if (wr == 0) PG8_BAR;
	s_add_i32 s51, 0, 0x18000
	s_add_i32 s52, 0, 0x1c000
	v_add_u32_e32 v156, s51, v145
	v_add_u32_e32 v172, s52, v145
	ds_read_b128 v[138:141], v156
	ds_read_b128 v[148:151], v156 offset:1024
	ds_read_b128 v[152:155], v156 offset:2048
	ds_read_b128 v[156:159], v156 offset:3072
	ds_read_b128 v[160:163], v172
	ds_read_b128 v[164:167], v172 offset:1024
	ds_read_b128 v[168:171], v172 offset:2048
	ds_read_b128 v[172:175], v172 offset:3072
	s_add_u32 s34, s34, 0x80000
	s_addc_u32 s35, s35, 0
	s_mov_b32 m0, s40
	v_lshl_add_u64 v[222:223], s[34:35], 0, v[128:129]
	ds_read_b128 v[176:179], v147 offset:32768
	ds_read_b128 v[180:183], v147 offset:33792
	ds_read_b128 v[188:191], v147 offset:34816
	ds_read_b128 v[196:199], v147 offset:35840
	ds_read_b128 v[200:203], v147 offset:36864
	ds_read_b128 v[204:207], v147 offset:37888
	ds_read_b128 v[208:211], v147 offset:38912
	ds_read_b128 v[212:215], v147 offset:39936
	global_load_lds_dwordx4 v[222:223], off
	s_mov_b32 m0, s41
	v_lshl_add_u64 v[222:223], s[34:35], 0, v[130:131]
	global_load_lds_dwordx4 v[222:223], off
	s_waitcnt vmcnt(8) lgkmcnt(0)
	s_barrier
	v_mfma_f32_16x16x32_bf16 v[124:127], v[138:141], v[176:179], v[124:127]
	v_mfma_f32_16x16x32_bf16 v[120:123], v[152:155], v[176:179], v[120:123]
	v_mfma_f32_16x16x32_bf16 v[108:111], v[138:141], v[188:191], v[108:111]
	v_mfma_f32_16x16x32_bf16 v[104:107], v[152:155], v[188:191], v[104:107]
	v_mfma_f32_16x16x32_bf16 v[92:95], v[138:141], v[200:203], v[92:95]
	v_mfma_f32_16x16x32_bf16 v[88:91], v[152:155], v[200:203], v[88:91]
	v_mfma_f32_16x16x32_bf16 v[76:79], v[138:141], v[208:211], v[76:79]
	v_mfma_f32_16x16x32_bf16 v[72:75], v[152:155], v[208:211], v[72:75]
	v_mfma_f32_16x16x32_bf16 v[124:127], v[148:151], v[180:183], v[124:127]
	v_mfma_f32_16x16x32_bf16 v[120:123], v[156:159], v[180:183], v[120:123]
	v_mfma_f32_16x16x32_bf16 v[108:111], v[148:151], v[196:199], v[108:111]
	v_mfma_f32_16x16x32_bf16 v[104:107], v[156:159], v[196:199], v[104:107]
	v_mfma_f32_16x16x32_bf16 v[92:95], v[148:151], v[204:207], v[92:95]
	v_mfma_f32_16x16x32_bf16 v[88:91], v[156:159], v[204:207], v[88:91]
	v_mfma_f32_16x16x32_bf16 v[76:79], v[148:151], v[212:215], v[76:79]
	v_mfma_f32_16x16x32_bf16 v[72:75], v[156:159], v[212:215], v[72:75]
	v_mfma_f32_16x16x32_bf16 v[116:119], v[160:163], v[176:179], v[116:119]
	v_mfma_f32_16x16x32_bf16 v[112:115], v[168:171], v[176:179], v[112:115]
	v_mfma_f32_16x16x32_bf16 v[100:103], v[160:163], v[188:191], v[100:103]
	v_mfma_f32_16x16x32_bf16 v[96:99], v[168:171], v[188:191], v[96:99]
	v_mfma_f32_16x16x32_bf16 v[84:87], v[160:163], v[200:203], v[84:87]
	v_mfma_f32_16x16x32_bf16 v[80:83], v[168:171], v[200:203], v[80:83]
	v_mfma_f32_16x16x32_bf16 v[68:71], v[160:163], v[208:211], v[68:71]
	v_mfma_f32_16x16x32_bf16 v[64:67], v[168:171], v[208:211], v[64:67]
	v_mfma_f32_16x16x32_bf16 v[116:119], v[164:167], v[180:183], v[116:119]
	v_mfma_f32_16x16x32_bf16 v[112:115], v[172:175], v[180:183], v[112:115]
	v_mfma_f32_16x16x32_bf16 v[100:103], v[164:167], v[196:199], v[100:103]
	v_mfma_f32_16x16x32_bf16 v[96:99], v[172:175], v[196:199], v[96:99]
	v_mfma_f32_16x16x32_bf16 v[84:87], v[164:167], v[204:207], v[84:87]
	v_mfma_f32_16x16x32_bf16 v[80:83], v[172:175], v[204:207], v[80:83]
	v_mfma_f32_16x16x32_bf16 v[68:71], v[164:167], v[212:215], v[68:71]
	v_mfma_f32_16x16x32_bf16 v[64:67], v[172:175], v[212:215], v[64:67]
	s_barrier
	s_add_i32 s34, s51, s38
	v_lshl_add_u64 v[142:143], v[142:143], 0, s[28:29]
	s_mov_b32 m0, s34
	ds_read_b128 v[176:179], v147 offset:49152
	ds_read_b128 v[180:183], v147 offset:50176
	ds_read_b128 v[188:191], v147 offset:51200
	ds_read_b128 v[196:199], v147 offset:52224
	ds_read_b128 v[200:203], v147 offset:53248
	ds_read_b128 v[204:207], v147 offset:54272
	ds_read_b128 v[208:211], v147 offset:55296
	ds_read_b128 v[212:215], v147 offset:56320
	global_load_lds_dwordx4 v[142:143], off
	s_add_i32 m0, s34, 0x2000
	s_add_u32 s30, s30, 0x80080
	v_lshl_add_u64 v[142:143], v[216:217], 0, s[28:29]
	s_addc_u32 s31, s31, 0
	s_add_i32 s34, s52, s38
	global_load_lds_dwordx4 v[142:143], off
	s_mov_b32 m0, s34
	v_lshl_add_u64 v[142:143], s[30:31], 0, v[184:185]
	global_load_lds_dwordx4 v[142:143], off
	s_add_i32 m0, s34, 0x2000
	v_lshl_add_u64 v[142:143], s[30:31], 0, v[132:133]
	global_load_lds_dwordx4 v[142:143], off
	s_mov_b32 m0, s43
	v_lshl_add_u64 v[142:143], v[218:219], 0, s[28:29]
	global_load_lds_dwordx4 v[142:143], off
	s_mov_b32 m0, s44
	v_lshl_add_u64 v[142:143], v[220:221], 0, s[28:29]
	global_load_lds_dwordx4 v[142:143], off
	s_waitcnt vmcnt(8) lgkmcnt(0)
	s_barrier
	v_mfma_f32_16x16x32_bf16 v[60:63], v[138:141], v[176:179], v[60:63]
	v_mfma_f32_16x16x32_bf16 v[56:59], v[152:155], v[176:179], v[56:59]
	v_mfma_f32_16x16x32_bf16 v[44:47], v[138:141], v[188:191], v[44:47]
	v_mfma_f32_16x16x32_bf16 v[40:43], v[152:155], v[188:191], v[40:43]
	v_mfma_f32_16x16x32_bf16 v[28:31], v[138:141], v[200:203], v[28:31]
	v_mfma_f32_16x16x32_bf16 v[24:27], v[152:155], v[200:203], v[24:27]
	v_mfma_f32_16x16x32_bf16 v[12:15], v[138:141], v[208:211], v[12:15]
	v_mfma_f32_16x16x32_bf16 v[8:11], v[152:155], v[208:211], v[8:11]
	v_mfma_f32_16x16x32_bf16 v[60:63], v[148:151], v[180:183], v[60:63]
	v_mfma_f32_16x16x32_bf16 v[56:59], v[156:159], v[180:183], v[56:59]
	v_mfma_f32_16x16x32_bf16 v[44:47], v[148:151], v[196:199], v[44:47]
	v_mfma_f32_16x16x32_bf16 v[40:43], v[156:159], v[196:199], v[40:43]
	v_mfma_f32_16x16x32_bf16 v[28:31], v[148:151], v[204:207], v[28:31]
	v_mfma_f32_16x16x32_bf16 v[24:27], v[156:159], v[204:207], v[24:27]
	v_mfma_f32_16x16x32_bf16 v[12:15], v[148:151], v[212:215], v[12:15]
	v_mfma_f32_16x16x32_bf16 v[8:11], v[156:159], v[212:215], v[8:11]
	v_mfma_f32_16x16x32_bf16 v[52:55], v[160:163], v[176:179], v[52:55]
	v_mfma_f32_16x16x32_bf16 v[48:51], v[168:171], v[176:179], v[48:51]
	v_mfma_f32_16x16x32_bf16 v[36:39], v[160:163], v[188:191], v[36:39]
	v_mfma_f32_16x16x32_bf16 v[32:35], v[168:171], v[188:191], v[32:35]
	v_mfma_f32_16x16x32_bf16 v[20:23], v[160:163], v[200:203], v[20:23]
	v_mfma_f32_16x16x32_bf16 v[16:19], v[168:171], v[200:203], v[16:19]
	v_mfma_f32_16x16x32_bf16 v[4:7], v[160:163], v[208:211], v[4:7]
	v_mfma_f32_16x16x32_bf16 v[0:3], v[168:171], v[208:211], v[0:3]
	v_mfma_f32_16x16x32_bf16 v[52:55], v[164:167], v[180:183], v[52:55]
	v_mfma_f32_16x16x32_bf16 v[48:51], v[172:175], v[180:183], v[48:51]
	v_mfma_f32_16x16x32_bf16 v[36:39], v[164:167], v[196:199], v[36:39]
	v_mfma_f32_16x16x32_bf16 v[32:35], v[172:175], v[196:199], v[32:35]
	v_mfma_f32_16x16x32_bf16 v[20:23], v[164:167], v[204:207], v[20:23]
	v_mfma_f32_16x16x32_bf16 v[16:19], v[172:175], v[204:207], v[16:19]
	v_mfma_f32_16x16x32_bf16 v[4:7], v[164:167], v[212:215], v[4:7]
	v_mfma_f32_16x16x32_bf16 v[0:3], v[172:175], v[212:215], v[0:3]
	s_barrier
	s_add_i32 s50, s50, 2
	s_add_u32 s26, s26, 0x100
	s_addc_u32 s27, s27, 0
	s_add_u32 s48, s48, 0x100
	s_addc_u32 s49, s49, 0
	s_cmp_gt_u32 s50, 29
	s_cbranch_scc0 .LBB0_1397
	s_and_b64 vcc, exec, s[10:11]
	s_cbranch_vccz .LBB0_1400
	s_barrier

;     DI bool next(int i, Unit& u) const { const long L = (long)i * G + c; if (L >= T.nwg) return false; T.map((int)L, u.pm, u.pn); u.seg = 0; return true; }
;     DI bool next(int i, Unit& u) const { const int ti = i / 3; const long L = (long)ti * G + c; if (L >= T.nwg) return false; T.map((int)L, u.pm, u.pn); u.seg = i - 3 * ti; return true; }
;     DI const char* aptr(const Unit& u) const { return A + (size_t)u.pm * ta + (size_t)kofs(u.seg) * 2; }
;     DI const char* bptr(const Unit& u) const { return B + (size_t)u.pn * tb + (size_t)kofs(u.seg) * 2; }
; #define PG8_STAGE(bufoff, gbase, voff) do { _Pragma("unroll") for (int _i = 0; _i < 2; ++_i) \
;         __builtin_amdgcn_global_load_lds((const unsigned*)((const char*)(gbase) + (voff)[_i]), (LAS unsigned*)(lds + (bufoff) + ldsw + _i * 8192), 16, 0, 0); } while (0)
; #define PG8_LDA(dst, b, h) do { _Pragma("unroll") for (int m = 0; m < 4; ++m) _Pragma("unroll") for (int k = 0; k < 2; ++k) dst[m][k] = *(const LAS bf16x8*)(lds + PG8_SA(b, h) + aoff + m * 2048 + k * 1024); } while (0)
; #define PG8_WAIT_V(n) asm volatile("s_waitcnt vmcnt(" #n ")" ::: "memory")
; #define PG8_WAIT_L(n) asm volatile("s_waitcnt lgkmcnt(" #n ")" ::: "memory")
; template <class Epi, class Sched>
; DI void gemm_phase(LAS unsigned char* lds, const int wv, const int lda, const int ldb, const Sched& S, const Epi& E) {
;     ...
;         const bool has_next = S.next(ui + 1, nxt);
;         const char* nA = has_next ? S.aptr(nxt) : cA; const char* nB = has_next ? S.bptr(nxt) : cB;
;         for (int t = 0; t < nt; t += 2) {
;             const bool last = (t == nt - 2);
;             const char* a1 = cA + (size_t)(t + 1) * kstep;
;             const char* a2 = last ? nA : cA + (size_t)(t + 2) * kstep; const char* b2 = last ? nB : cB + (size_t)(t + 2) * kstep;
;             const char* a3 = a2 + kstep; const char* b3 = b2 + kstep;
;             PG8_LDB(B0, 0, 0); PG8_LDB(B1, 0, 1); PG8_SCHED; PG8_LDA(At, 0, 0); PG8_STAGE(PG8_SA(1, 1), a1 + hstepA, voffA);
;             PG8_WAIT_V(8); PG8_WAIT_L(0); PG8_BAR; PG8_MMA(0, 0, At, B0); PG8_MMA(0, 1, At, B1); PG8_BAR; PG8_SCHED;
;             PG8_LDA(At, 0, 1); PG8_STAGE(PG8_SB(0, 0), b2, voffB); PG8_STAGE(PG8_SB(0, 1), b2 + hstepB, voffB); PG8_STAGE(PG8_SA(0, 0), a2, voffA);
;             PG8_WAIT_V(8); PG8_WAIT_L(0); PG8_BAR; PG8_MMA(1, 0, At, B0); PG8_MMA(1, 1, At, B1); PG8_BAR; PG8_SCHED;
.LBB0_1476:
	s_ashr_i32 s23, s22, 31
	s_lshl_b64 s[0:1], s[22:23], 22
	s_add_u32 s24, s33, s0
	s_addc_u32 s25, s40, s1
	s_and_b64 s[0:1], s[6:7], exec
	s_cselect_b32 s0, s25, s35
	s_cselect_b32 s1, s24, s34
	s_ashr_i32 s11, s10, 31
	s_lshl_b64 s[26:27], s[10:11], 22
	s_add_u32 s26, s41, s26
	s_addc_u32 s27, s42, s27
	s_and_b64 s[38:39], s[6:7], exec
	s_cselect_b32 s11, s27, s37
	s_cselect_b32 s19, s26, s36
	s_add_u32 s34, s34, 0x200080
	s_addc_u32 s35, s35, 0
	s_add_u32 s23, s36, 0x100
	s_addc_u32 s54, s37, 0
	s_mov_b32 s55, -2
	s_waitcnt lgkmcnt(0)
	s_add_u32 s36, s34, 0xffe00080
	s_addc_u32 s37, s35, -1
	s_add_i32 s56, 0, 0x10000
	s_cmpk_eq_i32 s55, 0x7c
	s_cselect_b32 s39, s0, s37
	s_cselect_b32 s38, s1, s36
	s_cselect_b32 s37, s11, s54
	s_cselect_b32 s36, s19, s23
	s_add_i32 s58, 0, 0x14000
	v_add_u32_e32 v150, s56, v155
	v_add_u32_e32 v172, s58, v155
	ds_read_b128 v[128:131], v150
	ds_read_b128 v[142:145], v150 offset:1024
	ds_read_b128 v[146:149], v150 offset:2048
	ds_read_b128 v[150:153], v150 offset:3072
	ds_read_b128 v[160:163], v172
	ds_read_b128 v[164:167], v172 offset:1024
	ds_read_b128 v[168:171], v172 offset:2048
	ds_read_b128 v[172:175], v172 offset:3072
	v_lshl_add_u64 v[216:217], s[34:35], 0, v[138:139]
	s_add_i32 m0, s31, 0xc000
	ds_read_b128 v[176:179], v159
	ds_read_b128 v[180:183], v159 offset:1024
	ds_read_b128 v[188:191], v159 offset:2048
	ds_read_b128 v[196:199], v159 offset:3072
	ds_read_b128 v[200:203], v159 offset:4096
	ds_read_b128 v[204:207], v159 offset:5120
	ds_read_b128 v[208:211], v159 offset:6144
	ds_read_b128 v[212:215], v159 offset:7168
	global_load_lds_dwordx4 v[216:217], off
	s_add_i32 m0, s31, 0xe000
	v_lshl_add_u64 v[216:217], s[34:35], 0, v[140:141]
	global_load_lds_dwordx4 v[216:217], off
	s_waitcnt vmcnt(8) lgkmcnt(0)
	s_barrier
	v_mfma_f32_16x16x32_bf16 v[124:127], v[128:131], v[176:179], 0
	v_mfma_f32_16x16x32_bf16 v[120:123], v[146:149], v[176:179], 0
	v_mfma_f32_16x16x32_bf16 v[108:111], v[128:131], v[188:191], 0
	v_mfma_f32_16x16x32_bf16 v[104:107], v[146:149], v[188:191], 0
	v_mfma_f32_16x16x32_bf16 v[96:99], v[128:131], v[200:203], 0
	v_mfma_f32_16x16x32_bf16 v[88:91], v[146:149], v[200:203], 0
	v_mfma_f32_16x16x32_bf16 v[80:83], v[128:131], v[208:211], 0
	v_mfma_f32_16x16x32_bf16 v[72:75], v[146:149], v[208:211], 0
	v_mfma_f32_16x16x32_bf16 v[124:127], v[142:145], v[180:183], v[124:127]
	v_mfma_f32_16x16x32_bf16 v[120:123], v[150:153], v[180:183], v[120:123]
	v_mfma_f32_16x16x32_bf16 v[108:111], v[142:145], v[196:199], v[108:111]
	v_mfma_f32_16x16x32_bf16 v[104:107], v[150:153], v[196:199], v[104:107]
	v_mfma_f32_16x16x32_bf16 v[96:99], v[142:145], v[204:207], v[96:99]
	v_mfma_f32_16x16x32_bf16 v[88:91], v[150:153], v[204:207], v[88:91]
	v_mfma_f32_16x16x32_bf16 v[80:83], v[142:145], v[212:215], v[80:83]
	v_mfma_f32_16x16x32_bf16 v[72:75], v[150:153], v[212:215], v[72:75]
	v_mfma_f32_16x16x32_bf16 v[116:119], v[160:163], v[176:179], 0
	v_mfma_f32_16x16x32_bf16 v[112:115], v[168:171], v[176:179], 0
	v_mfma_f32_16x16x32_bf16 v[100:103], v[160:163], v[188:191], 0
	v_mfma_f32_16x16x32_bf16 v[92:95], v[168:171], v[188:191], 0
	v_mfma_f32_16x16x32_bf16 v[84:87], v[160:163], v[200:203], 0
	v_mfma_f32_16x16x32_bf16 v[76:79], v[168:171], v[200:203], 0
	v_mfma_f32_16x16x32_bf16 v[68:71], v[160:163], v[208:211], 0
	v_mfma_f32_16x16x32_bf16 v[64:67], v[168:171], v[208:211], 0
	v_mfma_f32_16x16x32_bf16 v[116:119], v[164:167], v[180:183], v[116:119]
	v_mfma_f32_16x16x32_bf16 v[112:115], v[172:175], v[180:183], v[112:115]
	v_mfma_f32_16x16x32_bf16 v[100:103], v[164:167], v[196:199], v[100:103]
	v_mfma_f32_16x16x32_bf16 v[92:95], v[172:175], v[196:199], v[92:95]
	v_mfma_f32_16x16x32_bf16 v[84:87], v[164:167], v[204:207], v[84:87]
	v_mfma_f32_16x16x32_bf16 v[76:79], v[172:175], v[204:207], v[76:79]
	v_mfma_f32_16x16x32_bf16 v[68:71], v[164:167], v[212:215], v[68:71]
	v_mfma_f32_16x16x32_bf16 v[64:67], v[172:175], v[212:215], v[64:67]
	s_barrier
	s_add_i32 s56, s56, s43
	v_lshl_add_u64 v[216:217], s[36:37], 0, v[184:185]
	s_mov_b32 m0, s56
	ds_read_b128 v[176:179], v159 offset:16384
	ds_read_b128 v[180:183], v159 offset:17408
	ds_read_b128 v[188:191], v159 offset:18432
	ds_read_b128 v[196:199], v159 offset:19456
	ds_read_b128 v[200:203], v159 offset:20480
	ds_read_b128 v[204:207], v159 offset:21504
	ds_read_b128 v[208:211], v159 offset:22528
	ds_read_b128 v[212:215], v159 offset:23552
	global_load_lds_dwordx4 v[216:217], off
	s_add_i32 m0, s56, 0x2000
	s_add_u32 s56, s36, 0x200000
	v_lshl_add_u64 v[218:219], s[36:37], 0, v[136:137]
	s_addc_u32 s57, s37, 0
	s_add_i32 s58, s58, s43
	global_load_lds_dwordx4 v[218:219], off
	v_lshl_add_u64 v[220:221], s[56:57], 0, v[184:185]
	s_mov_b32 m0, s58
	v_lshl_add_u64 v[222:223], s[38:39], 0, v[134:135]
	global_load_lds_dwordx4 v[220:221], off
	s_add_i32 m0, s58, 0x2000
	v_lshl_add_u64 v[220:221], s[56:57], 0, v[136:137]
	global_load_lds_dwordx4 v[220:221], off
	s_mov_b32 m0, s31
	v_lshl_add_u64 v[220:221], s[38:39], 0, v[132:133]
	global_load_lds_dwordx4 v[220:221], off
	s_mov_b32 m0, s44
	s_nop 0
	global_load_lds_dwordx4 v[222:223], off
	s_waitcnt vmcnt(8) lgkmcnt(0)
	s_barrier
; #define PG8_STAGE(bufoff, gbase, voff) do { _Pragma("unroll") for (int _i = 0; _i < 2; ++_i) \
;         __builtin_amdgcn_global_load_lds((const unsigned*)((const char*)(gbase) + (voff)[_i]), (LAS unsigned*)(lds + (bufoff) + ldsw + _i * 8192), 16, 0, 0); } while (0)
; #define PG8_LDA(dst, b, h) do { _Pragma("unroll") for (int m = 0; m < 4; ++m) _Pragma("unroll") for (int k = 0; k < 2; ++k) dst[m][k] = *(const LAS bf16x8*)(lds + PG8_SA(b, h) + aoff + m * 2048 + k * 1024); } while (0)
; #define PG8_LDB(dst, b, h) do { _Pragma("unroll") for (int n = 0; n < 2; ++n) _Pragma("unroll") for (int k = 0; k < 2; ++k) dst[n][k] = *(const LAS bf16x8*)(lds + PG8_SB(b, h) + boff + n * 2048 + k * 1024); } while (0)
; #define PG8_MMA(ai, bj, At, Bt) do { __builtin_amdgcn_s_setprio(1); _Pragma("unroll") for (int m = 0; m < 4; ++m) _Pragma("unroll") for (int n = 0; n < 2; ++n) _Pragma("unroll") for (int k = 0; k < 2; ++k) \
;         acc[ai][bj][m][n] = __builtin_amdgcn_mfma_f32_16x16x32_bf16(Bt[n][k], At[m][k], acc[ai][bj][m][n], 0, 0, 0); __builtin_amdgcn_s_setprio(0); } while (0)
; #define PG8_WAIT_V(n) asm volatile("s_waitcnt vmcnt(" #n ")" ::: "memory")
; #define PG8_WAIT_L(n) asm volatile("s_waitcnt lgkmcnt(" #n ")" ::: "memory")
; #define PG8_BAR __builtin_amdgcn_s_barrier()
; #define PG8_SCHED __builtin_amdgcn_sched_barrier(0)
; template <class Epi, class Sched>
; DI void gemm_phase(LAS unsigned char* lds, const int wv, const int lda, const int ldb, const Sched& S, const Epi& E) {
;     ...
;             PG8_WAIT_V(8); PG8_WAIT_L(0); PG8_BAR; PG8_MMA(1, 0, At, B0); PG8_MMA(1, 1, At, B1); PG8_BAR; PG8_SCHED;
;             PG8_LDB(B0, 1, 0); PG8_LDB(B1, 1, 1); PG8_SCHED; PG8_LDA(At, 1, 0); PG8_STAGE(PG8_SA(0, 1), a2 + hstepA, voffA);
;             PG8_WAIT_V(8); PG8_WAIT_L(0); PG8_BAR; PG8_MMA(0, 0, At, B0); PG8_MMA(0, 1, At, B1); PG8_BAR; PG8_SCHED;
	v_mfma_f32_16x16x32_bf16 v[60:63], v[128:131], v[176:179], 0
	v_mfma_f32_16x16x32_bf16 v[56:59], v[146:149], v[176:179], 0
	v_mfma_f32_16x16x32_bf16 v[48:51], v[128:131], v[188:191], 0
	v_mfma_f32_16x16x32_bf16 v[40:43], v[146:149], v[188:191], 0
	v_mfma_f32_16x16x32_bf16 v[32:35], v[128:131], v[200:203], 0
	v_mfma_f32_16x16x32_bf16 v[24:27], v[146:149], v[200:203], 0
	v_mfma_f32_16x16x32_bf16 v[16:19], v[128:131], v[208:211], 0
	v_mfma_f32_16x16x32_bf16 v[8:11], v[146:149], v[208:211], 0
	v_mfma_f32_16x16x32_bf16 v[60:63], v[142:145], v[180:183], v[60:63]
	v_mfma_f32_16x16x32_bf16 v[56:59], v[150:153], v[180:183], v[56:59]
	v_mfma_f32_16x16x32_bf16 v[48:51], v[142:145], v[196:199], v[48:51]
	v_mfma_f32_16x16x32_bf16 v[40:43], v[150:153], v[196:199], v[40:43]
	v_mfma_f32_16x16x32_bf16 v[32:35], v[142:145], v[204:207], v[32:35]
	v_mfma_f32_16x16x32_bf16 v[24:27], v[150:153], v[204:207], v[24:27]
	v_mfma_f32_16x16x32_bf16 v[16:19], v[142:145], v[212:215], v[16:19]
	v_mfma_f32_16x16x32_bf16 v[8:11], v[150:153], v[212:215], v[8:11]
	v_mfma_f32_16x16x32_bf16 v[52:55], v[160:163], v[176:179], 0
	v_mfma_f32_16x16x32_bf16 v[44:47], v[168:171], v[176:179], 0
	v_mfma_f32_16x16x32_bf16 v[36:39], v[160:163], v[188:191], 0
	v_mfma_f32_16x16x32_bf16 v[28:31], v[168:171], v[188:191], 0
	v_mfma_f32_16x16x32_bf16 v[20:23], v[160:163], v[200:203], 0
	v_mfma_f32_16x16x32_bf16 v[12:15], v[168:171], v[200:203], 0
	v_mfma_f32_16x16x32_bf16 v[4:7], v[160:163], v[208:211], 0
	v_mfma_f32_16x16x32_bf16 v[0:3], v[168:171], v[208:211], 0
	v_mfma_f32_16x16x32_bf16 v[52:55], v[164:167], v[180:183], v[52:55]
	v_mfma_f32_16x16x32_bf16 v[44:47], v[172:175], v[180:183], v[44:47]
	v_mfma_f32_16x16x32_bf16 v[36:39], v[164:167], v[196:199], v[36:39]
	v_mfma_f32_16x16x32_bf16 v[28:31], v[172:175], v[196:199], v[28:31]
	v_mfma_f32_16x16x32_bf16 v[20:23], v[164:167], v[204:207], v[20:23]
	v_mfma_f32_16x16x32_bf16 v[12:15], v[172:175], v[204:207], v[12:15]
	v_mfma_f32_16x16x32_bf16 v[4:7], v[164:167], v[212:215], v[4:7]
	v_mfma_f32_16x16x32_bf16 v[0:3], v[172:175], v[212:215], v[0:3]
	s_barrier
	s_add_i32 s56, 0, 0x18000
	s_add_i32 s57, 0, 0x1c000
	v_add_u32_e32 v150, s56, v155
	v_add_u32_e32 v172, s57, v155
	ds_read_b128 v[128:131], v150
	ds_read_b128 v[142:145], v150 offset:1024
	ds_read_b128 v[146:149], v150 offset:2048
	ds_read_b128 v[150:153], v150 offset:3072
	ds_read_b128 v[160:163], v172
	ds_read_b128 v[164:167], v172 offset:1024
	ds_read_b128 v[168:171], v172 offset:2048
	ds_read_b128 v[172:175], v172 offset:3072
	s_add_u32 s38, s38, 0x200000
	s_addc_u32 s39, s39, 0
	s_mov_b32 m0, s45
	v_lshl_add_u64 v[234:235], s[38:39], 0, v[132:133]
	ds_read_b128 v[176:179], v159 offset:32768
	ds_read_b128 v[180:183], v159 offset:33792
	ds_read_b128 v[188:191], v159 offset:34816
	ds_read_b128 v[196:199], v159 offset:35840
	ds_read_b128 v[200:203], v159 offset:36864
	ds_read_b128 v[204:207], v159 offset:37888
	ds_read_b128 v[208:211], v159 offset:38912
	ds_read_b128 v[212:215], v159 offset:39936
	global_load_lds_dwordx4 v[234:235], off
	s_mov_b32 m0, s46
	v_lshl_add_u64 v[234:235], s[38:39], 0, v[134:135]
	global_load_lds_dwordx4 v[234:235], off
	s_waitcnt vmcnt(8) lgkmcnt(0)
	s_barrier
	v_mfma_f32_16x16x32_bf16 v[124:127], v[128:131], v[176:179], v[124:127]
	v_mfma_f32_16x16x32_bf16 v[120:123], v[146:149], v[176:179], v[120:123]
	v_mfma_f32_16x16x32_bf16 v[108:111], v[128:131], v[188:191], v[108:111]
	v_mfma_f32_16x16x32_bf16 v[104:107], v[146:149], v[188:191], v[104:107]
	v_mfma_f32_16x16x32_bf16 v[96:99], v[128:131], v[200:203], v[96:99]
	v_mfma_f32_16x16x32_bf16 v[88:91], v[146:149], v[200:203], v[88:91]
	v_mfma_f32_16x16x32_bf16 v[80:83], v[128:131], v[208:211], v[80:83]
	v_mfma_f32_16x16x32_bf16 v[72:75], v[146:149], v[208:211], v[72:75]
	v_mfma_f32_16x16x32_bf16 v[124:127], v[142:145], v[180:183], v[124:127]
	v_mfma_f32_16x16x32_bf16 v[120:123], v[150:153], v[180:183], v[120:123]
	v_mfma_f32_16x16x32_bf16 v[108:111], v[142:145], v[196:199], v[108:111]
	v_mfma_f32_16x16x32_bf16 v[104:107], v[150:153], v[196:199], v[104:107]
	v_mfma_f32_16x16x32_bf16 v[96:99], v[142:145], v[204:207], v[96:99]
	v_mfma_f32_16x16x32_bf16 v[88:91], v[150:153], v[204:207], v[88:91]
	v_mfma_f32_16x16x32_bf16 v[80:83], v[142:145], v[212:215], v[80:83]
	v_mfma_f32_16x16x32_bf16 v[72:75], v[150:153], v[212:215], v[72:75]
	v_mfma_f32_16x16x32_bf16 v[116:119], v[160:163], v[176:179], v[116:119]
	v_mfma_f32_16x16x32_bf16 v[112:115], v[168:171], v[176:179], v[112:115]
	v_mfma_f32_16x16x32_bf16 v[100:103], v[160:163], v[188:191], v[100:103]
	v_mfma_f32_16x16x32_bf16 v[92:95], v[168:171], v[188:191], v[92:95]
	v_mfma_f32_16x16x32_bf16 v[84:87], v[160:163], v[200:203], v[84:87]
	v_mfma_f32_16x16x32_bf16 v[76:79], v[168:171], v[200:203], v[76:79]
	v_mfma_f32_16x16x32_bf16 v[68:71], v[160:163], v[208:211], v[68:71]
	v_mfma_f32_16x16x32_bf16 v[64:67], v[168:171], v[208:211], v[64:67]
	v_mfma_f32_16x16x32_bf16 v[116:119], v[164:167], v[180:183], v[116:119]
	v_mfma_f32_16x16x32_bf16 v[112:115], v[172:175], v[180:183], v[112:115]
	v_mfma_f32_16x16x32_bf16 v[100:103], v[164:167], v[196:199], v[100:103]
	v_mfma_f32_16x16x32_bf16 v[92:95], v[172:175], v[196:199], v[92:95]
	v_mfma_f32_16x16x32_bf16 v[84:87], v[164:167], v[204:207], v[84:87]
	v_mfma_f32_16x16x32_bf16 v[76:79], v[172:175], v[204:207], v[76:79]
	v_mfma_f32_16x16x32_bf16 v[68:71], v[164:167], v[212:215], v[68:71]
	v_mfma_f32_16x16x32_bf16 v[64:67], v[172:175], v[212:215], v[64:67]
	s_barrier
; #define PG8_STAGE(bufoff, gbase, voff) do { _Pragma("unroll") for (int _i = 0; _i < 2; ++_i) \
;         __builtin_amdgcn_global_load_lds((const unsigned*)((const char*)(gbase) + (voff)[_i]), (LAS unsigned*)(lds + (bufoff) + ldsw + _i * 8192), 16, 0, 0); } while (0)
; #define PG8_LDA(dst, b, h) do { _Pragma("unroll") for (int m = 0; m < 4; ++m) _Pragma("unroll") for (int k = 0; k < 2; ++k) dst[m][k] = *(const LAS bf16x8*)(lds + PG8_SA(b, h) + aoff + m * 2048 + k * 1024); } while (0)
; #define PG8_LDB(dst, b, h) do { _Pragma("unroll") for (int n = 0; n < 2; ++n) _Pragma("unroll") for (int k = 0; k < 2; ++k) dst[n][k] = *(const LAS bf16x8*)(lds + PG8_SB(b, h) + boff + n * 2048 + k * 1024); } while (0)
; #define PG8_MMA(ai, bj, At, Bt) do { __builtin_amdgcn_s_setprio(1); _Pragma("unroll") for (int m = 0; m < 4; ++m) _Pragma("unroll") for (int n = 0; n < 2; ++n) _Pragma("unroll") for (int k = 0; k < 2; ++k) \
;         acc[ai][bj][m][n] = __builtin_amdgcn_mfma_f32_16x16x32_bf16(Bt[n][k], At[m][k], acc[ai][bj][m][n], 0, 0, 0); __builtin_amdgcn_s_setprio(0); } while (0)
; #define PG8_WAIT_V(n) asm volatile("s_waitcnt vmcnt(" #n ")" ::: "memory")
; #define PG8_WAIT_L(n) asm volatile("s_waitcnt lgkmcnt(" #n ")" ::: "memory")
; #define PG8_BAR __builtin_amdgcn_s_barrier()
; #define PG8_SCHED __builtin_amdgcn_sched_barrier(0)
; template <class Epi, class Sched>
; DI void gemm_phase(LAS unsigned char* lds, const int wv, const int lda, const int ldb, const Sched& S, const Epi& E) {
;     ...
;         for (int t = 0; t < nt; t += 2) {
;             const bool last = (t == nt - 2);
;             const char* a1 = cA + (size_t)(t + 1) * kstep;
;             const char* a2 = last ? nA : cA + (size_t)(t + 2) * kstep; const char* b2 = last ? nB : cB + (size_t)(t + 2) * kstep;
;             const char* a3 = a2 + kstep; const char* b3 = b2 + kstep;
;             PG8_LDB(B0, 0, 0); PG8_LDB(B1, 0, 1); PG8_SCHED; PG8_LDA(At, 0, 0); PG8_STAGE(PG8_SA(1, 1), a1 + hstepA, voffA);
;             PG8_WAIT_V(8); PG8_WAIT_L(0); PG8_BAR; PG8_MMA(0, 0, At, B0); PG8_MMA(0, 1, At, B1); PG8_BAR; PG8_SCHED;
;     ...
;             PG8_LDA(At, 1, 1); PG8_STAGE(PG8_SB(1, 0), b3, voffB); PG8_STAGE(PG8_SB(1, 1), b3 + hstepB, voffB); PG8_STAGE(PG8_SA(1, 0), a3, voffA);
;             PG8_WAIT_V(8); PG8_WAIT_L(0); PG8_BAR; PG8_MMA(1, 0, At, B0); PG8_MMA(1, 1, At, B1); PG8_BAR; PG8_SCHED;
	s_add_i32 s38, s56, s43
	v_lshl_add_u64 v[216:217], v[216:217], 0, s[28:29]
	s_mov_b32 m0, s38
	ds_read_b128 v[176:179], v159 offset:49152
	ds_read_b128 v[180:183], v159 offset:50176
	ds_read_b128 v[188:191], v159 offset:51200
	ds_read_b128 v[196:199], v159 offset:52224
	ds_read_b128 v[200:203], v159 offset:53248
	ds_read_b128 v[204:207], v159 offset:54272
	ds_read_b128 v[208:211], v159 offset:55296
	ds_read_b128 v[212:215], v159 offset:56320
	global_load_lds_dwordx4 v[216:217], off
	s_add_i32 m0, s38, 0x2000
	s_add_u32 s36, s36, 0x200080
	v_lshl_add_u64 v[216:217], v[218:219], 0, s[28:29]
	s_addc_u32 s37, s37, 0
	s_add_i32 s38, s57, s43
	global_load_lds_dwordx4 v[216:217], off
	s_mov_b32 m0, s38
	v_lshl_add_u64 v[216:217], s[36:37], 0, v[184:185]
	global_load_lds_dwordx4 v[216:217], off
	s_add_i32 m0, s38, 0x2000
	v_lshl_add_u64 v[216:217], s[36:37], 0, v[136:137]
	global_load_lds_dwordx4 v[216:217], off
	s_mov_b32 m0, s47
	v_lshl_add_u64 v[216:217], v[220:221], 0, s[28:29]
	global_load_lds_dwordx4 v[216:217], off
	s_mov_b32 m0, s48
	v_lshl_add_u64 v[216:217], v[222:223], 0, s[28:29]
	global_load_lds_dwordx4 v[216:217], off
	s_waitcnt vmcnt(8) lgkmcnt(0)
	s_barrier
	v_mfma_f32_16x16x32_bf16 v[60:63], v[128:131], v[176:179], v[60:63]
	v_mfma_f32_16x16x32_bf16 v[56:59], v[146:149], v[176:179], v[56:59]
	v_mfma_f32_16x16x32_bf16 v[48:51], v[128:131], v[188:191], v[48:51]
	v_mfma_f32_16x16x32_bf16 v[40:43], v[146:149], v[188:191], v[40:43]
	v_mfma_f32_16x16x32_bf16 v[32:35], v[128:131], v[200:203], v[32:35]
	v_mfma_f32_16x16x32_bf16 v[24:27], v[146:149], v[200:203], v[24:27]
	v_mfma_f32_16x16x32_bf16 v[16:19], v[128:131], v[208:211], v[16:19]
	v_mfma_f32_16x16x32_bf16 v[8:11], v[146:149], v[208:211], v[8:11]
	v_mfma_f32_16x16x32_bf16 v[60:63], v[142:145], v[180:183], v[60:63]
	v_mfma_f32_16x16x32_bf16 v[56:59], v[150:153], v[180:183], v[56:59]
	v_mfma_f32_16x16x32_bf16 v[48:51], v[142:145], v[196:199], v[48:51]
	v_mfma_f32_16x16x32_bf16 v[40:43], v[150:153], v[196:199], v[40:43]
	v_mfma_f32_16x16x32_bf16 v[32:35], v[142:145], v[204:207], v[32:35]
	v_mfma_f32_16x16x32_bf16 v[24:27], v[150:153], v[204:207], v[24:27]
	v_mfma_f32_16x16x32_bf16 v[16:19], v[142:145], v[212:215], v[16:19]
	v_mfma_f32_16x16x32_bf16 v[8:11], v[150:153], v[212:215], v[8:11]
	v_mfma_f32_16x16x32_bf16 v[52:55], v[160:163], v[176:179], v[52:55]
	v_mfma_f32_16x16x32_bf16 v[44:47], v[168:171], v[176:179], v[44:47]
	v_mfma_f32_16x16x32_bf16 v[36:39], v[160:163], v[188:191], v[36:39]
	v_mfma_f32_16x16x32_bf16 v[28:31], v[168:171], v[188:191], v[28:31]
	v_mfma_f32_16x16x32_bf16 v[20:23], v[160:163], v[200:203], v[20:23]
	v_mfma_f32_16x16x32_bf16 v[12:15], v[168:171], v[200:203], v[12:15]
	v_mfma_f32_16x16x32_bf16 v[4:7], v[160:163], v[208:211], v[4:7]
	v_mfma_f32_16x16x32_bf16 v[0:3], v[168:171], v[208:211], v[0:3]
	v_mfma_f32_16x16x32_bf16 v[52:55], v[164:167], v[180:183], v[52:55]
	v_mfma_f32_16x16x32_bf16 v[44:47], v[172:175], v[180:183], v[44:47]
	v_mfma_f32_16x16x32_bf16 v[36:39], v[164:167], v[196:199], v[36:39]
	v_mfma_f32_16x16x32_bf16 v[28:31], v[172:175], v[196:199], v[28:31]
	v_mfma_f32_16x16x32_bf16 v[20:23], v[164:167], v[204:207], v[20:23]
	v_mfma_f32_16x16x32_bf16 v[12:15], v[172:175], v[204:207], v[12:15]
	v_mfma_f32_16x16x32_bf16 v[4:7], v[164:167], v[212:215], v[4:7]
	v_mfma_f32_16x16x32_bf16 v[0:3], v[172:175], v[212:215], v[0:3]
	s_barrier
	s_add_i32 s55, s55, 2
	s_add_u32 s34, s34, 0x100
	s_addc_u32 s35, s35, 0
	s_add_u32 s23, s23, 0x100
	s_addc_u32 s54, s54, 0
.LBB0_1477:
	s_add_u32 s36, s34, 0xffe00080
	s_addc_u32 s37, s35, -1
	s_add_i32 s56, 0, 0x10000
	s_cmpk_eq_i32 s55, 0x7c
	s_cselect_b32 s39, s0, s37
	s_cselect_b32 s38, s1, s36
	s_cselect_b32 s37, s11, s54
	s_cselect_b32 s36, s19, s23
	s_add_i32 s58, 0, 0x14000
	v_add_u32_e32 v150, s56, v155
	v_add_u32_e32 v172, s58, v155
	ds_read_b128 v[128:131], v150
	ds_read_b128 v[142:145], v150 offset:1024
	ds_read_b128 v[146:149], v150 offset:2048
	ds_read_b128 v[150:153], v150 offset:3072
	ds_read_b128 v[160:163], v172
	ds_read_b128 v[164:167], v172 offset:1024
	ds_read_b128 v[168:171], v172 offset:2048
	ds_read_b128 v[172:175], v172 offset:3072
	v_lshl_add_u64 v[216:217], s[34:35], 0, v[138:139]
	s_add_i32 m0, s31, 0xc000
	ds_read_b128 v[176:179], v159
	ds_read_b128 v[180:183], v159 offset:1024
	ds_read_b128 v[188:191], v159 offset:2048
	ds_read_b128 v[196:199], v159 offset:3072
	ds_read_b128 v[200:203], v159 offset:4096
	ds_read_b128 v[204:207], v159 offset:5120
	ds_read_b128 v[208:211], v159 offset:6144
	ds_read_b128 v[212:215], v159 offset:7168
	global_load_lds_dwordx4 v[216:217], off
	s_add_i32 m0, s31, 0xe000
	v_lshl_add_u64 v[216:217], s[34:35], 0, v[140:141]
	global_load_lds_dwordx4 v[216:217], off
	s_waitcnt vmcnt(8) lgkmcnt(0)
	s_barrier
; #define PG8_STAGE(bufoff, gbase, voff) do { _Pragma("unroll") for (int _i = 0; _i < 2; ++_i) \
;         __builtin_amdgcn_global_load_lds((const unsigned*)((const char*)(gbase) + (voff)[_i]), (LAS unsigned*)(lds + (bufoff) + ldsw + _i * 8192), 16, 0, 0); } while (0)
; #define PG8_LDA(dst, b, h) do { _Pragma("unroll") for (int m = 0; m < 4; ++m) _Pragma("unroll") for (int k = 0; k < 2; ++k) dst[m][k] = *(const LAS bf16x8*)(lds + PG8_SA(b, h) + aoff + m * 2048 + k * 1024); } while (0)
; #define PG8_MMA(ai, bj, At, Bt) do { __builtin_amdgcn_s_setprio(1); _Pragma("unroll") for (int m = 0; m < 4; ++m) _Pragma("unroll") for (int n = 0; n < 2; ++n) _Pragma("unroll") for (int k = 0; k < 2; ++k) \
;         acc[ai][bj][m][n] = __builtin_amdgcn_mfma_f32_16x16x32_bf16(Bt[n][k], At[m][k], acc[ai][bj][m][n], 0, 0, 0); __builtin_amdgcn_s_setprio(0); } while (0)
; #define PG8_WAIT_V(n) asm volatile("s_waitcnt vmcnt(" #n ")" ::: "memory")
; #define PG8_WAIT_L(n) asm volatile("s_waitcnt lgkmcnt(" #n ")" ::: "memory")
; #define PG8_BAR __builtin_amdgcn_s_barrier()
; #define PG8_SCHED __builtin_amdgcn_sched_barrier(0)
; template <class Epi, class Sched>
; DI void gemm_phase(LAS unsigned char* lds, const int wv, const int lda, const int ldb, const Sched& S, const Epi& E) {
;     ...
;             PG8_WAIT_V(8); PG8_WAIT_L(0); PG8_BAR; PG8_MMA(0, 0, At, B0); PG8_MMA(0, 1, At, B1); PG8_BAR; PG8_SCHED;
;             PG8_LDA(At, 0, 1); PG8_STAGE(PG8_SB(0, 0), b2, voffB); PG8_STAGE(PG8_SB(0, 1), b2 + hstepB, voffB); PG8_STAGE(PG8_SA(0, 0), a2, voffA);
;             PG8_WAIT_V(8); PG8_WAIT_L(0); PG8_BAR; PG8_MMA(1, 0, At, B0); PG8_MMA(1, 1, At, B1); PG8_BAR; PG8_SCHED;
	v_mfma_f32_16x16x32_bf16 v[124:127], v[128:131], v[176:179], v[124:127]
	v_mfma_f32_16x16x32_bf16 v[120:123], v[146:149], v[176:179], v[120:123]
	v_mfma_f32_16x16x32_bf16 v[108:111], v[128:131], v[188:191], v[108:111]
	v_mfma_f32_16x16x32_bf16 v[104:107], v[146:149], v[188:191], v[104:107]
	v_mfma_f32_16x16x32_bf16 v[96:99], v[128:131], v[200:203], v[96:99]
	v_mfma_f32_16x16x32_bf16 v[88:91], v[146:149], v[200:203], v[88:91]
	v_mfma_f32_16x16x32_bf16 v[80:83], v[128:131], v[208:211], v[80:83]
	v_mfma_f32_16x16x32_bf16 v[72:75], v[146:149], v[208:211], v[72:75]
	v_mfma_f32_16x16x32_bf16 v[124:127], v[142:145], v[180:183], v[124:127]
	v_mfma_f32_16x16x32_bf16 v[120:123], v[150:153], v[180:183], v[120:123]
	v_mfma_f32_16x16x32_bf16 v[108:111], v[142:145], v[196:199], v[108:111]
	v_mfma_f32_16x16x32_bf16 v[104:107], v[150:153], v[196:199], v[104:107]
	v_mfma_f32_16x16x32_bf16 v[96:99], v[142:145], v[204:207], v[96:99]
	v_mfma_f32_16x16x32_bf16 v[88:91], v[150:153], v[204:207], v[88:91]
	v_mfma_f32_16x16x32_bf16 v[80:83], v[142:145], v[212:215], v[80:83]
	v_mfma_f32_16x16x32_bf16 v[72:75], v[150:153], v[212:215], v[72:75]
	v_mfma_f32_16x16x32_bf16 v[116:119], v[160:163], v[176:179], v[116:119]
	v_mfma_f32_16x16x32_bf16 v[112:115], v[168:171], v[176:179], v[112:115]
	v_mfma_f32_16x16x32_bf16 v[100:103], v[160:163], v[188:191], v[100:103]
	v_mfma_f32_16x16x32_bf16 v[92:95], v[168:171], v[188:191], v[92:95]
	v_mfma_f32_16x16x32_bf16 v[84:87], v[160:163], v[200:203], v[84:87]
	v_mfma_f32_16x16x32_bf16 v[76:79], v[168:171], v[200:203], v[76:79]
	v_mfma_f32_16x16x32_bf16 v[68:71], v[160:163], v[208:211], v[68:71]
	v_mfma_f32_16x16x32_bf16 v[64:67], v[168:171], v[208:211], v[64:67]
	v_mfma_f32_16x16x32_bf16 v[116:119], v[164:167], v[180:183], v[116:119]
	v_mfma_f32_16x16x32_bf16 v[112:115], v[172:175], v[180:183], v[112:115]
	v_mfma_f32_16x16x32_bf16 v[100:103], v[164:167], v[196:199], v[100:103]
	v_mfma_f32_16x16x32_bf16 v[92:95], v[172:175], v[196:199], v[92:95]
	v_mfma_f32_16x16x32_bf16 v[84:87], v[164:167], v[204:207], v[84:87]
	v_mfma_f32_16x16x32_bf16 v[76:79], v[172:175], v[204:207], v[76:79]
	v_mfma_f32_16x16x32_bf16 v[68:71], v[164:167], v[212:215], v[68:71]
	v_mfma_f32_16x16x32_bf16 v[64:67], v[172:175], v[212:215], v[64:67]
	s_barrier
	s_add_i32 s56, s56, s43
	v_lshl_add_u64 v[216:217], s[36:37], 0, v[184:185]
	s_mov_b32 m0, s56
	ds_read_b128 v[176:179], v159 offset:16384
	ds_read_b128 v[180:183], v159 offset:17408
	ds_read_b128 v[188:191], v159 offset:18432
	ds_read_b128 v[196:199], v159 offset:19456
	ds_read_b128 v[200:203], v159 offset:20480
	ds_read_b128 v[204:207], v159 offset:21504
	ds_read_b128 v[208:211], v159 offset:22528
	ds_read_b128 v[212:215], v159 offset:23552
	global_load_lds_dwordx4 v[216:217], off
	s_add_i32 m0, s56, 0x2000
	s_add_u32 s56, s36, 0x200000
	v_lshl_add_u64 v[218:219], s[36:37], 0, v[136:137]
	s_addc_u32 s57, s37, 0
	s_add_i32 s58, s58, s43
	global_load_lds_dwordx4 v[218:219], off
	v_lshl_add_u64 v[220:221], s[56:57], 0, v[184:185]
	s_mov_b32 m0, s58
	v_lshl_add_u64 v[222:223], s[38:39], 0, v[134:135]
	global_load_lds_dwordx4 v[220:221], off
	s_add_i32 m0, s58, 0x2000
	v_lshl_add_u64 v[220:221], s[56:57], 0, v[136:137]
	global_load_lds_dwordx4 v[220:221], off
	s_mov_b32 m0, s31
	v_lshl_add_u64 v[220:221], s[38:39], 0, v[132:133]
	global_load_lds_dwordx4 v[220:221], off
	s_mov_b32 m0, s44
	s_nop 0
	global_load_lds_dwordx4 v[222:223], off
	s_waitcnt vmcnt(8) lgkmcnt(0)
	s_barrier
	v_mfma_f32_16x16x32_bf16 v[60:63], v[128:131], v[176:179], v[60:63]
	v_mfma_f32_16x16x32_bf16 v[56:59], v[146:149], v[176:179], v[56:59]
	v_mfma_f32_16x16x32_bf16 v[48:51], v[128:131], v[188:191], v[48:51]
	v_mfma_f32_16x16x32_bf16 v[40:43], v[146:149], v[188:191], v[40:43]
	v_mfma_f32_16x16x32_bf16 v[32:35], v[128:131], v[200:203], v[32:35]
	v_mfma_f32_16x16x32_bf16 v[24:27], v[146:149], v[200:203], v[24:27]
	v_mfma_f32_16x16x32_bf16 v[16:19], v[128:131], v[208:211], v[16:19]
	v_mfma_f32_16x16x32_bf16 v[8:11], v[146:149], v[208:211], v[8:11]
	v_mfma_f32_16x16x32_bf16 v[60:63], v[142:145], v[180:183], v[60:63]
	v_mfma_f32_16x16x32_bf16 v[56:59], v[150:153], v[180:183], v[56:59]
	v_mfma_f32_16x16x32_bf16 v[48:51], v[142:145], v[196:199], v[48:51]
	v_mfma_f32_16x16x32_bf16 v[40:43], v[150:153], v[196:199], v[40:43]
	v_mfma_f32_16x16x32_bf16 v[32:35], v[142:145], v[204:207], v[32:35]
	v_mfma_f32_16x16x32_bf16 v[24:27], v[150:153], v[204:207], v[24:27]
	v_mfma_f32_16x16x32_bf16 v[16:19], v[142:145], v[212:215], v[16:19]
	v_mfma_f32_16x16x32_bf16 v[8:11], v[150:153], v[212:215], v[8:11]
	v_mfma_f32_16x16x32_bf16 v[52:55], v[160:163], v[176:179], v[52:55]
	v_mfma_f32_16x16x32_bf16 v[44:47], v[168:171], v[176:179], v[44:47]
	v_mfma_f32_16x16x32_bf16 v[36:39], v[160:163], v[188:191], v[36:39]
	v_mfma_f32_16x16x32_bf16 v[28:31], v[168:171], v[188:191], v[28:31]
	v_mfma_f32_16x16x32_bf16 v[20:23], v[160:163], v[200:203], v[20:23]
	v_mfma_f32_16x16x32_bf16 v[12:15], v[168:171], v[200:203], v[12:15]
	v_mfma_f32_16x16x32_bf16 v[4:7], v[160:163], v[208:211], v[4:7]
	v_mfma_f32_16x16x32_bf16 v[0:3], v[168:171], v[208:211], v[0:3]
	v_mfma_f32_16x16x32_bf16 v[52:55], v[164:167], v[180:183], v[52:55]
	v_mfma_f32_16x16x32_bf16 v[44:47], v[172:175], v[180:183], v[44:47]
	v_mfma_f32_16x16x32_bf16 v[36:39], v[164:167], v[196:199], v[36:39]
	v_mfma_f32_16x16x32_bf16 v[28:31], v[172:175], v[196:199], v[28:31]
	v_mfma_f32_16x16x32_bf16 v[20:23], v[164:167], v[204:207], v[20:23]
	v_mfma_f32_16x16x32_bf16 v[12:15], v[172:175], v[204:207], v[12:15]
	v_mfma_f32_16x16x32_bf16 v[4:7], v[164:167], v[212:215], v[4:7]
	v_mfma_f32_16x16x32_bf16 v[0:3], v[172:175], v[212:215], v[0:3]
	s_barrier
; #define PG8_STAGE(bufoff, gbase, voff) do { _Pragma("unroll") for (int _i = 0; _i < 2; ++_i) \
;         __builtin_amdgcn_global_load_lds((const unsigned*)((const char*)(gbase) + (voff)[_i]), (LAS unsigned*)(lds + (bufoff) + ldsw + _i * 8192), 16, 0, 0); } while (0)
; #define PG8_LDA(dst, b, h) do { _Pragma("unroll") for (int m = 0; m < 4; ++m) _Pragma("unroll") for (int k = 0; k < 2; ++k) dst[m][k] = *(const LAS bf16x8*)(lds + PG8_SA(b, h) + aoff + m * 2048 + k * 1024); } while (0)
; #define PG8_LDB(dst, b, h) do { _Pragma("unroll") for (int n = 0; n < 2; ++n) _Pragma("unroll") for (int k = 0; k < 2; ++k) dst[n][k] = *(const LAS bf16x8*)(lds + PG8_SB(b, h) + boff + n * 2048 + k * 1024); } while (0)
; #define PG8_MMA(ai, bj, At, Bt) do { __builtin_amdgcn_s_setprio(1); _Pragma("unroll") for (int m = 0; m < 4; ++m) _Pragma("unroll") for (int n = 0; n < 2; ++n) _Pragma("unroll") for (int k = 0; k < 2; ++k) \
;         acc[ai][bj][m][n] = __builtin_amdgcn_mfma_f32_16x16x32_bf16(Bt[n][k], At[m][k], acc[ai][bj][m][n], 0, 0, 0); __builtin_amdgcn_s_setprio(0); } while (0)
; #define PG8_WAIT_V(n) asm volatile("s_waitcnt vmcnt(" #n ")" ::: "memory")
; #define PG8_WAIT_L(n) asm volatile("s_waitcnt lgkmcnt(" #n ")" ::: "memory")
; #define PG8_BAR __builtin_amdgcn_s_barrier()
; #define PG8_SCHED __builtin_amdgcn_sched_barrier(0)
; template <class Epi, class Sched>
; DI void gemm_phase(LAS unsigned char* lds, const int wv, const int lda, const int ldb, const Sched& S, const Epi& E) {
;     ...
;             PG8_LDB(B0, 1, 0); PG8_LDB(B1, 1, 1); PG8_SCHED; PG8_LDA(At, 1, 0); PG8_STAGE(PG8_SA(0, 1), a2 + hstepA, voffA);
;             PG8_WAIT_V(8); PG8_WAIT_L(0); PG8_BAR; PG8_MMA(0, 0, At, B0); PG8_MMA(0, 1, At, B1); PG8_BAR; PG8_SCHED;
;             PG8_LDA(At, 1, 1); PG8_STAGE(PG8_SB(1, 0), b3, voffB); PG8_STAGE(PG8_SB(1, 1), b3 + hstepB, voffB); PG8_STAGE(PG8_SA(1, 0), a3, voffA);
;             PG8_WAIT_V(8); PG8_WAIT_L(0); PG8_BAR; PG8_MMA(1, 0, At, B0); PG8_MMA(1, 1, At, B1); PG8_BAR; PG8_SCHED;
;         }
	s_add_i32 s56, 0, 0x18000
	s_add_i32 s57, 0, 0x1c000
	v_add_u32_e32 v150, s56, v155
	v_add_u32_e32 v172, s57, v155
	ds_read_b128 v[128:131], v150
	ds_read_b128 v[142:145], v150 offset:1024
	ds_read_b128 v[146:149], v150 offset:2048
	ds_read_b128 v[150:153], v150 offset:3072
	ds_read_b128 v[160:163], v172
	ds_read_b128 v[164:167], v172 offset:1024
	ds_read_b128 v[168:171], v172 offset:2048
	ds_read_b128 v[172:175], v172 offset:3072
	s_add_u32 s38, s38, 0x200000
	s_addc_u32 s39, s39, 0
	s_mov_b32 m0, s45
	v_lshl_add_u64 v[234:235], s[38:39], 0, v[132:133]
	ds_read_b128 v[176:179], v159 offset:32768
	ds_read_b128 v[180:183], v159 offset:33792
	ds_read_b128 v[188:191], v159 offset:34816
	ds_read_b128 v[196:199], v159 offset:35840
	ds_read_b128 v[200:203], v159 offset:36864
	ds_read_b128 v[204:207], v159 offset:37888
	ds_read_b128 v[208:211], v159 offset:38912
	ds_read_b128 v[212:215], v159 offset:39936
	global_load_lds_dwordx4 v[234:235], off
	s_mov_b32 m0, s46
	v_lshl_add_u64 v[234:235], s[38:39], 0, v[134:135]
	global_load_lds_dwordx4 v[234:235], off
	s_waitcnt vmcnt(8) lgkmcnt(0)
	s_barrier
	v_mfma_f32_16x16x32_bf16 v[124:127], v[128:131], v[176:179], v[124:127]
	v_mfma_f32_16x16x32_bf16 v[120:123], v[146:149], v[176:179], v[120:123]
	v_mfma_f32_16x16x32_bf16 v[108:111], v[128:131], v[188:191], v[108:111]
	v_mfma_f32_16x16x32_bf16 v[104:107], v[146:149], v[188:191], v[104:107]
	v_mfma_f32_16x16x32_bf16 v[96:99], v[128:131], v[200:203], v[96:99]
	v_mfma_f32_16x16x32_bf16 v[88:91], v[146:149], v[200:203], v[88:91]
	v_mfma_f32_16x16x32_bf16 v[80:83], v[128:131], v[208:211], v[80:83]
	v_mfma_f32_16x16x32_bf16 v[72:75], v[146:149], v[208:211], v[72:75]
	v_mfma_f32_16x16x32_bf16 v[124:127], v[142:145], v[180:183], v[124:127]
	v_mfma_f32_16x16x32_bf16 v[120:123], v[150:153], v[180:183], v[120:123]
	v_mfma_f32_16x16x32_bf16 v[108:111], v[142:145], v[196:199], v[108:111]
	v_mfma_f32_16x16x32_bf16 v[104:107], v[150:153], v[196:199], v[104:107]
	v_mfma_f32_16x16x32_bf16 v[96:99], v[142:145], v[204:207], v[96:99]
	v_mfma_f32_16x16x32_bf16 v[88:91], v[150:153], v[204:207], v[88:91]
	v_mfma_f32_16x16x32_bf16 v[80:83], v[142:145], v[212:215], v[80:83]
	v_mfma_f32_16x16x32_bf16 v[72:75], v[150:153], v[212:215], v[72:75]
	v_mfma_f32_16x16x32_bf16 v[116:119], v[160:163], v[176:179], v[116:119]
	v_mfma_f32_16x16x32_bf16 v[112:115], v[168:171], v[176:179], v[112:115]
	v_mfma_f32_16x16x32_bf16 v[100:103], v[160:163], v[188:191], v[100:103]
	v_mfma_f32_16x16x32_bf16 v[92:95], v[168:171], v[188:191], v[92:95]
	v_mfma_f32_16x16x32_bf16 v[84:87], v[160:163], v[200:203], v[84:87]
	v_mfma_f32_16x16x32_bf16 v[76:79], v[168:171], v[200:203], v[76:79]
	v_mfma_f32_16x16x32_bf16 v[68:71], v[160:163], v[208:211], v[68:71]
	v_mfma_f32_16x16x32_bf16 v[64:67], v[168:171], v[208:211], v[64:67]
	v_mfma_f32_16x16x32_bf16 v[116:119], v[164:167], v[180:183], v[116:119]
	v_mfma_f32_16x16x32_bf16 v[112:115], v[172:175], v[180:183], v[112:115]
	v_mfma_f32_16x16x32_bf16 v[100:103], v[164:167], v[196:199], v[100:103]
	v_mfma_f32_16x16x32_bf16 v[92:95], v[172:175], v[196:199], v[92:95]
	v_mfma_f32_16x16x32_bf16 v[84:87], v[164:167], v[204:207], v[84:87]
	v_mfma_f32_16x16x32_bf16 v[76:79], v[172:175], v[204:207], v[76:79]
	v_mfma_f32_16x16x32_bf16 v[68:71], v[164:167], v[212:215], v[68:71]
	v_mfma_f32_16x16x32_bf16 v[64:67], v[172:175], v[212:215], v[64:67]
	s_barrier
	s_add_i32 s38, s56, s43
	v_lshl_add_u64 v[216:217], v[216:217], 0, s[28:29]
	s_mov_b32 m0, s38
	ds_read_b128 v[176:179], v159 offset:49152
	ds_read_b128 v[180:183], v159 offset:50176
	ds_read_b128 v[188:191], v159 offset:51200
	ds_read_b128 v[196:199], v159 offset:52224
	ds_read_b128 v[200:203], v159 offset:53248
	ds_read_b128 v[204:207], v159 offset:54272
	ds_read_b128 v[208:211], v159 offset:55296
	ds_read_b128 v[212:215], v159 offset:56320
	global_load_lds_dwordx4 v[216:217], off
	s_add_i32 m0, s38, 0x2000
	s_add_u32 s36, s36, 0x200080
	v_lshl_add_u64 v[216:217], v[218:219], 0, s[28:29]
	s_addc_u32 s37, s37, 0
	s_add_i32 s38, s57, s43
	global_load_lds_dwordx4 v[216:217], off
	s_mov_b32 m0, s38
	v_lshl_add_u64 v[216:217], s[36:37], 0, v[184:185]
	global_load_lds_dwordx4 v[216:217], off
	s_add_i32 m0, s38, 0x2000
	v_lshl_add_u64 v[216:217], s[36:37], 0, v[136:137]
	global_load_lds_dwordx4 v[216:217], off
	s_mov_b32 m0, s47
	v_lshl_add_u64 v[216:217], v[220:221], 0, s[28:29]
	global_load_lds_dwordx4 v[216:217], off
	s_mov_b32 m0, s48
	v_lshl_add_u64 v[216:217], v[222:223], 0, s[28:29]
	global_load_lds_dwordx4 v[216:217], off
	s_waitcnt vmcnt(8) lgkmcnt(0)
	s_barrier
	v_mfma_f32_16x16x32_bf16 v[60:63], v[128:131], v[176:179], v[60:63]
	v_mfma_f32_16x16x32_bf16 v[56:59], v[146:149], v[176:179], v[56:59]
	v_mfma_f32_16x16x32_bf16 v[48:51], v[128:131], v[188:191], v[48:51]
	v_mfma_f32_16x16x32_bf16 v[40:43], v[146:149], v[188:191], v[40:43]
	v_mfma_f32_16x16x32_bf16 v[32:35], v[128:131], v[200:203], v[32:35]
	v_mfma_f32_16x16x32_bf16 v[24:27], v[146:149], v[200:203], v[24:27]
	v_mfma_f32_16x16x32_bf16 v[16:19], v[128:131], v[208:211], v[16:19]
	v_mfma_f32_16x16x32_bf16 v[8:11], v[146:149], v[208:211], v[8:11]
	v_mfma_f32_16x16x32_bf16 v[60:63], v[142:145], v[180:183], v[60:63]
	v_mfma_f32_16x16x32_bf16 v[56:59], v[150:153], v[180:183], v[56:59]
	v_mfma_f32_16x16x32_bf16 v[48:51], v[142:145], v[196:199], v[48:51]
	v_mfma_f32_16x16x32_bf16 v[40:43], v[150:153], v[196:199], v[40:43]
	v_mfma_f32_16x16x32_bf16 v[32:35], v[142:145], v[204:207], v[32:35]
	v_mfma_f32_16x16x32_bf16 v[24:27], v[150:153], v[204:207], v[24:27]
	v_mfma_f32_16x16x32_bf16 v[16:19], v[142:145], v[212:215], v[16:19]
	v_mfma_f32_16x16x32_bf16 v[8:11], v[150:153], v[212:215], v[8:11]
	v_mfma_f32_16x16x32_bf16 v[52:55], v[160:163], v[176:179], v[52:55]
	v_mfma_f32_16x16x32_bf16 v[44:47], v[168:171], v[176:179], v[44:47]
	v_mfma_f32_16x16x32_bf16 v[36:39], v[160:163], v[188:191], v[36:39]
	v_mfma_f32_16x16x32_bf16 v[28:31], v[168:171], v[188:191], v[28:31]
	v_mfma_f32_16x16x32_bf16 v[20:23], v[160:163], v[200:203], v[20:23]
	v_mfma_f32_16x16x32_bf16 v[12:15], v[168:171], v[200:203], v[12:15]
	v_mfma_f32_16x16x32_bf16 v[4:7], v[160:163], v[208:211], v[4:7]
	v_mfma_f32_16x16x32_bf16 v[0:3], v[168:171], v[208:211], v[0:3]
	v_mfma_f32_16x16x32_bf16 v[52:55], v[164:167], v[180:183], v[52:55]
	v_mfma_f32_16x16x32_bf16 v[44:47], v[172:175], v[180:183], v[44:47]
	v_mfma_f32_16x16x32_bf16 v[36:39], v[164:167], v[196:199], v[36:39]
	v_mfma_f32_16x16x32_bf16 v[28:31], v[172:175], v[196:199], v[28:31]
	v_mfma_f32_16x16x32_bf16 v[20:23], v[164:167], v[204:207], v[20:23]
	v_mfma_f32_16x16x32_bf16 v[12:15], v[172:175], v[204:207], v[12:15]
	v_mfma_f32_16x16x32_bf16 v[4:7], v[164:167], v[212:215], v[4:7]
	v_mfma_f32_16x16x32_bf16 v[0:3], v[172:175], v[212:215], v[0:3]
	s_barrier
	s_add_i32 s55, s55, 2
	s_add_u32 s34, s34, 0x100
	s_addc_u32 s35, s35, 0
	s_add_u32 s23, s23, 0x100
	s_addc_u32 s54, s54, 0
	s_cmpk_gt_u32 s55, 0x7d
	s_cbranch_scc0 .LBB0_1477
	s_and_b64 vcc, exec, s[14:15]
	s_cbranch_vccz .LBB0_1480
	s_barrier
